# in-proj and W1 GEMM K-loops: staging loads use scalar base + 32-bit VGPR offset (no 64-bit VALU address arithmetic per load); plus diff exp interleave
# speedup vs baseline: 1.0165x; 1.0165x over previous
; #define G_GLOAD(XR, WR, KT) { _Pragma("unroll") for (int i_ = 0; i_ < 4; ++i_) XR[i_] = *(const u32x4*)(Xt + ((size_t)(64 * i_) * ldx + (KT) * 64) * 2 + xoff); \
;     _Pragma("unroll") for (int i_ = 0; i_ < 4; ++i_) WR[i_] = *(const u32x4*)(Wtb + ((size_t)(64 * i_) * K + (KT) * 64) * 2 + woff); }
; #define G_LSTORE(XR, WR, STG) { char* xs_ = lds + (STG) * G_STAGE; char* ws_ = xs_ + G_XB; \
;     _Pragma("unroll") for (int i_ = 0; i_ < 4; ++i_) *(u32x4*)(xs_ + (lrow + 64 * i_) * LROW + lch * 16) = XR[i_]; \
;     _Pragma("unroll") for (int i_ = 0; i_ < 4; ++i_) *(u32x4*)(ws_ + (lrow + 64 * i_) * LROW + lch * 16) = WR[i_]; }
; template <class Epi>
; DI void gemm_phase(const bf16_t* __restrict__ X, const int ldx, const bf16_t* __restrict__ Wt, const int N, const int K, const Epi& epi, char* lds) {
;     ...
;   for (int chunk = xcd; chunk < nchunks; chunk += 8) {
;     const int L = chunk * 32 + slot, band = L / (4 * nNt), rem = L % (4 * nNt);
;     const int mt_ = band * 4 + (rem & 3), nt_ = rem >> 2;
;     const char* Xt = (const char*)(X + (size_t)(mt_ * 256) * ldx);
;     const char* Wtb = (const char*)(Wt + (size_t)(nt_ * 256) * K);
;     const unsigned xoff = (unsigned)(lrow * ldx + lch * 8) * 2u, woff = (unsigned)(lrow * K + lch * 8) * 2u;
;     const bool has_next = !Epi::kFull && (chunk + 8 < nchunks);
;     const int Ln = (has_next ? chunk + 8 : chunk) * 32 + slot, band_n = Ln / (4 * nNt), rem_n = Ln % (4 * nNt);
;     const char* Xt_n = (const char*)(X + (size_t)((band_n * 4 + (rem_n & 3)) * 256) * ldx);
;     const char* Wtb_n = (const char*)(Wt + (size_t)((rem_n >> 2) * 256) * K);
;     f32x16 acc[2][2][2];
;     ...
;     asm volatile("" ::: "memory");
;     if (Epi::kFull || chunk == xcd) {
;       G_GLOAD(xr0, wr0, 0);
;       G_LSTORE(xr0, wr0, 0);
;       __syncthreads();
;       G_GLOAD(xr0, wr0, 1);
;     }
; #pragma unroll
;     for (int c = 0; c < 2; ++c)
; #pragma unroll
;       for (int a = 0; a < 2; ++a)
; #pragma unroll
;         for (int b = 0; b < 2; ++b)
; #pragma unroll
;           for (int i = 0; i < 16; ++i) acc[c][a][b][i] = 0.f;
.LBB0_85:
	s_add_i32 s46, s26, 8
	s_cmp_gt_u32 s26, 59
	s_cselect_b64 s[24:25], -1, 0
	s_cmp_lt_u32 s26, 60
	s_cselect_b32 s26, s46, s26
	s_cselect_b32 s5, 0, 15
	s_cselect_b32 s28, 1, 15
	s_lshl_b32 s26, s26, 5
	v_readlane_b32 s27, v254, 3
	s_add_i32 s26, s26, s27
	s_mul_hi_u32 s27, s26, 0xf0f0f0f1
	s_lshr_b32 s27, s27, 6
	s_mul_i32 s29, s27, 0x44
	s_sub_i32 s31, s26, s29
	s_lshl_b32 s26, s27, 10
	s_lshl_b32 s27, s31, 8
	s_and_b32 s27, s27, 0x300
	s_or_b32 s26, s27, s26
	s_ashr_i32 s27, s26, 31
	s_lshl_b64 s[26:27], s[26:27], 11
	s_add_u32 s29, s6, s26
	s_addc_u32 s30, s7, s27
	s_lshl_b32 s26, s31, 17
	s_and_b32 s26, s26, 0xf80000
	s_add_u32 s31, s44, s26
	v_mov_b32_e32 v2, 0
	s_addc_u32 s33, s45, 0
	s_mov_b32 s34, 3
	v_mov_b32_e32 v3, v2
	v_mov_b32_e32 v4, v2
	v_mov_b32_e32 v5, v2
	v_mov_b32_e32 v6, v2
	v_mov_b32_e32 v7, v2
	v_mov_b32_e32 v8, v2
	v_mov_b32_e32 v9, v2
	v_mov_b32_e32 v10, v2
	v_mov_b32_e32 v11, v2
	v_mov_b32_e32 v12, v2
	v_mov_b32_e32 v13, v2
	v_mov_b32_e32 v14, v2
	v_mov_b32_e32 v15, v2
	v_mov_b32_e32 v16, v2
	v_mov_b32_e32 v17, v2
	s_waitcnt vmcnt(5)
	v_mov_b32_e32 v34, v2
	v_mov_b32_e32 v35, v2
	v_mov_b32_e32 v36, v2
	v_mov_b32_e32 v37, v2
	s_waitcnt vmcnt(4)
	v_mov_b32_e32 v38, v2
	v_mov_b32_e32 v39, v2
	v_mov_b32_e32 v40, v2
	v_mov_b32_e32 v41, v2
	s_waitcnt vmcnt(3)
	v_mov_b32_e32 v42, v2
	v_mov_b32_e32 v43, v2
	v_mov_b32_e32 v44, v2
	v_mov_b32_e32 v45, v2
	s_waitcnt vmcnt(2)
	v_mov_b32_e32 v46, v2
	v_mov_b32_e32 v47, v2
	v_mov_b32_e32 v48, v2
	v_mov_b32_e32 v49, v2
	v_mov_b32_e32 v18, v2
	v_mov_b32_e32 v19, v2
	v_mov_b32_e32 v20, v2
	v_mov_b32_e32 v21, v2
	v_mov_b32_e32 v22, v2
	v_mov_b32_e32 v23, v2
	v_mov_b32_e32 v24, v2
	v_mov_b32_e32 v25, v2
	v_mov_b32_e32 v26, v2
	v_mov_b32_e32 v27, v2
	v_mov_b32_e32 v28, v2
	v_mov_b32_e32 v29, v2
	v_mov_b32_e32 v30, v2
	v_mov_b32_e32 v31, v2
	v_mov_b32_e32 v32, v2
	v_mov_b32_e32 v33, v2
	s_waitcnt vmcnt(1)
	v_mov_b32_e32 v50, v2
	v_mov_b32_e32 v51, v2
	v_mov_b32_e32 v52, v2
	v_mov_b32_e32 v53, v2
	s_waitcnt vmcnt(0)
	v_mov_b32_e32 v54, v2
	v_mov_b32_e32 v55, v2
	v_mov_b32_e32 v56, v2
	v_mov_b32_e32 v57, v2
	v_mov_b32_e32 v58, v2
	v_mov_b32_e32 v59, v2
	v_mov_b32_e32 v60, v2
	v_mov_b32_e32 v61, v2
	v_mov_b32_e32 v62, v2
	v_mov_b32_e32 v63, v2
	v_mov_b32_e32 v64, v2
	v_mov_b32_e32 v65, v2
	v_mov_b32_e32 v66, v2
	v_mov_b32_e32 v67, v2
	v_mov_b32_e32 v68, v2
	v_mov_b32_e32 v69, v2
	v_mov_b32_e32 v70, v2
	v_mov_b32_e32 v71, v2
	v_mov_b32_e32 v72, v2
	v_mov_b32_e32 v73, v2
	v_mov_b32_e32 v74, v2
	v_mov_b32_e32 v75, v2
	v_mov_b32_e32 v76, v2
	v_mov_b32_e32 v77, v2
	v_mov_b32_e32 v78, v2
	v_mov_b32_e32 v79, v2
	v_mov_b32_e32 v80, v2
	v_mov_b32_e32 v81, v2
	v_mov_b32_e32 v98, v2
	v_mov_b32_e32 v99, v2
	v_mov_b32_e32 v100, v2
	v_mov_b32_e32 v101, v2
	v_mov_b32_e32 v102, v2
	v_mov_b32_e32 v103, v2
	v_mov_b32_e32 v104, v2
	v_mov_b32_e32 v105, v2
	v_mov_b32_e32 v106, v2
	v_mov_b32_e32 v107, v2
	v_mov_b32_e32 v108, v2
	v_mov_b32_e32 v109, v2
	v_mov_b32_e32 v110, v2
	v_mov_b32_e32 v111, v2
	v_mov_b32_e32 v112, v2
	v_mov_b32_e32 v113, v2
	v_mov_b32_e32 v82, v2
	v_mov_b32_e32 v83, v2
	v_mov_b32_e32 v84, v2
	v_mov_b32_e32 v85, v2
	v_mov_b32_e32 v86, v2
	v_mov_b32_e32 v87, v2
	v_mov_b32_e32 v88, v2
	v_mov_b32_e32 v89, v2
	v_mov_b32_e32 v90, v2
	v_mov_b32_e32 v91, v2
	v_mov_b32_e32 v92, v2
	v_mov_b32_e32 v93, v2
	v_mov_b32_e32 v94, v2
	v_mov_b32_e32 v95, v2
	v_mov_b32_e32 v96, v2
	v_mov_b32_e32 v97, v2
	v_mov_b32_e32 v114, v2
	v_mov_b32_e32 v115, v2
	v_mov_b32_e32 v116, v2
	v_mov_b32_e32 v117, v2
	v_mov_b32_e32 v118, v2
	v_mov_b32_e32 v119, v2
	v_mov_b32_e32 v120, v2
	v_mov_b32_e32 v121, v2
	v_mov_b32_e32 v122, v2
	v_mov_b32_e32 v123, v2
	v_mov_b32_e32 v124, v2
	v_mov_b32_e32 v125, v2
	v_mov_b32_e32 v126, v2
	v_mov_b32_e32 v127, v2
	v_mov_b32_e32 v128, v2
	v_mov_b32_e32 v129, v2
	v_add_u32_e32 v232, s91, v162
	v_add_u32_e32 v233, s1, v162
	v_add_u32_e32 v234, s76, v162
.LBB0_86:
	v_add_u32_e32 v0, v178, v179
	ds_read_b128 v[164:167], v0
	ds_read_b128 v[168:171], v0 offset:4608
	v_add_u32_e32 v0, v178, v180
	ds_read_b128 v[174:177], v0 offset:36864
	ds_read_b128 v[194:197], v0 offset:41472
	ds_read_b128 v[202:205], v0 offset:46080
	ds_read_b128 v[210:213], v0 offset:50688
	ds_read_b128 v[214:217], v184 offset:32
	ds_read_b128 v[218:221], v184 offset:4640
	s_add_i32 s35, s34, -3
	s_cmp_lt_u32 s35, 14
	s_cselect_b64 s[36:37], -1, 0
	s_and_b64 s[26:27], s[36:37], exec
	s_cselect_b32 s27, s11, s33
	s_cselect_b32 s26, s10, s31
	s_cselect_b32 s39, s9, s30
	s_cselect_b32 s38, s8, s29
	s_add_i32 s47, s34, -1
	s_waitcnt lgkmcnt(5)
	v_mfma_f32_32x32x16_bf16 v[114:129], v[174:177], v[164:167], v[114:129]
	v_mfma_f32_32x32x16_bf16 v[82:97], v[174:177], v[168:171], v[82:97]
	s_waitcnt lgkmcnt(4)
	v_mfma_f32_32x32x16_bf16 v[98:113], v[194:197], v[164:167], v[98:113]
	v_mfma_f32_32x32x16_bf16 v[66:81], v[194:197], v[168:171], v[66:81]
	s_waitcnt lgkmcnt(3)
	v_mfma_f32_32x32x16_bf16 v[50:65], v[202:205], v[164:167], v[50:65]
	s_and_b64 s[36:37], s[36:37], exec
	s_cselect_b32 s36, s47, s5
	v_mfma_f32_32x32x16_bf16 v[18:33], v[202:205], v[168:171], v[18:33]
	s_waitcnt lgkmcnt(2)
	v_mfma_f32_32x32x16_bf16 v[34:49], v[210:213], v[164:167], v[34:49]
	ds_read_b128 v[164:167], v185 offset:36896
	ds_read_b128 v[174:177], v185 offset:41504
	v_mfma_f32_32x32x16_bf16 v[2:17], v[210:213], v[168:171], v[2:17]
	s_lshl_b32 s96, s36, 7
	s_add_u32 s100, s38, s96
	s_addc_u32 s101, s39, 0
	s_waitcnt vmcnt(6)
	ds_write_b128 v186, v[142:145] offset:9216
	ds_write_b128 v186, v[134:137]
	s_nop 0
	global_load_dwordx4 v[134:137], v162, s[100:101]
	global_load_dwordx4 v[142:145], v232, s[100:101]
	s_waitcnt vmcnt(7)
; #define G_GLOAD(XR, WR, KT) { _Pragma("unroll") for (int i_ = 0; i_ < 4; ++i_) XR[i_] = *(const u32x4*)(Xt + ((size_t)(64 * i_) * ldx + (KT) * 64) * 2 + xoff); \
;     _Pragma("unroll") for (int i_ = 0; i_ < 4; ++i_) WR[i_] = *(const u32x4*)(Wtb + ((size_t)(64 * i_) * K + (KT) * 64) * 2 + woff); }
; #define G_LSTORE(XR, WR, STG) { char* xs_ = lds + (STG) * G_STAGE; char* ws_ = xs_ + G_XB; \
;     _Pragma("unroll") for (int i_ = 0; i_ < 4; ++i_) *(u32x4*)(xs_ + (lrow + 64 * i_) * LROW + lch * 16) = XR[i_]; \
;     _Pragma("unroll") for (int i_ = 0; i_ < 4; ++i_) *(u32x4*)(ws_ + (lrow + 64 * i_) * LROW + lch * 16) = WR[i_]; }
; template <class Epi>
; DI void gemm_phase(const bf16_t* __restrict__ X, const int ldx, const bf16_t* __restrict__ Wt, const int N, const int K, const Epi& epi, char* lds) {
;     ...
;     asm volatile("" ::: "memory");
;     if (Epi::kFull || chunk == xcd) {
;       G_GLOAD(xr0, wr0, 0);
;       G_LSTORE(xr0, wr0, 0);
;       __syncthreads();
;       G_GLOAD(xr0, wr0, 1);
;     }
; #pragma unroll
;     for (int c = 0; c < 2; ++c)
; #pragma unroll
;       for (int a = 0; a < 2; ++a)
; #pragma unroll
;         for (int b = 0; b < 2; ++b)
; #pragma unroll
;           for (int i = 0; i < 16; ++i) acc[c][a][b][i] = 0.f;
	ds_write_b128 v186, v[130:133] offset:18432
	s_waitcnt vmcnt(6)
	ds_write_b128 v186, v[150:153] offset:27648
	s_nop 0
	global_load_dwordx4 v[130:133], v233, s[100:101]
	global_load_dwordx4 v[150:153], v234, s[100:101]
	ds_read_b128 v[168:171], v185 offset:46112
	ds_read_b128 v[194:197], v185 offset:50720
	ds_read_b128 v[202:205], v184 offset:64
	ds_read_b128 v[210:213], v184 offset:4672
	s_waitcnt lgkmcnt(9)
	v_mfma_f32_32x32x16_bf16 v[114:129], v[164:167], v[214:217], v[114:129]
	v_mfma_f32_32x32x16_bf16 v[82:97], v[164:167], v[218:221], v[82:97]
	s_waitcnt lgkmcnt(8)
	v_mfma_f32_32x32x16_bf16 v[98:113], v[174:177], v[214:217], v[98:113]
	v_mfma_f32_32x32x16_bf16 v[66:81], v[174:177], v[218:221], v[66:81]
	s_waitcnt lgkmcnt(3)
	v_mfma_f32_32x32x16_bf16 v[50:65], v[168:171], v[214:217], v[50:65]
	v_mfma_f32_32x32x16_bf16 v[18:33], v[168:171], v[218:221], v[18:33]
	ds_read_b128 v[164:167], v185 offset:36928
	ds_read_b128 v[168:171], v185 offset:41536
	s_waitcnt lgkmcnt(4)
	v_mfma_f32_32x32x16_bf16 v[34:49], v[194:197], v[214:217], v[34:49]
	v_mfma_f32_32x32x16_bf16 v[2:17], v[194:197], v[218:221], v[2:17]
	s_add_u32 s100, s26, s96
	s_addc_u32 s101, s27, 0
	s_waitcnt vmcnt(6)
	ds_write_b128 v187, v[154:157] offset:9216
	ds_write_b128 v187, v[138:141]
	s_nop 0
	global_load_dwordx4 v[138:141], v162, s[100:101]
	global_load_dwordx4 v[154:157], v232, s[100:101]
	ds_read_b128 v[174:177], v185 offset:46144
	ds_read_b128 v[194:197], v185 offset:50752
	ds_read_b128 v[214:217], v184 offset:96
	ds_read_b128 v[218:221], v184 offset:4704
	s_waitcnt lgkmcnt(7)
	v_mfma_f32_32x32x16_bf16 v[114:129], v[164:167], v[202:205], v[114:129]
	v_mfma_f32_32x32x16_bf16 v[82:97], v[164:167], v[210:213], v[82:97]
	s_waitcnt lgkmcnt(6)
	v_mfma_f32_32x32x16_bf16 v[98:113], v[168:171], v[202:205], v[98:113]
	v_mfma_f32_32x32x16_bf16 v[66:81], v[168:171], v[210:213], v[66:81]
	s_waitcnt lgkmcnt(3)
	v_mfma_f32_32x32x16_bf16 v[50:65], v[174:177], v[202:205], v[50:65]
	ds_read_b128 v[164:167], v185 offset:36960
	ds_read_b128 v[168:171], v185 offset:41568
	v_mfma_f32_32x32x16_bf16 v[18:33], v[174:177], v[210:213], v[18:33]
	s_waitcnt lgkmcnt(4)
	v_mfma_f32_32x32x16_bf16 v[34:49], v[194:197], v[202:205], v[34:49]
	v_mfma_f32_32x32x16_bf16 v[2:17], v[194:197], v[210:213], v[2:17]
	s_waitcnt vmcnt(7)
	ds_write_b128 v187, v[146:149] offset:18432
	s_waitcnt vmcnt(6)
	ds_write_b128 v187, v[158:161] offset:27648
	s_nop 0
	global_load_dwordx4 v[146:149], v233, s[100:101]
	global_load_dwordx4 v[158:161], v234, s[100:101]
	ds_read_b128 v[174:177], v185 offset:46176
	ds_read_b128 v[194:197], v185 offset:50784
	s_waitcnt lgkmcnt(5)
	v_mfma_f32_32x32x16_bf16 v[114:129], v[164:167], v[214:217], v[114:129]
	v_mfma_f32_32x32x16_bf16 v[82:97], v[164:167], v[218:221], v[82:97]
	s_waitcnt lgkmcnt(4)
	v_mfma_f32_32x32x16_bf16 v[98:113], v[168:171], v[214:217], v[98:113]
	v_mfma_f32_32x32x16_bf16 v[66:81], v[168:171], v[218:221], v[66:81]
	s_waitcnt lgkmcnt(1)
	v_mfma_f32_32x32x16_bf16 v[50:65], v[174:177], v[214:217], v[50:65]
	v_mfma_f32_32x32x16_bf16 v[18:33], v[174:177], v[218:221], v[18:33]
	s_waitcnt lgkmcnt(0)
	v_mfma_f32_32x32x16_bf16 v[34:49], v[194:197], v[214:217], v[34:49]
	v_mfma_f32_32x32x16_bf16 v[2:17], v[194:197], v[218:221], v[2:17]
	s_barrier
	ds_read_b128 v[164:167], v188
	ds_read_b128 v[168:171], v188 offset:4608
	ds_read_b128 v[174:177], v189
	ds_read_b128 v[194:197], v189 offset:4608
	ds_read_b128 v[202:205], v189 offset:9216
	ds_read_b128 v[210:213], v189 offset:13824
	v_add_u32_e32 v0, v181, v173
	ds_read_b128 v[214:217], v0 offset:32
	ds_read_b128 v[218:221], v190 offset:32
	s_cmp_lt_u32 s35, 13
	s_cselect_b64 s[26:27], -1, 0
	s_and_b64 s[26:27], s[26:27], exec
	s_cselect_b32 s37, s9, s30
	s_cselect_b32 s36, s8, s29
	s_cselect_b32 s27, s11, s33
	s_cselect_b32 s26, s10, s31
	s_waitcnt lgkmcnt(5)
	v_mfma_f32_32x32x16_bf16 v[114:129], v[174:177], v[164:167], v[114:129]
	v_mfma_f32_32x32x16_bf16 v[82:97], v[174:177], v[168:171], v[82:97]
	s_waitcnt lgkmcnt(4)
	v_mfma_f32_32x32x16_bf16 v[98:113], v[194:197], v[164:167], v[98:113]
	v_mfma_f32_32x32x16_bf16 v[66:81], v[194:197], v[168:171], v[66:81]
	s_waitcnt lgkmcnt(3)
	v_mfma_f32_32x32x16_bf16 v[50:65], v[202:205], v[164:167], v[50:65]
	v_add_u32_e32 v172, v182, v173
	s_cselect_b32 s38, s34, s28
	v_mfma_f32_32x32x16_bf16 v[18:33], v[202:205], v[168:171], v[18:33]
	s_waitcnt lgkmcnt(2)
	v_mfma_f32_32x32x16_bf16 v[34:49], v[210:213], v[164:167], v[34:49]
	ds_read_b128 v[164:167], v172 offset:32
	ds_read_b128 v[174:177], v191 offset:32
	v_mfma_f32_32x32x16_bf16 v[2:17], v[210:213], v[168:171], v[2:17]
	s_lshl_b32 s96, s38, 7
	s_add_u32 s100, s36, s96
	s_addc_u32 s101, s37, 0
	s_waitcnt vmcnt(6)
	ds_write_b128 v183, v[142:145] offset:9216
	ds_write_b128 v183, v[134:137]
	s_nop 0
	global_load_dwordx4 v[134:137], v162, s[100:101]
	global_load_dwordx4 v[142:145], v232, s[100:101]
	s_waitcnt vmcnt(7)
	ds_write_b128 v183, v[130:133] offset:18432
	s_waitcnt vmcnt(6)
	ds_write_b128 v183, v[150:153] offset:27648
	s_nop 0
	global_load_dwordx4 v[130:133], v233, s[100:101]
	global_load_dwordx4 v[150:153], v234, s[100:101]
	ds_read_b128 v[168:171], v208 offset:32
	ds_read_b128 v[194:197], v209 offset:32
	ds_read_b128 v[202:205], v0 offset:64
	ds_read_b128 v[210:213], v190 offset:64
	s_waitcnt lgkmcnt(9)
	v_mfma_f32_32x32x16_bf16 v[114:129], v[164:167], v[214:217], v[114:129]
	v_mfma_f32_32x32x16_bf16 v[82:97], v[164:167], v[218:221], v[82:97]
	s_waitcnt lgkmcnt(8)
	v_mfma_f32_32x32x16_bf16 v[98:113], v[174:177], v[214:217], v[98:113]
	v_mfma_f32_32x32x16_bf16 v[66:81], v[174:177], v[218:221], v[66:81]
	s_waitcnt lgkmcnt(3)
; #define G_GLOAD(XR, WR, KT) { _Pragma("unroll") for (int i_ = 0; i_ < 4; ++i_) XR[i_] = *(const u32x4*)(Xt + ((size_t)(64 * i_) * ldx + (KT) * 64) * 2 + xoff); \
;     _Pragma("unroll") for (int i_ = 0; i_ < 4; ++i_) WR[i_] = *(const u32x4*)(Wtb + ((size_t)(64 * i_) * K + (KT) * 64) * 2 + woff); }
; #define G_LSTORE(XR, WR, STG) { char* xs_ = lds + (STG) * G_STAGE; char* ws_ = xs_ + G_XB; \
;     _Pragma("unroll") for (int i_ = 0; i_ < 4; ++i_) *(u32x4*)(xs_ + (lrow + 64 * i_) * LROW + lch * 16) = XR[i_]; \
;     _Pragma("unroll") for (int i_ = 0; i_ < 4; ++i_) *(u32x4*)(ws_ + (lrow + 64 * i_) * LROW + lch * 16) = WR[i_]; }
; template <class Epi>
; DI void gemm_phase(const bf16_t* __restrict__ X, const int ldx, const bf16_t* __restrict__ Wt, const int N, const int K, const Epi& epi, char* lds) {
;     ...
;     asm volatile("" ::: "memory");
;     if (Epi::kFull || chunk == xcd) {
;       G_GLOAD(xr0, wr0, 0);
;       G_LSTORE(xr0, wr0, 0);
;       __syncthreads();
;       G_GLOAD(xr0, wr0, 1);
;     }
; #pragma unroll
;     for (int c = 0; c < 2; ++c)
; #pragma unroll
;       for (int a = 0; a < 2; ++a)
; #pragma unroll
;         for (int b = 0; b < 2; ++b)
; #pragma unroll
;           for (int i = 0; i < 16; ++i) acc[c][a][b][i] = 0.f;
;   DI void operator()(int tok0, int feat0, f32x16 (&acc)[2][2], int r, int hh) const {
;     ...
;       } else if (feat0 == 4096) {
;         if (hh == 0) {
; #pragma unroll
;           for (int i = 0; i < 16; ++i) {
;             const float xv = acc[0][mt][i] + bf[i];
;             const float ls = fminf(xv, 0.f) - log1pf(expf(-fabsf(xv)));
	v_mfma_f32_32x32x16_bf16 v[50:65], v[168:171], v[214:217], v[50:65]
	v_mfma_f32_32x32x16_bf16 v[18:33], v[168:171], v[218:221], v[18:33]
	ds_read_b128 v[164:167], v172 offset:64
	ds_read_b128 v[168:171], v191 offset:64
	s_waitcnt lgkmcnt(4)
	v_mfma_f32_32x32x16_bf16 v[34:49], v[194:197], v[214:217], v[34:49]
	v_mfma_f32_32x32x16_bf16 v[2:17], v[194:197], v[218:221], v[2:17]
	s_add_u32 s100, s26, s96
	s_addc_u32 s101, s27, 0
	s_waitcnt vmcnt(6)
	ds_write_b128 v183, v[154:157] offset:46080
	ds_write_b128 v183, v[138:141] offset:36864
	s_nop 0
	global_load_dwordx4 v[138:141], v162, s[100:101]
	global_load_dwordx4 v[154:157], v232, s[100:101]
	ds_read_b128 v[174:177], v208 offset:64
	ds_read_b128 v[194:197], v209 offset:64
	ds_read_b128 v[214:217], v0 offset:96
	ds_read_b128 v[218:221], v190 offset:96
	s_waitcnt lgkmcnt(7)
	v_mfma_f32_32x32x16_bf16 v[114:129], v[164:167], v[202:205], v[114:129]
	v_mfma_f32_32x32x16_bf16 v[82:97], v[164:167], v[210:213], v[82:97]
	s_waitcnt lgkmcnt(6)
	v_mfma_f32_32x32x16_bf16 v[98:113], v[168:171], v[202:205], v[98:113]
	v_mfma_f32_32x32x16_bf16 v[66:81], v[168:171], v[210:213], v[66:81]
	s_waitcnt lgkmcnt(3)
	v_mfma_f32_32x32x16_bf16 v[50:65], v[174:177], v[202:205], v[50:65]
	ds_read_b128 v[164:167], v172 offset:96
	ds_read_b128 v[168:171], v191 offset:96
	v_mfma_f32_32x32x16_bf16 v[18:33], v[174:177], v[210:213], v[18:33]
	s_waitcnt lgkmcnt(4)
	v_mfma_f32_32x32x16_bf16 v[34:49], v[194:197], v[202:205], v[34:49]
	v_mfma_f32_32x32x16_bf16 v[2:17], v[194:197], v[210:213], v[2:17]
	s_waitcnt vmcnt(7)
	ds_write_b128 v183, v[146:149] offset:55296
	s_waitcnt vmcnt(6)
	ds_write_b128 v183, v[158:161] offset:64512
	s_nop 0
	global_load_dwordx4 v[146:149], v233, s[100:101]
	global_load_dwordx4 v[158:161], v234, s[100:101]
	ds_read_b128 v[174:177], v208 offset:96
	ds_read_b128 v[194:197], v209 offset:96
	s_waitcnt lgkmcnt(5)
	v_mfma_f32_32x32x16_bf16 v[114:129], v[164:167], v[214:217], v[114:129]
	v_mfma_f32_32x32x16_bf16 v[82:97], v[164:167], v[218:221], v[82:97]
	s_waitcnt lgkmcnt(4)
	v_mfma_f32_32x32x16_bf16 v[98:113], v[168:171], v[214:217], v[98:113]
	v_mfma_f32_32x32x16_bf16 v[66:81], v[168:171], v[218:221], v[66:81]
	s_waitcnt lgkmcnt(1)
	v_mfma_f32_32x32x16_bf16 v[50:65], v[174:177], v[214:217], v[50:65]
	v_mfma_f32_32x32x16_bf16 v[18:33], v[174:177], v[218:221], v[18:33]
	s_waitcnt lgkmcnt(0)
	v_mfma_f32_32x32x16_bf16 v[34:49], v[194:197], v[214:217], v[34:49]
	v_mfma_f32_32x32x16_bf16 v[2:17], v[194:197], v[218:221], v[2:17]
	s_add_i32 s34, s34, 2
	s_cmp_gt_u32 s35, 13
	s_barrier
	s_cbranch_scc0 .LBB0_86
	v_mov_b32_e32 v212, v192
	s_ashr_i32 s47, s2, 14
	v_ashrrev_i32_e32 v164, 1, v212
	v_and_b32_e32 v164, 0xffffff80, v164
	v_bfe_u32 v0, v212, 5, 1
	v_add_u32_e32 v165, s3, v164
	s_movk_i32 s3, 0x1000
	v_ashrrev_i32_e32 v213, 10, v165
	v_and_b32_e32 v210, 0x380, v165
	v_and_b32_e32 v166, 0xdf, v212
	v_lshlrev_b32_e32 v211, 4, v0
	v_cmp_eq_u32_e32 vcc, s3, v165
	v_cmp_eq_u32_e64 s[10:11], 0, v0
	s_movk_i32 s3, 0x400
	v_mov_b32_e32 v0, s4
	v_or_b32_e32 v164, s4, v166
	v_cmp_lt_i32_e64 s[8:9], 1, v213
	v_or_b32_e32 v215, v210, v211
	s_and_b64 s[26:27], s[10:11], vcc
	v_cmp_gt_u32_e32 vcc, s3, v165
	v_bitop3_b32 v214, v166, s53, v0 bitop3:0xc8
	s_and_saveexec_b64 s[2:3], s[8:9]
	s_xor_b64 s[28:29], exec, s[2:3]
	s_cbranch_execz .LBB0_99
	v_cmp_lt_i32_e64 s[10:11], 2, v213
	s_and_saveexec_b64 s[2:3], s[10:11]
	s_xor_b64 s[30:31], exec, s[2:3]
	s_cbranch_execz .LBB0_96
	v_cmp_ne_u32_e64 s[10:11], 3, v213
	s_and_saveexec_b64 s[2:3], s[10:11]
	s_xor_b64 s[34:35], exec, s[2:3]
	s_cbranch_execz .LBB0_93
	s_and_saveexec_b64 s[36:37], s[26:27]
	s_cbranch_execz .LBB0_92
	v_lshlrev_b32_e32 v0, 2, v214
	v_lshl_add_u64 v[166:167], s[16:17], 0, v[0:1]
	global_load_dword v0, v1, s[18:19]
	v_mov_b32_e32 v197, 0x7f800000
	v_mov_b32_e32 v196, 0x3ecc95a3
	s_lshl_b32 s38, s47, 4
	s_ashr_i32 s39, s38, 31
	s_lshl_b64 s[2:3], s[38:39], 16
	s_waitcnt vmcnt(0)
	v_add_f32_e32 v0, v114, v0
	v_mul_f32_e64 v168, |v0|, s54
	v_fma_f32 v169, |v0|, s54, -v168
	v_rndne_f32_e32 v170, v168
	v_fma_f32 v169, |v0|, s55, v169
	v_sub_f32_e32 v168, v168, v170
	v_add_f32_e32 v168, v168, v169
	v_exp_f32_e32 v168, v168
	v_cvt_i32_f32_e32 v169, v170
	v_cmp_ngt_f32_e64 s[10:11], |v0|, s56
	v_min_f32_e32 v165, 0, v0
	v_ldexp_f32 v168, v168, v169
	v_cndmask_b32_e64 v168, 0, v168, s[10:11]
	v_cmp_nlt_f32_e64 s[10:11], |v0|, s57
	s_nop 1
	v_cndmask_b32_e64 v0, v197, v168, s[10:11]
	v_add_f32_e32 v170, 1.0, v0
	v_add_f32_e32 v168, -1.0, v170
	v_sub_f32_e32 v169, v168, v170
	v_add_f32_e32 v169, 1.0, v169
	v_sub_f32_e32 v168, v0, v168
	v_add_f32_e32 v171, v168, v169
	v_frexp_mant_f32_e32 v168, v170
	v_cmp_gt_f32_e64 s[10:11], s59, v168
	v_cvt_f64_f32_e32 v[168:169], v170
	v_frexp_exp_i32_f64_e32 v168, v[168:169]
	v_subbrev_co_u32_e64 v168, s[10:11], 0, v168, s[10:11]
	v_sub_u32_e32 v169, 0, v168
	v_ldexp_f32 v170, v170, v169
	v_ldexp_f32 v169, v171, v169
	v_add_f32_e32 v171, -1.0, v170
	v_add_f32_e32 v172, 1.0, v171
	v_sub_f32_e32 v172, v170, v172
	v_add_f32_e32 v172, v169, v172
	v_add_f32_e32 v174, v171, v172
	v_sub_f32_e32 v171, v171, v174
	v_add_f32_e32 v171, v172, v171
	v_add_f32_e32 v172, 1.0, v170
	v_add_f32_e32 v175, -1.0, v172
	v_sub_f32_e32 v170, v170, v175
	v_add_f32_e32 v169, v169, v170
	v_add_f32_e32 v170, v172, v169
	v_sub_f32_e32 v172, v172, v170
	v_add_f32_e32 v169, v169, v172
	v_rcp_f32_e32 v172, v170
	v_cvt_f32_i32_e32 v168, v168
	v_cmp_neq_f32_e64 s[10:11], s58, v0
	v_mul_f32_e32 v175, v174, v172
	v_mul_f32_e32 v176, v170, v175
	v_fma_f32 v177, v175, v170, -v176
	v_fmac_f32_e32 v177, v175, v169
	v_add_f32_e32 v194, v176, v177
;   DI void operator()(int tok0, int feat0, f32x16 (&acc)[2][2], int r, int hh) const {
;     ...
;           for (int i = 0; i < 16; ++i) {
;             const float xv = acc[0][mt][i] + bf[i];
;             const float ls = fminf(xv, 0.f) - log1pf(expf(-fabsf(xv)));
;             lf[((size_t)(b * 16 + i)) * SEQ + s] = ls;
;           }
	v_sub_f32_e32 v195, v174, v194
	v_sub_f32_e32 v174, v174, v195
	v_sub_f32_e32 v176, v194, v176
	v_sub_f32_e32 v174, v174, v194
	v_add_f32_e32 v171, v171, v174
	v_sub_f32_e32 v174, v176, v177
	v_add_f32_e32 v171, v174, v171
	v_add_f32_e32 v174, v195, v171
	v_mul_f32_e32 v176, v172, v174
	v_mul_f32_e32 v177, v170, v176
	v_fma_f32 v170, v176, v170, -v177
	v_fmac_f32_e32 v170, v176, v169
	v_sub_f32_e32 v169, v195, v174
	v_add_f32_e32 v169, v171, v169
	v_add_f32_e32 v171, v177, v170
	v_sub_f32_e32 v194, v174, v171
	v_sub_f32_e32 v174, v174, v194
	v_sub_f32_e32 v177, v171, v177
	v_sub_f32_e32 v171, v174, v171
	v_add_f32_e32 v169, v169, v171
	v_sub_f32_e32 v170, v177, v170
	v_add_f32_e32 v169, v170, v169
	v_add_f32_e32 v170, v175, v176
	v_add_f32_e32 v169, v194, v169
	v_sub_f32_e32 v171, v170, v175
	v_mul_f32_e32 v169, v172, v169
	v_sub_f32_e32 v171, v176, v171
	v_add_f32_e32 v169, v171, v169
	v_mul_f32_e32 v175, 0x3f317218, v168
	v_add_f32_e32 v171, v170, v169
	v_fma_f32 v176, v168, s60, -v175
	v_mul_f32_e32 v172, v171, v171
	v_fmac_f32_e32 v176, 0xb102e308, v168
	v_sub_f32_e32 v168, v171, v170
	v_fmamk_f32 v174, v172, 0x3e9b6dac, v196
	v_sub_f32_e32 v168, v169, v168
	v_add_f32_e32 v169, v175, v176
	v_fmaak_f32 v174, v172, v174, 0x3f2aaada
	v_sub_f32_e32 v170, v169, v175
	v_ldexp_f32 v175, v171, 1
	v_mul_f32_e32 v171, v171, v172
	v_mul_f32_e32 v171, v171, v174
	v_add_f32_e32 v172, v175, v171
	v_sub_f32_e32 v174, v172, v175
	v_ldexp_f32 v168, v168, 1
	v_sub_f32_e32 v171, v171, v174
	v_add_f32_e32 v168, v168, v171
	v_add_f32_e32 v171, v172, v168
	v_sub_f32_e32 v172, v171, v172
	v_sub_f32_e32 v168, v168, v172
	v_add_f32_e32 v172, v169, v171
	v_sub_f32_e32 v174, v172, v169
	v_sub_f32_e32 v175, v172, v174
	v_sub_f32_e32 v170, v176, v170
	v_sub_f32_e32 v169, v169, v175
	v_sub_f32_e32 v171, v171, v174
	v_add_f32_e32 v169, v171, v169
	v_add_f32_e32 v171, v170, v168
	v_sub_f32_e32 v174, v171, v170
	v_sub_f32_e32 v175, v171, v174
	v_sub_f32_e32 v170, v170, v175
	v_sub_f32_e32 v168, v168, v174
	v_add_f32_e32 v169, v171, v169
	v_add_f32_e32 v168, v168, v170
	v_add_f32_e32 v170, v172, v169
	v_sub_f32_e32 v171, v170, v172
	v_sub_f32_e32 v169, v169, v171
	v_add_f32_e32 v168, v168, v169
	v_add_f32_e32 v168, v170, v168
	v_cndmask_b32_e64 v168, v197, v168, s[10:11]
	v_cmp_lt_f32_e64 s[10:11], |v0|, s61
	s_nop 1
	v_cndmask_b32_e64 v0, v168, v0, s[10:11]
	v_sub_f32_e32 v0, v165, v0
	v_lshl_add_u64 v[168:169], v[166:167], 0, s[2:3]
	global_store_dword v[168:169], v0, off
	global_load_dword v0, v1, s[18:19] offset:4
	s_or_b32 s2, s38, 1
	s_ashr_i32 s3, s2, 31
	s_lshl_b64 s[2:3], s[2:3], 16
	s_waitcnt vmcnt(0)
	v_add_f32_e32 v0, v115, v0
	v_mul_f32_e64 v168, |v0|, s54
	v_fma_f32 v169, |v0|, s54, -v168
	v_rndne_f32_e32 v170, v168
	v_fma_f32 v169, |v0|, s55, v169
	v_sub_f32_e32 v168, v168, v170
	v_add_f32_e32 v168, v168, v169
	v_exp_f32_e32 v168, v168
	v_cvt_i32_f32_e32 v169, v170
	v_cmp_ngt_f32_e64 s[10:11], |v0|, s56
	v_min_f32_e32 v165, 0, v0
	v_ldexp_f32 v168, v168, v169
	v_cndmask_b32_e64 v168, 0, v168, s[10:11]
	v_cmp_nlt_f32_e64 s[10:11], |v0|, s57
	s_nop 1
	v_cndmask_b32_e64 v0, v197, v168, s[10:11]
	v_add_f32_e32 v170, 1.0, v0
	v_add_f32_e32 v168, -1.0, v170
	v_sub_f32_e32 v169, v168, v170
	v_add_f32_e32 v169, 1.0, v169
	v_sub_f32_e32 v168, v0, v168
	v_add_f32_e32 v171, v168, v169
	v_frexp_mant_f32_e32 v168, v170
	v_cmp_gt_f32_e64 s[10:11], s59, v168
	v_cvt_f64_f32_e32 v[168:169], v170
	v_frexp_exp_i32_f64_e32 v168, v[168:169]
	v_subbrev_co_u32_e64 v168, s[10:11], 0, v168, s[10:11]
	v_sub_u32_e32 v169, 0, v168
	v_ldexp_f32 v170, v170, v169
	v_ldexp_f32 v169, v171, v169
	v_add_f32_e32 v171, -1.0, v170
	v_add_f32_e32 v172, 1.0, v171
	v_sub_f32_e32 v172, v170, v172
	v_add_f32_e32 v172, v169, v172
	v_add_f32_e32 v174, v171, v172
	v_sub_f32_e32 v171, v171, v174
	v_add_f32_e32 v171, v172, v171
	v_add_f32_e32 v172, 1.0, v170
	v_add_f32_e32 v175, -1.0, v172
	v_sub_f32_e32 v170, v170, v175
	v_add_f32_e32 v169, v169, v170
	v_add_f32_e32 v170, v172, v169
	v_sub_f32_e32 v172, v172, v170
	v_add_f32_e32 v169, v169, v172
	v_rcp_f32_e32 v172, v170
	v_cvt_f32_i32_e32 v168, v168
	v_cmp_neq_f32_e64 s[10:11], s58, v0
	v_mul_f32_e32 v175, v174, v172
	v_mul_f32_e32 v176, v170, v175
	v_fma_f32 v177, v175, v170, -v176
	v_fmac_f32_e32 v177, v175, v169
	v_add_f32_e32 v194, v176, v177
	v_sub_f32_e32 v195, v174, v194
	v_sub_f32_e32 v174, v174, v195
	v_sub_f32_e32 v176, v194, v176
	v_sub_f32_e32 v174, v174, v194
	v_add_f32_e32 v171, v171, v174
	v_sub_f32_e32 v174, v176, v177
	v_add_f32_e32 v171, v174, v171
	v_add_f32_e32 v174, v195, v171
	v_mul_f32_e32 v176, v172, v174
	v_mul_f32_e32 v177, v170, v176
	v_fma_f32 v170, v176, v170, -v177
	v_fmac_f32_e32 v170, v176, v169
	v_sub_f32_e32 v169, v195, v174
	v_add_f32_e32 v169, v171, v169
	v_add_f32_e32 v171, v177, v170
	v_sub_f32_e32 v194, v174, v171
	v_sub_f32_e32 v174, v174, v194
	v_sub_f32_e32 v177, v171, v177
	v_sub_f32_e32 v171, v174, v171
	v_add_f32_e32 v169, v169, v171
	v_sub_f32_e32 v170, v177, v170
	v_add_f32_e32 v169, v170, v169
	v_add_f32_e32 v170, v175, v176
	v_add_f32_e32 v169, v194, v169
	v_sub_f32_e32 v171, v170, v175
	v_mul_f32_e32 v169, v172, v169
	v_sub_f32_e32 v171, v176, v171
	v_add_f32_e32 v169, v171, v169
	v_mul_f32_e32 v175, 0x3f317218, v168
	v_add_f32_e32 v171, v170, v169
	v_fma_f32 v176, v168, s60, -v175
	v_mul_f32_e32 v172, v171, v171
	v_fmac_f32_e32 v176, 0xb102e308, v168
	v_sub_f32_e32 v168, v171, v170
	v_fmamk_f32 v174, v172, 0x3e9b6dac, v196
	v_sub_f32_e32 v168, v169, v168
	v_add_f32_e32 v169, v175, v176
	v_fmaak_f32 v174, v172, v174, 0x3f2aaada
	v_sub_f32_e32 v170, v169, v175
	v_ldexp_f32 v175, v171, 1
	v_mul_f32_e32 v171, v171, v172
	v_mul_f32_e32 v171, v171, v174
	v_add_f32_e32 v172, v175, v171
	v_sub_f32_e32 v174, v172, v175
	v_ldexp_f32 v168, v168, 1
	v_sub_f32_e32 v171, v171, v174
	v_add_f32_e32 v168, v168, v171
	v_add_f32_e32 v171, v172, v168
	v_sub_f32_e32 v172, v171, v172
	v_sub_f32_e32 v168, v168, v172
	v_add_f32_e32 v172, v169, v171
	v_sub_f32_e32 v174, v172, v169
	v_sub_f32_e32 v175, v172, v174
	v_sub_f32_e32 v170, v176, v170
	v_sub_f32_e32 v169, v169, v175
	v_sub_f32_e32 v171, v171, v174
	v_add_f32_e32 v169, v171, v169
	v_add_f32_e32 v171, v170, v168
	v_sub_f32_e32 v174, v171, v170
	v_sub_f32_e32 v175, v171, v174
	v_sub_f32_e32 v170, v170, v175
	v_sub_f32_e32 v168, v168, v174
	v_add_f32_e32 v169, v171, v169
	v_add_f32_e32 v168, v168, v170
	v_add_f32_e32 v170, v172, v169
	v_sub_f32_e32 v171, v170, v172
	v_sub_f32_e32 v169, v169, v171
	v_add_f32_e32 v168, v168, v169
	v_add_f32_e32 v168, v170, v168
	v_cndmask_b32_e64 v168, v197, v168, s[10:11]
	v_cmp_lt_f32_e64 s[10:11], |v0|, s61
	s_nop 1
	v_cndmask_b32_e64 v0, v168, v0, s[10:11]
	v_sub_f32_e32 v0, v165, v0
	v_lshl_add_u64 v[168:169], v[166:167], 0, s[2:3]
	global_store_dword v[168:169], v0, off
	global_load_dword v0, v1, s[18:19] offset:8
	s_or_b32 s2, s38, 2
	s_ashr_i32 s3, s2, 31
	s_lshl_b64 s[2:3], s[2:3], 16
	s_waitcnt vmcnt(0)
;   DI void operator()(int tok0, int feat0, f32x16 (&acc)[2][2], int r, int hh) const {
;     ...
;           for (int i = 0; i < 16; ++i) {
;             const float xv = acc[0][mt][i] + bf[i];
;             const float ls = fminf(xv, 0.f) - log1pf(expf(-fabsf(xv)));
;             lf[((size_t)(b * 16 + i)) * SEQ + s] = ls;
;           }
	v_add_f32_e32 v0, v116, v0
	v_mul_f32_e64 v168, |v0|, s54
	v_fma_f32 v169, |v0|, s54, -v168
	v_rndne_f32_e32 v170, v168
	v_fma_f32 v169, |v0|, s55, v169
	v_sub_f32_e32 v168, v168, v170
	v_add_f32_e32 v168, v168, v169
	v_exp_f32_e32 v168, v168
	v_cvt_i32_f32_e32 v169, v170
	v_cmp_ngt_f32_e64 s[10:11], |v0|, s56
	v_min_f32_e32 v165, 0, v0
	v_ldexp_f32 v168, v168, v169
	v_cndmask_b32_e64 v168, 0, v168, s[10:11]
	v_cmp_nlt_f32_e64 s[10:11], |v0|, s57
	s_nop 1
	v_cndmask_b32_e64 v0, v197, v168, s[10:11]
	v_add_f32_e32 v170, 1.0, v0
	v_add_f32_e32 v168, -1.0, v170
	v_sub_f32_e32 v169, v168, v170
	v_add_f32_e32 v169, 1.0, v169
	v_sub_f32_e32 v168, v0, v168
	v_add_f32_e32 v171, v168, v169
	v_frexp_mant_f32_e32 v168, v170
	v_cmp_gt_f32_e64 s[10:11], s59, v168
	v_cvt_f64_f32_e32 v[168:169], v170
	v_frexp_exp_i32_f64_e32 v168, v[168:169]
	v_subbrev_co_u32_e64 v168, s[10:11], 0, v168, s[10:11]
	v_sub_u32_e32 v169, 0, v168
	v_ldexp_f32 v170, v170, v169
	v_ldexp_f32 v169, v171, v169
	v_add_f32_e32 v171, -1.0, v170
	v_add_f32_e32 v172, 1.0, v171
	v_sub_f32_e32 v172, v170, v172
	v_add_f32_e32 v172, v169, v172
	v_add_f32_e32 v174, v171, v172
	v_sub_f32_e32 v171, v171, v174
	v_add_f32_e32 v171, v172, v171
	v_add_f32_e32 v172, 1.0, v170
	v_add_f32_e32 v175, -1.0, v172
	v_sub_f32_e32 v170, v170, v175
	v_add_f32_e32 v169, v169, v170
	v_add_f32_e32 v170, v172, v169
	v_sub_f32_e32 v172, v172, v170
	v_add_f32_e32 v169, v169, v172
	v_rcp_f32_e32 v172, v170
	v_cvt_f32_i32_e32 v168, v168
	v_cmp_neq_f32_e64 s[10:11], s58, v0
	v_mul_f32_e32 v175, v174, v172
	v_mul_f32_e32 v176, v170, v175
	v_fma_f32 v177, v175, v170, -v176
	v_fmac_f32_e32 v177, v175, v169
	v_add_f32_e32 v194, v176, v177
	v_sub_f32_e32 v195, v174, v194
	v_sub_f32_e32 v174, v174, v195
	v_sub_f32_e32 v176, v194, v176
	v_sub_f32_e32 v174, v174, v194
	v_add_f32_e32 v171, v171, v174
	v_sub_f32_e32 v174, v176, v177
	v_add_f32_e32 v171, v174, v171
	v_add_f32_e32 v174, v195, v171
	v_mul_f32_e32 v176, v172, v174
	v_mul_f32_e32 v177, v170, v176
	v_fma_f32 v170, v176, v170, -v177
	v_fmac_f32_e32 v170, v176, v169
	v_sub_f32_e32 v169, v195, v174
	v_add_f32_e32 v169, v171, v169
	v_add_f32_e32 v171, v177, v170
	v_sub_f32_e32 v194, v174, v171
	v_sub_f32_e32 v174, v174, v194
	v_sub_f32_e32 v177, v171, v177
	v_sub_f32_e32 v171, v174, v171
	v_add_f32_e32 v169, v169, v171
	v_sub_f32_e32 v170, v177, v170
	v_add_f32_e32 v169, v170, v169
	v_add_f32_e32 v170, v175, v176
	v_add_f32_e32 v169, v194, v169
	v_sub_f32_e32 v171, v170, v175
	v_mul_f32_e32 v169, v172, v169
	v_sub_f32_e32 v171, v176, v171
	v_add_f32_e32 v169, v171, v169
	v_mul_f32_e32 v175, 0x3f317218, v168
	v_add_f32_e32 v171, v170, v169
	v_fma_f32 v176, v168, s60, -v175
	v_mul_f32_e32 v172, v171, v171
	v_fmac_f32_e32 v176, 0xb102e308, v168
	v_sub_f32_e32 v168, v171, v170
	v_fmamk_f32 v174, v172, 0x3e9b6dac, v196
	v_sub_f32_e32 v168, v169, v168
	v_add_f32_e32 v169, v175, v176
	v_fmaak_f32 v174, v172, v174, 0x3f2aaada
	v_sub_f32_e32 v170, v169, v175
	v_ldexp_f32 v175, v171, 1
	v_mul_f32_e32 v171, v171, v172
	v_mul_f32_e32 v171, v171, v174
	v_add_f32_e32 v172, v175, v171
	v_sub_f32_e32 v174, v172, v175
	v_ldexp_f32 v168, v168, 1
	v_sub_f32_e32 v171, v171, v174
	v_add_f32_e32 v168, v168, v171
	v_add_f32_e32 v171, v172, v168
	v_sub_f32_e32 v172, v171, v172
	v_sub_f32_e32 v168, v168, v172
	v_add_f32_e32 v172, v169, v171
	v_sub_f32_e32 v174, v172, v169
	v_sub_f32_e32 v175, v172, v174
	v_sub_f32_e32 v170, v176, v170
	v_sub_f32_e32 v169, v169, v175
	v_sub_f32_e32 v171, v171, v174
	v_add_f32_e32 v169, v171, v169
	v_add_f32_e32 v171, v170, v168
	v_sub_f32_e32 v174, v171, v170
	v_sub_f32_e32 v175, v171, v174
	v_sub_f32_e32 v170, v170, v175
	v_sub_f32_e32 v168, v168, v174
	v_add_f32_e32 v169, v171, v169
	v_add_f32_e32 v168, v168, v170
	v_add_f32_e32 v170, v172, v169
	v_sub_f32_e32 v171, v170, v172
	v_sub_f32_e32 v169, v169, v171
	v_add_f32_e32 v168, v168, v169
	v_add_f32_e32 v168, v170, v168
	v_cndmask_b32_e64 v168, v197, v168, s[10:11]
	v_cmp_lt_f32_e64 s[10:11], |v0|, s61
	s_nop 1
	v_cndmask_b32_e64 v0, v168, v0, s[10:11]
	v_sub_f32_e32 v0, v165, v0
	v_lshl_add_u64 v[168:169], v[166:167], 0, s[2:3]
	global_store_dword v[168:169], v0, off
	global_load_dword v0, v1, s[18:19] offset:12
	s_or_b32 s2, s38, 3
	s_ashr_i32 s3, s2, 31
	s_lshl_b64 s[2:3], s[2:3], 16
	s_waitcnt vmcnt(0)
;   DI void operator()(int tok0, int feat0, f32x16 (&acc)[2][2], int r, int hh) const {
;     ...
;           for (int i = 0; i < 16; ++i) {
;             const float xv = acc[0][mt][i] + bf[i];
;             const float ls = fminf(xv, 0.f) - log1pf(expf(-fabsf(xv)));
;             lf[((size_t)(b * 16 + i)) * SEQ + s] = ls;
;           }
	v_add_f32_e32 v0, v117, v0
	v_mul_f32_e64 v168, |v0|, s54
	v_fma_f32 v169, |v0|, s54, -v168
	v_rndne_f32_e32 v170, v168
	v_fma_f32 v169, |v0|, s55, v169
	v_sub_f32_e32 v168, v168, v170
	v_add_f32_e32 v168, v168, v169
	v_exp_f32_e32 v168, v168
	v_cvt_i32_f32_e32 v169, v170
	v_cmp_ngt_f32_e64 s[10:11], |v0|, s56
	v_min_f32_e32 v165, 0, v0
	v_ldexp_f32 v168, v168, v169
	v_cndmask_b32_e64 v168, 0, v168, s[10:11]
	v_cmp_nlt_f32_e64 s[10:11], |v0|, s57
	s_nop 1
	v_cndmask_b32_e64 v0, v197, v168, s[10:11]
	v_add_f32_e32 v170, 1.0, v0
	v_add_f32_e32 v168, -1.0, v170
	v_sub_f32_e32 v169, v168, v170
	v_add_f32_e32 v169, 1.0, v169
	v_sub_f32_e32 v168, v0, v168
	v_add_f32_e32 v171, v168, v169
	v_frexp_mant_f32_e32 v168, v170
	v_cmp_gt_f32_e64 s[10:11], s59, v168
	v_cvt_f64_f32_e32 v[168:169], v170
	v_frexp_exp_i32_f64_e32 v168, v[168:169]
	v_subbrev_co_u32_e64 v168, s[10:11], 0, v168, s[10:11]
	v_sub_u32_e32 v169, 0, v168
	v_ldexp_f32 v170, v170, v169
	v_ldexp_f32 v169, v171, v169
	v_add_f32_e32 v171, -1.0, v170
	v_add_f32_e32 v172, 1.0, v171
	v_sub_f32_e32 v172, v170, v172
	v_add_f32_e32 v172, v169, v172
	v_add_f32_e32 v174, v171, v172
	v_sub_f32_e32 v171, v171, v174
	v_add_f32_e32 v171, v172, v171
	v_add_f32_e32 v172, 1.0, v170
	v_add_f32_e32 v175, -1.0, v172
	v_sub_f32_e32 v170, v170, v175
	v_add_f32_e32 v169, v169, v170
	v_add_f32_e32 v170, v172, v169
	v_sub_f32_e32 v172, v172, v170
	v_add_f32_e32 v169, v169, v172
	v_rcp_f32_e32 v172, v170
	v_cvt_f32_i32_e32 v168, v168
	v_cmp_neq_f32_e64 s[10:11], s58, v0
	v_mul_f32_e32 v175, v174, v172
	v_mul_f32_e32 v176, v170, v175
	v_fma_f32 v177, v175, v170, -v176
	v_fmac_f32_e32 v177, v175, v169
	v_add_f32_e32 v194, v176, v177
	v_sub_f32_e32 v195, v174, v194
	v_sub_f32_e32 v174, v174, v195
	v_sub_f32_e32 v176, v194, v176
	v_sub_f32_e32 v174, v174, v194
	v_add_f32_e32 v171, v171, v174
	v_sub_f32_e32 v174, v176, v177
	v_add_f32_e32 v171, v174, v171
	v_add_f32_e32 v174, v195, v171
	v_mul_f32_e32 v176, v172, v174
	v_mul_f32_e32 v177, v170, v176
	v_fma_f32 v170, v176, v170, -v177
	v_fmac_f32_e32 v170, v176, v169
	v_sub_f32_e32 v169, v195, v174
	v_add_f32_e32 v169, v171, v169
	v_add_f32_e32 v171, v177, v170
	v_sub_f32_e32 v194, v174, v171
	v_sub_f32_e32 v174, v174, v194
	v_sub_f32_e32 v177, v171, v177
	v_sub_f32_e32 v171, v174, v171
	v_add_f32_e32 v169, v169, v171
	v_sub_f32_e32 v170, v177, v170
	v_add_f32_e32 v169, v170, v169
	v_add_f32_e32 v170, v175, v176
	v_add_f32_e32 v169, v194, v169
	v_sub_f32_e32 v171, v170, v175
	v_mul_f32_e32 v169, v172, v169
	v_sub_f32_e32 v171, v176, v171
	v_add_f32_e32 v169, v171, v169
	v_mul_f32_e32 v175, 0x3f317218, v168
	v_add_f32_e32 v171, v170, v169
	v_fma_f32 v176, v168, s60, -v175
	v_mul_f32_e32 v172, v171, v171
	v_fmac_f32_e32 v176, 0xb102e308, v168
	v_sub_f32_e32 v168, v171, v170
	v_fmamk_f32 v174, v172, 0x3e9b6dac, v196
	v_sub_f32_e32 v168, v169, v168
	v_add_f32_e32 v169, v175, v176
	v_fmaak_f32 v174, v172, v174, 0x3f2aaada
	v_sub_f32_e32 v170, v169, v175
	v_ldexp_f32 v175, v171, 1
	v_mul_f32_e32 v171, v171, v172
	v_mul_f32_e32 v171, v171, v174
	v_add_f32_e32 v172, v175, v171
	v_sub_f32_e32 v174, v172, v175
	v_ldexp_f32 v168, v168, 1
	v_sub_f32_e32 v171, v171, v174
	v_add_f32_e32 v168, v168, v171
	v_add_f32_e32 v171, v172, v168
	v_sub_f32_e32 v172, v171, v172
	v_sub_f32_e32 v168, v168, v172
	v_add_f32_e32 v172, v169, v171
	v_sub_f32_e32 v174, v172, v169
	v_sub_f32_e32 v175, v172, v174
	v_sub_f32_e32 v170, v176, v170
	v_sub_f32_e32 v169, v169, v175
	v_sub_f32_e32 v171, v171, v174
	v_add_f32_e32 v169, v171, v169
	v_add_f32_e32 v171, v170, v168
	v_sub_f32_e32 v174, v171, v170
	v_sub_f32_e32 v175, v171, v174
	v_sub_f32_e32 v170, v170, v175
	v_sub_f32_e32 v168, v168, v174
	v_add_f32_e32 v169, v171, v169
	v_add_f32_e32 v168, v168, v170
	v_add_f32_e32 v170, v172, v169
	v_sub_f32_e32 v171, v170, v172
	v_sub_f32_e32 v169, v169, v171
	v_add_f32_e32 v168, v168, v169
	v_add_f32_e32 v168, v170, v168
	v_cndmask_b32_e64 v168, v197, v168, s[10:11]
	v_cmp_lt_f32_e64 s[10:11], |v0|, s61
	s_nop 1
	v_cndmask_b32_e64 v0, v168, v0, s[10:11]
	v_sub_f32_e32 v0, v165, v0
	v_lshl_add_u64 v[168:169], v[166:167], 0, s[2:3]
	global_store_dword v[168:169], v0, off
	global_load_dword v0, v1, s[18:19] offset:16
	s_or_b32 s2, s38, 4
	s_ashr_i32 s3, s2, 31
	s_lshl_b64 s[2:3], s[2:3], 16
	s_waitcnt vmcnt(0)
;   DI void operator()(int tok0, int feat0, f32x16 (&acc)[2][2], int r, int hh) const {
;     ...
;           for (int i = 0; i < 16; ++i) {
;             const float xv = acc[0][mt][i] + bf[i];
;             const float ls = fminf(xv, 0.f) - log1pf(expf(-fabsf(xv)));
;             lf[((size_t)(b * 16 + i)) * SEQ + s] = ls;
;           }
	v_add_f32_e32 v0, v118, v0
	v_mul_f32_e64 v168, |v0|, s54
	v_fma_f32 v169, |v0|, s54, -v168
	v_rndne_f32_e32 v170, v168
	v_fma_f32 v169, |v0|, s55, v169
	v_sub_f32_e32 v168, v168, v170
	v_add_f32_e32 v168, v168, v169
	v_exp_f32_e32 v168, v168
	v_cvt_i32_f32_e32 v169, v170
	v_cmp_ngt_f32_e64 s[10:11], |v0|, s56
	v_min_f32_e32 v165, 0, v0
	v_ldexp_f32 v168, v168, v169
	v_cndmask_b32_e64 v168, 0, v168, s[10:11]
	v_cmp_nlt_f32_e64 s[10:11], |v0|, s57
	s_nop 1
	v_cndmask_b32_e64 v0, v197, v168, s[10:11]
	v_add_f32_e32 v170, 1.0, v0
	v_add_f32_e32 v168, -1.0, v170
	v_sub_f32_e32 v169, v168, v170
	v_add_f32_e32 v169, 1.0, v169
	v_sub_f32_e32 v168, v0, v168
	v_add_f32_e32 v171, v168, v169
	v_frexp_mant_f32_e32 v168, v170
	v_cmp_gt_f32_e64 s[10:11], s59, v168
	v_cvt_f64_f32_e32 v[168:169], v170
	v_frexp_exp_i32_f64_e32 v168, v[168:169]
	v_subbrev_co_u32_e64 v168, s[10:11], 0, v168, s[10:11]
	v_sub_u32_e32 v169, 0, v168
	v_ldexp_f32 v170, v170, v169
	v_ldexp_f32 v169, v171, v169
	v_add_f32_e32 v171, -1.0, v170
	v_add_f32_e32 v172, 1.0, v171
	v_sub_f32_e32 v172, v170, v172
	v_add_f32_e32 v172, v169, v172
	v_add_f32_e32 v174, v171, v172
	v_sub_f32_e32 v171, v171, v174
	v_add_f32_e32 v171, v172, v171
	v_add_f32_e32 v172, 1.0, v170
	v_add_f32_e32 v175, -1.0, v172
	v_sub_f32_e32 v170, v170, v175
	v_add_f32_e32 v169, v169, v170
	v_add_f32_e32 v170, v172, v169
	v_sub_f32_e32 v172, v172, v170
	v_add_f32_e32 v169, v169, v172
	v_rcp_f32_e32 v172, v170
	v_cvt_f32_i32_e32 v168, v168
	v_cmp_neq_f32_e64 s[10:11], s58, v0
	v_mul_f32_e32 v175, v174, v172
	v_mul_f32_e32 v176, v170, v175
	v_fma_f32 v177, v175, v170, -v176
	v_fmac_f32_e32 v177, v175, v169
	v_add_f32_e32 v194, v176, v177
	v_sub_f32_e32 v195, v174, v194
	v_sub_f32_e32 v174, v174, v195
	v_sub_f32_e32 v176, v194, v176
	v_sub_f32_e32 v174, v174, v194
	v_add_f32_e32 v171, v171, v174
	v_sub_f32_e32 v174, v176, v177
	v_add_f32_e32 v171, v174, v171
	v_add_f32_e32 v174, v195, v171
	v_mul_f32_e32 v176, v172, v174
	v_mul_f32_e32 v177, v170, v176
	v_fma_f32 v170, v176, v170, -v177
	v_fmac_f32_e32 v170, v176, v169
	v_sub_f32_e32 v169, v195, v174
	v_add_f32_e32 v169, v171, v169
	v_add_f32_e32 v171, v177, v170
	v_sub_f32_e32 v194, v174, v171
	v_sub_f32_e32 v174, v174, v194
	v_sub_f32_e32 v177, v171, v177
	v_sub_f32_e32 v171, v174, v171
	v_add_f32_e32 v169, v169, v171
	v_sub_f32_e32 v170, v177, v170
	v_add_f32_e32 v169, v170, v169
	v_add_f32_e32 v170, v175, v176
	v_add_f32_e32 v169, v194, v169
	v_sub_f32_e32 v171, v170, v175
	v_mul_f32_e32 v169, v172, v169
	v_sub_f32_e32 v171, v176, v171
	v_add_f32_e32 v169, v171, v169
	v_mul_f32_e32 v175, 0x3f317218, v168
	v_add_f32_e32 v171, v170, v169
	v_fma_f32 v176, v168, s60, -v175
	v_mul_f32_e32 v172, v171, v171
	v_fmac_f32_e32 v176, 0xb102e308, v168
	v_sub_f32_e32 v168, v171, v170
	v_fmamk_f32 v174, v172, 0x3e9b6dac, v196
	v_sub_f32_e32 v168, v169, v168
	v_add_f32_e32 v169, v175, v176
	v_fmaak_f32 v174, v172, v174, 0x3f2aaada
	v_sub_f32_e32 v170, v169, v175
	v_ldexp_f32 v175, v171, 1
	v_mul_f32_e32 v171, v171, v172
	v_mul_f32_e32 v171, v171, v174
	v_add_f32_e32 v172, v175, v171
	v_sub_f32_e32 v174, v172, v175
	v_ldexp_f32 v168, v168, 1
	v_sub_f32_e32 v171, v171, v174
	v_add_f32_e32 v168, v168, v171
	v_add_f32_e32 v171, v172, v168
	v_sub_f32_e32 v172, v171, v172
	v_sub_f32_e32 v168, v168, v172
	v_add_f32_e32 v172, v169, v171
	v_sub_f32_e32 v174, v172, v169
	v_sub_f32_e32 v175, v172, v174
	v_sub_f32_e32 v170, v176, v170
	v_sub_f32_e32 v169, v169, v175
	v_sub_f32_e32 v171, v171, v174
	v_add_f32_e32 v169, v171, v169
	v_add_f32_e32 v171, v170, v168
	v_sub_f32_e32 v174, v171, v170
	v_sub_f32_e32 v175, v171, v174
	v_sub_f32_e32 v170, v170, v175
	v_sub_f32_e32 v168, v168, v174
	v_add_f32_e32 v169, v171, v169
	v_add_f32_e32 v168, v168, v170
	v_add_f32_e32 v170, v172, v169
	v_sub_f32_e32 v171, v170, v172
	v_sub_f32_e32 v169, v169, v171
	v_add_f32_e32 v168, v168, v169
	v_add_f32_e32 v168, v170, v168
	v_cndmask_b32_e64 v168, v197, v168, s[10:11]
	v_cmp_lt_f32_e64 s[10:11], |v0|, s61
	s_nop 1
	v_cndmask_b32_e64 v0, v168, v0, s[10:11]
	v_sub_f32_e32 v0, v165, v0
	v_lshl_add_u64 v[168:169], v[166:167], 0, s[2:3]
	global_store_dword v[168:169], v0, off
	global_load_dword v0, v1, s[18:19] offset:20
	s_or_b32 s2, s38, 5
	s_ashr_i32 s3, s2, 31
	s_lshl_b64 s[2:3], s[2:3], 16
	s_waitcnt vmcnt(0)
;   DI void operator()(int tok0, int feat0, f32x16 (&acc)[2][2], int r, int hh) const {
;     ...
;           for (int i = 0; i < 16; ++i) {
;             const float xv = acc[0][mt][i] + bf[i];
;             const float ls = fminf(xv, 0.f) - log1pf(expf(-fabsf(xv)));
;             lf[((size_t)(b * 16 + i)) * SEQ + s] = ls;
;           }
	v_add_f32_e32 v0, v119, v0
	v_mul_f32_e64 v168, |v0|, s54
	v_fma_f32 v169, |v0|, s54, -v168
	v_rndne_f32_e32 v170, v168
	v_fma_f32 v169, |v0|, s55, v169
	v_sub_f32_e32 v168, v168, v170
	v_add_f32_e32 v168, v168, v169
	v_exp_f32_e32 v168, v168
	v_cvt_i32_f32_e32 v169, v170
	v_cmp_ngt_f32_e64 s[10:11], |v0|, s56
	v_min_f32_e32 v165, 0, v0
	v_ldexp_f32 v168, v168, v169
	v_cndmask_b32_e64 v168, 0, v168, s[10:11]
	v_cmp_nlt_f32_e64 s[10:11], |v0|, s57
	s_nop 1
	v_cndmask_b32_e64 v0, v197, v168, s[10:11]
	v_add_f32_e32 v170, 1.0, v0
	v_add_f32_e32 v168, -1.0, v170
	v_sub_f32_e32 v169, v168, v170
	v_add_f32_e32 v169, 1.0, v169
	v_sub_f32_e32 v168, v0, v168
	v_add_f32_e32 v171, v168, v169
	v_frexp_mant_f32_e32 v168, v170
	v_cmp_gt_f32_e64 s[10:11], s59, v168
	v_cvt_f64_f32_e32 v[168:169], v170
	v_frexp_exp_i32_f64_e32 v168, v[168:169]
	v_subbrev_co_u32_e64 v168, s[10:11], 0, v168, s[10:11]
	v_sub_u32_e32 v169, 0, v168
	v_ldexp_f32 v170, v170, v169
	v_ldexp_f32 v169, v171, v169
	v_add_f32_e32 v171, -1.0, v170
	v_add_f32_e32 v172, 1.0, v171
	v_sub_f32_e32 v172, v170, v172
	v_add_f32_e32 v172, v169, v172
	v_add_f32_e32 v174, v171, v172
	v_sub_f32_e32 v171, v171, v174
	v_add_f32_e32 v171, v172, v171
	v_add_f32_e32 v172, 1.0, v170
	v_add_f32_e32 v175, -1.0, v172
	v_sub_f32_e32 v170, v170, v175
	v_add_f32_e32 v169, v169, v170
	v_add_f32_e32 v170, v172, v169
	v_sub_f32_e32 v172, v172, v170
	v_add_f32_e32 v169, v169, v172
	v_rcp_f32_e32 v172, v170
	v_cvt_f32_i32_e32 v168, v168
	v_cmp_neq_f32_e64 s[10:11], s58, v0
	v_mul_f32_e32 v175, v174, v172
	v_mul_f32_e32 v176, v170, v175
	v_fma_f32 v177, v175, v170, -v176
	v_fmac_f32_e32 v177, v175, v169
	v_add_f32_e32 v194, v176, v177
	v_sub_f32_e32 v195, v174, v194
	v_sub_f32_e32 v174, v174, v195
	v_sub_f32_e32 v176, v194, v176
	v_sub_f32_e32 v174, v174, v194
	v_add_f32_e32 v171, v171, v174
	v_sub_f32_e32 v174, v176, v177
	v_add_f32_e32 v171, v174, v171
	v_add_f32_e32 v174, v195, v171
	v_mul_f32_e32 v176, v172, v174
	v_mul_f32_e32 v177, v170, v176
	v_fma_f32 v170, v176, v170, -v177
	v_fmac_f32_e32 v170, v176, v169
	v_sub_f32_e32 v169, v195, v174
	v_add_f32_e32 v169, v171, v169
	v_add_f32_e32 v171, v177, v170
	v_sub_f32_e32 v194, v174, v171
	v_sub_f32_e32 v174, v174, v194
	v_sub_f32_e32 v177, v171, v177
	v_sub_f32_e32 v171, v174, v171
	v_add_f32_e32 v169, v169, v171
	v_sub_f32_e32 v170, v177, v170
	v_add_f32_e32 v169, v170, v169
	v_add_f32_e32 v170, v175, v176
	v_add_f32_e32 v169, v194, v169
	v_sub_f32_e32 v171, v170, v175
	v_mul_f32_e32 v169, v172, v169
	v_sub_f32_e32 v171, v176, v171
	v_add_f32_e32 v169, v171, v169
	v_mul_f32_e32 v175, 0x3f317218, v168
	v_add_f32_e32 v171, v170, v169
	v_fma_f32 v176, v168, s60, -v175
	v_mul_f32_e32 v172, v171, v171
	v_fmac_f32_e32 v176, 0xb102e308, v168
	v_sub_f32_e32 v168, v171, v170
	v_fmamk_f32 v174, v172, 0x3e9b6dac, v196
	v_sub_f32_e32 v168, v169, v168
	v_add_f32_e32 v169, v175, v176
	v_fmaak_f32 v174, v172, v174, 0x3f2aaada
	v_sub_f32_e32 v170, v169, v175
	v_ldexp_f32 v175, v171, 1
	v_mul_f32_e32 v171, v171, v172
	v_mul_f32_e32 v171, v171, v174
	v_add_f32_e32 v172, v175, v171
	v_sub_f32_e32 v174, v172, v175
	v_ldexp_f32 v168, v168, 1
	v_sub_f32_e32 v171, v171, v174
	v_add_f32_e32 v168, v168, v171
	v_add_f32_e32 v171, v172, v168
	v_sub_f32_e32 v172, v171, v172
	v_sub_f32_e32 v168, v168, v172
	v_add_f32_e32 v172, v169, v171
	v_sub_f32_e32 v174, v172, v169
	v_sub_f32_e32 v175, v172, v174
	v_sub_f32_e32 v170, v176, v170
	v_sub_f32_e32 v169, v169, v175
	v_sub_f32_e32 v171, v171, v174
	v_add_f32_e32 v169, v171, v169
	v_add_f32_e32 v171, v170, v168
	v_sub_f32_e32 v174, v171, v170
	v_sub_f32_e32 v175, v171, v174
	v_sub_f32_e32 v170, v170, v175
	v_sub_f32_e32 v168, v168, v174
	v_add_f32_e32 v169, v171, v169
	v_add_f32_e32 v168, v168, v170
	v_add_f32_e32 v170, v172, v169
	v_sub_f32_e32 v171, v170, v172
	v_sub_f32_e32 v169, v169, v171
	v_add_f32_e32 v168, v168, v169
	v_add_f32_e32 v168, v170, v168
	v_cndmask_b32_e64 v168, v197, v168, s[10:11]
	v_cmp_lt_f32_e64 s[10:11], |v0|, s61
	s_nop 1
	v_cndmask_b32_e64 v0, v168, v0, s[10:11]
	v_sub_f32_e32 v0, v165, v0
	v_lshl_add_u64 v[168:169], v[166:167], 0, s[2:3]
	global_store_dword v[168:169], v0, off
	global_load_dword v0, v1, s[18:19] offset:24
	s_or_b32 s2, s38, 6
	s_ashr_i32 s3, s2, 31
	s_lshl_b64 s[2:3], s[2:3], 16
	s_waitcnt vmcnt(0)
;   DI void operator()(int tok0, int feat0, f32x16 (&acc)[2][2], int r, int hh) const {
;     ...
;           for (int i = 0; i < 16; ++i) {
;             const float xv = acc[0][mt][i] + bf[i];
;             const float ls = fminf(xv, 0.f) - log1pf(expf(-fabsf(xv)));
;             lf[((size_t)(b * 16 + i)) * SEQ + s] = ls;
;           }
	v_add_f32_e32 v0, v120, v0
	v_mul_f32_e64 v168, |v0|, s54
	v_fma_f32 v169, |v0|, s54, -v168
	v_rndne_f32_e32 v170, v168
	v_fma_f32 v169, |v0|, s55, v169
	v_sub_f32_e32 v168, v168, v170
	v_add_f32_e32 v168, v168, v169
	v_exp_f32_e32 v168, v168
	v_cvt_i32_f32_e32 v169, v170
	v_cmp_ngt_f32_e64 s[10:11], |v0|, s56
	v_min_f32_e32 v165, 0, v0
	v_ldexp_f32 v168, v168, v169
	v_cndmask_b32_e64 v168, 0, v168, s[10:11]
	v_cmp_nlt_f32_e64 s[10:11], |v0|, s57
	s_nop 1
	v_cndmask_b32_e64 v0, v197, v168, s[10:11]
	v_add_f32_e32 v170, 1.0, v0
	v_add_f32_e32 v168, -1.0, v170
	v_sub_f32_e32 v169, v168, v170
	v_add_f32_e32 v169, 1.0, v169
	v_sub_f32_e32 v168, v0, v168
	v_add_f32_e32 v171, v168, v169
	v_frexp_mant_f32_e32 v168, v170
	v_cmp_gt_f32_e64 s[10:11], s59, v168
	v_cvt_f64_f32_e32 v[168:169], v170
	v_frexp_exp_i32_f64_e32 v168, v[168:169]
	v_subbrev_co_u32_e64 v168, s[10:11], 0, v168, s[10:11]
	v_sub_u32_e32 v169, 0, v168
	v_ldexp_f32 v170, v170, v169
	v_ldexp_f32 v169, v171, v169
	v_add_f32_e32 v171, -1.0, v170
	v_add_f32_e32 v172, 1.0, v171
	v_sub_f32_e32 v172, v170, v172
	v_add_f32_e32 v172, v169, v172
	v_add_f32_e32 v174, v171, v172
	v_sub_f32_e32 v171, v171, v174
	v_add_f32_e32 v171, v172, v171
	v_add_f32_e32 v172, 1.0, v170
	v_add_f32_e32 v175, -1.0, v172
	v_sub_f32_e32 v170, v170, v175
	v_add_f32_e32 v169, v169, v170
	v_add_f32_e32 v170, v172, v169
	v_sub_f32_e32 v172, v172, v170
	v_add_f32_e32 v169, v169, v172
	v_rcp_f32_e32 v172, v170
	v_cvt_f32_i32_e32 v168, v168
	v_cmp_neq_f32_e64 s[10:11], s58, v0
	v_mul_f32_e32 v175, v174, v172
	v_mul_f32_e32 v176, v170, v175
	v_fma_f32 v177, v175, v170, -v176
	v_fmac_f32_e32 v177, v175, v169
	v_add_f32_e32 v194, v176, v177
	v_sub_f32_e32 v195, v174, v194
	v_sub_f32_e32 v174, v174, v195
	v_sub_f32_e32 v176, v194, v176
	v_sub_f32_e32 v174, v174, v194
	v_add_f32_e32 v171, v171, v174
	v_sub_f32_e32 v174, v176, v177
	v_add_f32_e32 v171, v174, v171
	v_add_f32_e32 v174, v195, v171
	v_mul_f32_e32 v176, v172, v174
	v_mul_f32_e32 v177, v170, v176
	v_fma_f32 v170, v176, v170, -v177
	v_fmac_f32_e32 v170, v176, v169
	v_sub_f32_e32 v169, v195, v174
	v_add_f32_e32 v169, v171, v169
	v_add_f32_e32 v171, v177, v170
	v_sub_f32_e32 v194, v174, v171
	v_sub_f32_e32 v174, v174, v194
	v_sub_f32_e32 v177, v171, v177
	v_sub_f32_e32 v171, v174, v171
	v_add_f32_e32 v169, v169, v171
	v_sub_f32_e32 v170, v177, v170
	v_add_f32_e32 v169, v170, v169
	v_add_f32_e32 v170, v175, v176
	v_add_f32_e32 v169, v194, v169
	v_sub_f32_e32 v171, v170, v175
	v_mul_f32_e32 v169, v172, v169
	v_sub_f32_e32 v171, v176, v171
	v_add_f32_e32 v169, v171, v169
	v_mul_f32_e32 v175, 0x3f317218, v168
	v_add_f32_e32 v171, v170, v169
	v_fma_f32 v176, v168, s60, -v175
	v_mul_f32_e32 v172, v171, v171
	v_fmac_f32_e32 v176, 0xb102e308, v168
	v_sub_f32_e32 v168, v171, v170
	v_fmamk_f32 v174, v172, 0x3e9b6dac, v196
	v_sub_f32_e32 v168, v169, v168
	v_add_f32_e32 v169, v175, v176
	v_fmaak_f32 v174, v172, v174, 0x3f2aaada
	v_sub_f32_e32 v170, v169, v175
	v_ldexp_f32 v175, v171, 1
	v_mul_f32_e32 v171, v171, v172
	v_mul_f32_e32 v171, v171, v174
	v_add_f32_e32 v172, v175, v171
	v_sub_f32_e32 v174, v172, v175
	v_ldexp_f32 v168, v168, 1
	v_sub_f32_e32 v171, v171, v174
	v_add_f32_e32 v168, v168, v171
	v_add_f32_e32 v171, v172, v168
	v_sub_f32_e32 v172, v171, v172
	v_sub_f32_e32 v168, v168, v172
	v_add_f32_e32 v172, v169, v171
	v_sub_f32_e32 v174, v172, v169
	v_sub_f32_e32 v175, v172, v174
	v_sub_f32_e32 v170, v176, v170
	v_sub_f32_e32 v169, v169, v175
	v_sub_f32_e32 v171, v171, v174
	v_add_f32_e32 v169, v171, v169
	v_add_f32_e32 v171, v170, v168
	v_sub_f32_e32 v174, v171, v170
	v_sub_f32_e32 v175, v171, v174
	v_sub_f32_e32 v170, v170, v175
	v_sub_f32_e32 v168, v168, v174
	v_add_f32_e32 v169, v171, v169
	v_add_f32_e32 v168, v168, v170
	v_add_f32_e32 v170, v172, v169
	v_sub_f32_e32 v171, v170, v172
	v_sub_f32_e32 v169, v169, v171
	v_add_f32_e32 v168, v168, v169
	v_add_f32_e32 v168, v170, v168
	v_cndmask_b32_e64 v168, v197, v168, s[10:11]
	v_cmp_lt_f32_e64 s[10:11], |v0|, s61
	s_nop 1
	v_cndmask_b32_e64 v0, v168, v0, s[10:11]
	v_sub_f32_e32 v0, v165, v0
	v_lshl_add_u64 v[168:169], v[166:167], 0, s[2:3]
	global_store_dword v[168:169], v0, off
	global_load_dword v0, v1, s[18:19] offset:28
	s_or_b32 s2, s38, 7
	s_ashr_i32 s3, s2, 31
	s_lshl_b64 s[2:3], s[2:3], 16
	s_waitcnt vmcnt(0)
;   DI void operator()(int tok0, int feat0, f32x16 (&acc)[2][2], int r, int hh) const {
;     ...
;           for (int i = 0; i < 16; ++i) {
;             const float xv = acc[0][mt][i] + bf[i];
;             const float ls = fminf(xv, 0.f) - log1pf(expf(-fabsf(xv)));
;             lf[((size_t)(b * 16 + i)) * SEQ + s] = ls;
;           }
	v_add_f32_e32 v0, v121, v0
	v_mul_f32_e64 v168, |v0|, s54
	v_fma_f32 v169, |v0|, s54, -v168
	v_rndne_f32_e32 v170, v168
	v_fma_f32 v169, |v0|, s55, v169
	v_sub_f32_e32 v168, v168, v170
	v_add_f32_e32 v168, v168, v169
	v_exp_f32_e32 v168, v168
	v_cvt_i32_f32_e32 v169, v170
	v_cmp_ngt_f32_e64 s[10:11], |v0|, s56
	v_min_f32_e32 v165, 0, v0
	v_ldexp_f32 v168, v168, v169
	v_cndmask_b32_e64 v168, 0, v168, s[10:11]
	v_cmp_nlt_f32_e64 s[10:11], |v0|, s57
	s_nop 1
	v_cndmask_b32_e64 v0, v197, v168, s[10:11]
	v_add_f32_e32 v170, 1.0, v0
	v_add_f32_e32 v168, -1.0, v170
	v_sub_f32_e32 v169, v168, v170
	v_add_f32_e32 v169, 1.0, v169
	v_sub_f32_e32 v168, v0, v168
	v_add_f32_e32 v171, v168, v169
	v_frexp_mant_f32_e32 v168, v170
	v_cmp_gt_f32_e64 s[10:11], s59, v168
	v_cvt_f64_f32_e32 v[168:169], v170
	v_frexp_exp_i32_f64_e32 v168, v[168:169]
	v_subbrev_co_u32_e64 v168, s[10:11], 0, v168, s[10:11]
	v_sub_u32_e32 v169, 0, v168
	v_ldexp_f32 v170, v170, v169
	v_ldexp_f32 v169, v171, v169
	v_add_f32_e32 v171, -1.0, v170
	v_add_f32_e32 v172, 1.0, v171
	v_sub_f32_e32 v172, v170, v172
	v_add_f32_e32 v172, v169, v172
	v_add_f32_e32 v174, v171, v172
	v_sub_f32_e32 v171, v171, v174
	v_add_f32_e32 v171, v172, v171
	v_add_f32_e32 v172, 1.0, v170
	v_add_f32_e32 v175, -1.0, v172
	v_sub_f32_e32 v170, v170, v175
	v_add_f32_e32 v169, v169, v170
	v_add_f32_e32 v170, v172, v169
	v_sub_f32_e32 v172, v172, v170
	v_add_f32_e32 v169, v169, v172
	v_rcp_f32_e32 v172, v170
	v_cvt_f32_i32_e32 v168, v168
	v_cmp_neq_f32_e64 s[10:11], s58, v0
	v_mul_f32_e32 v175, v174, v172
	v_mul_f32_e32 v176, v170, v175
	v_fma_f32 v177, v175, v170, -v176
	v_fmac_f32_e32 v177, v175, v169
	v_add_f32_e32 v194, v176, v177
	v_sub_f32_e32 v195, v174, v194
	v_sub_f32_e32 v174, v174, v195
	v_sub_f32_e32 v176, v194, v176
	v_sub_f32_e32 v174, v174, v194
	v_add_f32_e32 v171, v171, v174
	v_sub_f32_e32 v174, v176, v177
	v_add_f32_e32 v171, v174, v171
	v_add_f32_e32 v174, v195, v171
	v_mul_f32_e32 v176, v172, v174
	v_mul_f32_e32 v177, v170, v176
	v_fma_f32 v170, v176, v170, -v177
	v_fmac_f32_e32 v170, v176, v169
	v_sub_f32_e32 v169, v195, v174
	v_add_f32_e32 v169, v171, v169
	v_add_f32_e32 v171, v177, v170
	v_sub_f32_e32 v194, v174, v171
	v_sub_f32_e32 v174, v174, v194
	v_sub_f32_e32 v177, v171, v177
	v_sub_f32_e32 v171, v174, v171
	v_add_f32_e32 v169, v169, v171
	v_sub_f32_e32 v170, v177, v170
	v_add_f32_e32 v169, v170, v169
	v_add_f32_e32 v170, v175, v176
	v_add_f32_e32 v169, v194, v169
	v_sub_f32_e32 v171, v170, v175
	v_mul_f32_e32 v169, v172, v169
	v_sub_f32_e32 v171, v176, v171
	v_add_f32_e32 v169, v171, v169
	v_mul_f32_e32 v175, 0x3f317218, v168
	v_add_f32_e32 v171, v170, v169
	v_fma_f32 v176, v168, s60, -v175
	v_mul_f32_e32 v172, v171, v171
	v_fmac_f32_e32 v176, 0xb102e308, v168
	v_sub_f32_e32 v168, v171, v170
	v_fmamk_f32 v174, v172, 0x3e9b6dac, v196
	v_sub_f32_e32 v168, v169, v168
	v_add_f32_e32 v169, v175, v176
	v_fmaak_f32 v174, v172, v174, 0x3f2aaada
	v_sub_f32_e32 v170, v169, v175
	v_ldexp_f32 v175, v171, 1
	v_mul_f32_e32 v171, v171, v172
	v_mul_f32_e32 v171, v171, v174
	v_add_f32_e32 v172, v175, v171
	v_sub_f32_e32 v174, v172, v175
	v_ldexp_f32 v168, v168, 1
	v_sub_f32_e32 v171, v171, v174
	v_add_f32_e32 v168, v168, v171
	v_add_f32_e32 v171, v172, v168
	v_sub_f32_e32 v172, v171, v172
	v_sub_f32_e32 v168, v168, v172
	v_add_f32_e32 v172, v169, v171
	v_sub_f32_e32 v174, v172, v169
	v_sub_f32_e32 v175, v172, v174
	v_sub_f32_e32 v170, v176, v170
	v_sub_f32_e32 v169, v169, v175
	v_sub_f32_e32 v171, v171, v174
	v_add_f32_e32 v169, v171, v169
	v_add_f32_e32 v171, v170, v168
	v_sub_f32_e32 v174, v171, v170
	v_sub_f32_e32 v175, v171, v174
	v_sub_f32_e32 v170, v170, v175
	v_sub_f32_e32 v168, v168, v174
	v_add_f32_e32 v169, v171, v169
	v_add_f32_e32 v168, v168, v170
	v_add_f32_e32 v170, v172, v169
	v_sub_f32_e32 v171, v170, v172
	v_sub_f32_e32 v169, v169, v171
	v_add_f32_e32 v168, v168, v169
	v_add_f32_e32 v168, v170, v168
	v_cndmask_b32_e64 v168, v197, v168, s[10:11]
	v_cmp_lt_f32_e64 s[10:11], |v0|, s61
	s_nop 1
	v_cndmask_b32_e64 v0, v168, v0, s[10:11]
	v_sub_f32_e32 v0, v165, v0
	v_lshl_add_u64 v[168:169], v[166:167], 0, s[2:3]
	global_store_dword v[168:169], v0, off
	global_load_dword v0, v1, s[18:19] offset:32
	s_or_b32 s2, s38, 8
	s_ashr_i32 s3, s2, 31
	s_lshl_b64 s[2:3], s[2:3], 16
	s_waitcnt vmcnt(0)
;   DI void operator()(int tok0, int feat0, f32x16 (&acc)[2][2], int r, int hh) const {
;     ...
;           for (int i = 0; i < 16; ++i) {
;             const float xv = acc[0][mt][i] + bf[i];
;             const float ls = fminf(xv, 0.f) - log1pf(expf(-fabsf(xv)));
;             lf[((size_t)(b * 16 + i)) * SEQ + s] = ls;
;           }
	v_add_f32_e32 v0, v122, v0
	v_mul_f32_e64 v168, |v0|, s54
	v_fma_f32 v169, |v0|, s54, -v168
	v_rndne_f32_e32 v170, v168
	v_fma_f32 v169, |v0|, s55, v169
	v_sub_f32_e32 v168, v168, v170
	v_add_f32_e32 v168, v168, v169
	v_exp_f32_e32 v168, v168
	v_cvt_i32_f32_e32 v169, v170
	v_cmp_ngt_f32_e64 s[10:11], |v0|, s56
	v_min_f32_e32 v165, 0, v0
	v_ldexp_f32 v168, v168, v169
	v_cndmask_b32_e64 v168, 0, v168, s[10:11]
	v_cmp_nlt_f32_e64 s[10:11], |v0|, s57
	s_nop 1
	v_cndmask_b32_e64 v0, v197, v168, s[10:11]
	v_add_f32_e32 v170, 1.0, v0
	v_add_f32_e32 v168, -1.0, v170
	v_sub_f32_e32 v169, v168, v170
	v_add_f32_e32 v169, 1.0, v169
	v_sub_f32_e32 v168, v0, v168
	v_add_f32_e32 v171, v168, v169
	v_frexp_mant_f32_e32 v168, v170
	v_cmp_gt_f32_e64 s[10:11], s59, v168
	v_cvt_f64_f32_e32 v[168:169], v170
	v_frexp_exp_i32_f64_e32 v168, v[168:169]
	v_subbrev_co_u32_e64 v168, s[10:11], 0, v168, s[10:11]
	v_sub_u32_e32 v169, 0, v168
	v_ldexp_f32 v170, v170, v169
	v_ldexp_f32 v169, v171, v169
	v_add_f32_e32 v171, -1.0, v170
	v_add_f32_e32 v172, 1.0, v171
	v_sub_f32_e32 v172, v170, v172
	v_add_f32_e32 v172, v169, v172
	v_add_f32_e32 v174, v171, v172
	v_sub_f32_e32 v171, v171, v174
	v_add_f32_e32 v171, v172, v171
	v_add_f32_e32 v172, 1.0, v170
	v_add_f32_e32 v175, -1.0, v172
	v_sub_f32_e32 v170, v170, v175
	v_add_f32_e32 v169, v169, v170
	v_add_f32_e32 v170, v172, v169
	v_sub_f32_e32 v172, v172, v170
	v_add_f32_e32 v169, v169, v172
	v_rcp_f32_e32 v172, v170
	v_cvt_f32_i32_e32 v168, v168
	v_cmp_neq_f32_e64 s[10:11], s58, v0
	v_mul_f32_e32 v175, v174, v172
	v_mul_f32_e32 v176, v170, v175
	v_fma_f32 v177, v175, v170, -v176
	v_fmac_f32_e32 v177, v175, v169
	v_add_f32_e32 v194, v176, v177
	v_sub_f32_e32 v195, v174, v194
	v_sub_f32_e32 v174, v174, v195
	v_sub_f32_e32 v176, v194, v176
	v_sub_f32_e32 v174, v174, v194
	v_add_f32_e32 v171, v171, v174
	v_sub_f32_e32 v174, v176, v177
	v_add_f32_e32 v171, v174, v171
	v_add_f32_e32 v174, v195, v171
	v_mul_f32_e32 v176, v172, v174
	v_mul_f32_e32 v177, v170, v176
	v_fma_f32 v170, v176, v170, -v177
	v_fmac_f32_e32 v170, v176, v169
	v_sub_f32_e32 v169, v195, v174
	v_add_f32_e32 v169, v171, v169
	v_add_f32_e32 v171, v177, v170
	v_sub_f32_e32 v194, v174, v171
	v_sub_f32_e32 v174, v174, v194
	v_sub_f32_e32 v177, v171, v177
	v_sub_f32_e32 v171, v174, v171
	v_add_f32_e32 v169, v169, v171
	v_sub_f32_e32 v170, v177, v170
	v_add_f32_e32 v169, v170, v169
	v_add_f32_e32 v170, v175, v176
	v_add_f32_e32 v169, v194, v169
	v_sub_f32_e32 v171, v170, v175
	v_mul_f32_e32 v169, v172, v169
	v_sub_f32_e32 v171, v176, v171
	v_add_f32_e32 v169, v171, v169
	v_mul_f32_e32 v175, 0x3f317218, v168
	v_add_f32_e32 v171, v170, v169
	v_fma_f32 v176, v168, s60, -v175
	v_mul_f32_e32 v172, v171, v171
	v_fmac_f32_e32 v176, 0xb102e308, v168
	v_sub_f32_e32 v168, v171, v170
	v_fmamk_f32 v174, v172, 0x3e9b6dac, v196
	v_sub_f32_e32 v168, v169, v168
	v_add_f32_e32 v169, v175, v176
	v_fmaak_f32 v174, v172, v174, 0x3f2aaada
	v_sub_f32_e32 v170, v169, v175
	v_ldexp_f32 v175, v171, 1
	v_mul_f32_e32 v171, v171, v172
	v_mul_f32_e32 v171, v171, v174
	v_add_f32_e32 v172, v175, v171
	v_sub_f32_e32 v174, v172, v175
	v_ldexp_f32 v168, v168, 1
	v_sub_f32_e32 v171, v171, v174
	v_add_f32_e32 v168, v168, v171
	v_add_f32_e32 v171, v172, v168
	v_sub_f32_e32 v172, v171, v172
	v_sub_f32_e32 v168, v168, v172
	v_add_f32_e32 v172, v169, v171
	v_sub_f32_e32 v174, v172, v169
	v_sub_f32_e32 v175, v172, v174
	v_sub_f32_e32 v170, v176, v170
	v_sub_f32_e32 v169, v169, v175
	v_sub_f32_e32 v171, v171, v174
	v_add_f32_e32 v169, v171, v169
	v_add_f32_e32 v171, v170, v168
	v_sub_f32_e32 v174, v171, v170
	v_sub_f32_e32 v175, v171, v174
	v_sub_f32_e32 v170, v170, v175
	v_sub_f32_e32 v168, v168, v174
	v_add_f32_e32 v169, v171, v169
	v_add_f32_e32 v168, v168, v170
	v_add_f32_e32 v170, v172, v169
	v_sub_f32_e32 v171, v170, v172
	v_sub_f32_e32 v169, v169, v171
	v_add_f32_e32 v168, v168, v169
	v_add_f32_e32 v168, v170, v168
	v_cndmask_b32_e64 v168, v197, v168, s[10:11]
	v_cmp_lt_f32_e64 s[10:11], |v0|, s61
	s_nop 1
	v_cndmask_b32_e64 v0, v168, v0, s[10:11]
	v_sub_f32_e32 v0, v165, v0
	v_lshl_add_u64 v[168:169], v[166:167], 0, s[2:3]
	global_store_dword v[168:169], v0, off
	global_load_dword v0, v1, s[18:19] offset:36
	s_or_b32 s2, s38, 9
	s_ashr_i32 s3, s2, 31
	s_lshl_b64 s[2:3], s[2:3], 16
	s_waitcnt vmcnt(0)
;   DI void operator()(int tok0, int feat0, f32x16 (&acc)[2][2], int r, int hh) const {
;     ...
;           for (int i = 0; i < 16; ++i) {
;             const float xv = acc[0][mt][i] + bf[i];
;             const float ls = fminf(xv, 0.f) - log1pf(expf(-fabsf(xv)));
;             lf[((size_t)(b * 16 + i)) * SEQ + s] = ls;
;           }
	v_add_f32_e32 v0, v123, v0
	v_mul_f32_e64 v168, |v0|, s54
	v_fma_f32 v169, |v0|, s54, -v168
	v_rndne_f32_e32 v170, v168
	v_fma_f32 v169, |v0|, s55, v169
	v_sub_f32_e32 v168, v168, v170
	v_add_f32_e32 v168, v168, v169
	v_exp_f32_e32 v168, v168
	v_cvt_i32_f32_e32 v169, v170
	v_cmp_ngt_f32_e64 s[10:11], |v0|, s56
	v_min_f32_e32 v165, 0, v0
	v_ldexp_f32 v168, v168, v169
	v_cndmask_b32_e64 v168, 0, v168, s[10:11]
	v_cmp_nlt_f32_e64 s[10:11], |v0|, s57
	s_nop 1
	v_cndmask_b32_e64 v0, v197, v168, s[10:11]
	v_add_f32_e32 v170, 1.0, v0
	v_add_f32_e32 v168, -1.0, v170
	v_sub_f32_e32 v169, v168, v170
	v_add_f32_e32 v169, 1.0, v169
	v_sub_f32_e32 v168, v0, v168
	v_add_f32_e32 v171, v168, v169
	v_frexp_mant_f32_e32 v168, v170
	v_cmp_gt_f32_e64 s[10:11], s59, v168
	v_cvt_f64_f32_e32 v[168:169], v170
	v_frexp_exp_i32_f64_e32 v168, v[168:169]
	v_subbrev_co_u32_e64 v168, s[10:11], 0, v168, s[10:11]
	v_sub_u32_e32 v169, 0, v168
	v_ldexp_f32 v170, v170, v169
	v_ldexp_f32 v169, v171, v169
	v_add_f32_e32 v171, -1.0, v170
	v_add_f32_e32 v172, 1.0, v171
	v_sub_f32_e32 v172, v170, v172
	v_add_f32_e32 v172, v169, v172
	v_add_f32_e32 v174, v171, v172
	v_sub_f32_e32 v171, v171, v174
	v_add_f32_e32 v171, v172, v171
	v_add_f32_e32 v172, 1.0, v170
	v_add_f32_e32 v175, -1.0, v172
	v_sub_f32_e32 v170, v170, v175
	v_add_f32_e32 v169, v169, v170
	v_add_f32_e32 v170, v172, v169
	v_sub_f32_e32 v172, v172, v170
	v_add_f32_e32 v169, v169, v172
	v_rcp_f32_e32 v172, v170
	v_cvt_f32_i32_e32 v168, v168
	v_cmp_neq_f32_e64 s[10:11], s58, v0
	v_mul_f32_e32 v175, v174, v172
	v_mul_f32_e32 v176, v170, v175
	v_fma_f32 v177, v175, v170, -v176
	v_fmac_f32_e32 v177, v175, v169
	v_add_f32_e32 v194, v176, v177
	v_sub_f32_e32 v195, v174, v194
	v_sub_f32_e32 v174, v174, v195
	v_sub_f32_e32 v176, v194, v176
	v_sub_f32_e32 v174, v174, v194
	v_add_f32_e32 v171, v171, v174
	v_sub_f32_e32 v174, v176, v177
	v_add_f32_e32 v171, v174, v171
	v_add_f32_e32 v174, v195, v171
	v_mul_f32_e32 v176, v172, v174
	v_mul_f32_e32 v177, v170, v176
	v_fma_f32 v170, v176, v170, -v177
	v_fmac_f32_e32 v170, v176, v169
	v_sub_f32_e32 v169, v195, v174
	v_add_f32_e32 v169, v171, v169
	v_add_f32_e32 v171, v177, v170
	v_sub_f32_e32 v194, v174, v171
	v_sub_f32_e32 v174, v174, v194
	v_sub_f32_e32 v177, v171, v177
	v_sub_f32_e32 v171, v174, v171
	v_add_f32_e32 v169, v169, v171
	v_sub_f32_e32 v170, v177, v170
	v_add_f32_e32 v169, v170, v169
	v_add_f32_e32 v170, v175, v176
	v_add_f32_e32 v169, v194, v169
	v_sub_f32_e32 v171, v170, v175
	v_mul_f32_e32 v169, v172, v169
	v_sub_f32_e32 v171, v176, v171
	v_add_f32_e32 v169, v171, v169
	v_mul_f32_e32 v175, 0x3f317218, v168
	v_add_f32_e32 v171, v170, v169
	v_fma_f32 v176, v168, s60, -v175
	v_mul_f32_e32 v172, v171, v171
	v_fmac_f32_e32 v176, 0xb102e308, v168
	v_sub_f32_e32 v168, v171, v170
	v_fmamk_f32 v174, v172, 0x3e9b6dac, v196
	v_sub_f32_e32 v168, v169, v168
	v_add_f32_e32 v169, v175, v176
	v_fmaak_f32 v174, v172, v174, 0x3f2aaada
	v_sub_f32_e32 v170, v169, v175
	v_ldexp_f32 v175, v171, 1
	v_mul_f32_e32 v171, v171, v172
	v_mul_f32_e32 v171, v171, v174
	v_add_f32_e32 v172, v175, v171
	v_sub_f32_e32 v174, v172, v175
	v_ldexp_f32 v168, v168, 1
	v_sub_f32_e32 v171, v171, v174
	v_add_f32_e32 v168, v168, v171
	v_add_f32_e32 v171, v172, v168
	v_sub_f32_e32 v172, v171, v172
	v_sub_f32_e32 v168, v168, v172
	v_add_f32_e32 v172, v169, v171
	v_sub_f32_e32 v174, v172, v169
	v_sub_f32_e32 v175, v172, v174
	v_sub_f32_e32 v170, v176, v170
	v_sub_f32_e32 v169, v169, v175
	v_sub_f32_e32 v171, v171, v174
	v_add_f32_e32 v169, v171, v169
	v_add_f32_e32 v171, v170, v168
	v_sub_f32_e32 v174, v171, v170
	v_sub_f32_e32 v175, v171, v174
	v_sub_f32_e32 v170, v170, v175
	v_sub_f32_e32 v168, v168, v174
	v_add_f32_e32 v169, v171, v169
	v_add_f32_e32 v168, v168, v170
	v_add_f32_e32 v170, v172, v169
	v_sub_f32_e32 v171, v170, v172
	v_sub_f32_e32 v169, v169, v171
	v_add_f32_e32 v168, v168, v169
	v_add_f32_e32 v168, v170, v168
	v_cndmask_b32_e64 v168, v197, v168, s[10:11]
	v_cmp_lt_f32_e64 s[10:11], |v0|, s61
	s_nop 1
	v_cndmask_b32_e64 v0, v168, v0, s[10:11]
	v_sub_f32_e32 v0, v165, v0
	v_lshl_add_u64 v[168:169], v[166:167], 0, s[2:3]
	global_store_dword v[168:169], v0, off
	global_load_dword v0, v1, s[18:19] offset:40
	s_or_b32 s2, s38, 10
	s_ashr_i32 s3, s2, 31
	s_lshl_b64 s[2:3], s[2:3], 16
	s_waitcnt vmcnt(0)
;   DI void operator()(int tok0, int feat0, f32x16 (&acc)[2][2], int r, int hh) const {
;     ...
;           for (int i = 0; i < 16; ++i) {
;             const float xv = acc[0][mt][i] + bf[i];
;             const float ls = fminf(xv, 0.f) - log1pf(expf(-fabsf(xv)));
;             lf[((size_t)(b * 16 + i)) * SEQ + s] = ls;
;           }
	v_add_f32_e32 v0, v124, v0
	v_mul_f32_e64 v168, |v0|, s54
	v_fma_f32 v169, |v0|, s54, -v168
	v_rndne_f32_e32 v170, v168
	v_fma_f32 v169, |v0|, s55, v169
	v_sub_f32_e32 v168, v168, v170
	v_add_f32_e32 v168, v168, v169
	v_exp_f32_e32 v168, v168
	v_cvt_i32_f32_e32 v169, v170
	v_cmp_ngt_f32_e64 s[10:11], |v0|, s56
	v_min_f32_e32 v165, 0, v0
	v_ldexp_f32 v168, v168, v169
	v_cndmask_b32_e64 v168, 0, v168, s[10:11]
	v_cmp_nlt_f32_e64 s[10:11], |v0|, s57
	s_nop 1
	v_cndmask_b32_e64 v0, v197, v168, s[10:11]
	v_add_f32_e32 v170, 1.0, v0
	v_add_f32_e32 v168, -1.0, v170
	v_sub_f32_e32 v169, v168, v170
	v_add_f32_e32 v169, 1.0, v169
	v_sub_f32_e32 v168, v0, v168
	v_add_f32_e32 v171, v168, v169
	v_frexp_mant_f32_e32 v168, v170
	v_cmp_gt_f32_e64 s[10:11], s59, v168
	v_cvt_f64_f32_e32 v[168:169], v170
	v_frexp_exp_i32_f64_e32 v168, v[168:169]
	v_subbrev_co_u32_e64 v168, s[10:11], 0, v168, s[10:11]
	v_sub_u32_e32 v169, 0, v168
	v_ldexp_f32 v170, v170, v169
	v_ldexp_f32 v169, v171, v169
	v_add_f32_e32 v171, -1.0, v170
	v_add_f32_e32 v172, 1.0, v171
	v_sub_f32_e32 v172, v170, v172
	v_add_f32_e32 v172, v169, v172
	v_add_f32_e32 v174, v171, v172
	v_sub_f32_e32 v171, v171, v174
	v_add_f32_e32 v171, v172, v171
	v_add_f32_e32 v172, 1.0, v170
	v_add_f32_e32 v175, -1.0, v172
	v_sub_f32_e32 v170, v170, v175
	v_add_f32_e32 v169, v169, v170
	v_add_f32_e32 v170, v172, v169
	v_sub_f32_e32 v172, v172, v170
	v_add_f32_e32 v169, v169, v172
	v_rcp_f32_e32 v172, v170
	v_cvt_f32_i32_e32 v168, v168
	v_cmp_neq_f32_e64 s[10:11], s58, v0
	v_mul_f32_e32 v175, v174, v172
	v_mul_f32_e32 v176, v170, v175
	v_fma_f32 v177, v175, v170, -v176
	v_fmac_f32_e32 v177, v175, v169
	v_add_f32_e32 v194, v176, v177
	v_sub_f32_e32 v195, v174, v194
	v_sub_f32_e32 v174, v174, v195
	v_sub_f32_e32 v176, v194, v176
	v_sub_f32_e32 v174, v174, v194
	v_add_f32_e32 v171, v171, v174
	v_sub_f32_e32 v174, v176, v177
	v_add_f32_e32 v171, v174, v171
	v_add_f32_e32 v174, v195, v171
	v_mul_f32_e32 v176, v172, v174
	v_mul_f32_e32 v177, v170, v176
	v_fma_f32 v170, v176, v170, -v177
	v_fmac_f32_e32 v170, v176, v169
	v_sub_f32_e32 v169, v195, v174
	v_add_f32_e32 v169, v171, v169
	v_add_f32_e32 v171, v177, v170
	v_sub_f32_e32 v194, v174, v171
	v_sub_f32_e32 v174, v174, v194
	v_sub_f32_e32 v177, v171, v177
	v_sub_f32_e32 v171, v174, v171
	v_add_f32_e32 v169, v169, v171
	v_sub_f32_e32 v170, v177, v170
	v_add_f32_e32 v169, v170, v169
	v_add_f32_e32 v170, v175, v176
	v_add_f32_e32 v169, v194, v169
	v_sub_f32_e32 v171, v170, v175
	v_mul_f32_e32 v169, v172, v169
	v_sub_f32_e32 v171, v176, v171
	v_add_f32_e32 v169, v171, v169
	v_mul_f32_e32 v175, 0x3f317218, v168
	v_add_f32_e32 v171, v170, v169
	v_fma_f32 v176, v168, s60, -v175
	v_mul_f32_e32 v172, v171, v171
	v_fmac_f32_e32 v176, 0xb102e308, v168
	v_sub_f32_e32 v168, v171, v170
	v_fmamk_f32 v174, v172, 0x3e9b6dac, v196
	v_sub_f32_e32 v168, v169, v168
	v_add_f32_e32 v169, v175, v176
	v_fmaak_f32 v174, v172, v174, 0x3f2aaada
	v_sub_f32_e32 v170, v169, v175
	v_ldexp_f32 v175, v171, 1
	v_mul_f32_e32 v171, v171, v172
	v_mul_f32_e32 v171, v171, v174
	v_add_f32_e32 v172, v175, v171
	v_sub_f32_e32 v174, v172, v175
	v_ldexp_f32 v168, v168, 1
	v_sub_f32_e32 v171, v171, v174
	v_add_f32_e32 v168, v168, v171
	v_add_f32_e32 v171, v172, v168
	v_sub_f32_e32 v172, v171, v172
	v_sub_f32_e32 v168, v168, v172
	v_add_f32_e32 v172, v169, v171
	v_sub_f32_e32 v174, v172, v169
	v_sub_f32_e32 v175, v172, v174
	v_sub_f32_e32 v170, v176, v170
	v_sub_f32_e32 v169, v169, v175
	v_sub_f32_e32 v171, v171, v174
	v_add_f32_e32 v169, v171, v169
	v_add_f32_e32 v171, v170, v168
	v_sub_f32_e32 v174, v171, v170
	v_sub_f32_e32 v175, v171, v174
	v_sub_f32_e32 v170, v170, v175
	v_sub_f32_e32 v168, v168, v174
	v_add_f32_e32 v169, v171, v169
	v_add_f32_e32 v168, v168, v170
	v_add_f32_e32 v170, v172, v169
	v_sub_f32_e32 v171, v170, v172
	v_sub_f32_e32 v169, v169, v171
	v_add_f32_e32 v168, v168, v169
	v_add_f32_e32 v168, v170, v168
	v_cndmask_b32_e64 v168, v197, v168, s[10:11]
	v_cmp_lt_f32_e64 s[10:11], |v0|, s61
	s_nop 1
	v_cndmask_b32_e64 v0, v168, v0, s[10:11]
	v_sub_f32_e32 v0, v165, v0
	v_lshl_add_u64 v[168:169], v[166:167], 0, s[2:3]
	global_store_dword v[168:169], v0, off
	global_load_dword v0, v1, s[18:19] offset:44
	s_or_b32 s2, s38, 11
	s_ashr_i32 s3, s2, 31
	s_lshl_b64 s[2:3], s[2:3], 16
	s_waitcnt vmcnt(0)
;   DI void operator()(int tok0, int feat0, f32x16 (&acc)[2][2], int r, int hh) const {
;     ...
;           for (int i = 0; i < 16; ++i) {
;             const float xv = acc[0][mt][i] + bf[i];
;             const float ls = fminf(xv, 0.f) - log1pf(expf(-fabsf(xv)));
;             lf[((size_t)(b * 16 + i)) * SEQ + s] = ls;
;           }
	v_add_f32_e32 v0, v125, v0
	v_mul_f32_e64 v168, |v0|, s54
	v_fma_f32 v169, |v0|, s54, -v168
	v_rndne_f32_e32 v170, v168
	v_fma_f32 v169, |v0|, s55, v169
	v_sub_f32_e32 v168, v168, v170
	v_add_f32_e32 v168, v168, v169
	v_exp_f32_e32 v168, v168
	v_cvt_i32_f32_e32 v169, v170
	v_cmp_ngt_f32_e64 s[10:11], |v0|, s56
	v_min_f32_e32 v165, 0, v0
	v_ldexp_f32 v168, v168, v169
	v_cndmask_b32_e64 v168, 0, v168, s[10:11]
	v_cmp_nlt_f32_e64 s[10:11], |v0|, s57
	s_nop 1
	v_cndmask_b32_e64 v0, v197, v168, s[10:11]
	v_add_f32_e32 v170, 1.0, v0
	v_add_f32_e32 v168, -1.0, v170
	v_sub_f32_e32 v169, v168, v170
	v_add_f32_e32 v169, 1.0, v169
	v_sub_f32_e32 v168, v0, v168
	v_add_f32_e32 v171, v168, v169
	v_frexp_mant_f32_e32 v168, v170
	v_cmp_gt_f32_e64 s[10:11], s59, v168
	v_cvt_f64_f32_e32 v[168:169], v170
	v_frexp_exp_i32_f64_e32 v168, v[168:169]
	v_subbrev_co_u32_e64 v168, s[10:11], 0, v168, s[10:11]
	v_sub_u32_e32 v169, 0, v168
	v_ldexp_f32 v170, v170, v169
	v_ldexp_f32 v169, v171, v169
	v_add_f32_e32 v171, -1.0, v170
	v_add_f32_e32 v172, 1.0, v171
	v_sub_f32_e32 v172, v170, v172
	v_add_f32_e32 v172, v169, v172
	v_add_f32_e32 v174, v171, v172
	v_sub_f32_e32 v171, v171, v174
	v_add_f32_e32 v171, v172, v171
	v_add_f32_e32 v172, 1.0, v170
	v_add_f32_e32 v175, -1.0, v172
	v_sub_f32_e32 v170, v170, v175
	v_add_f32_e32 v169, v169, v170
	v_add_f32_e32 v170, v172, v169
	v_sub_f32_e32 v172, v172, v170
	v_add_f32_e32 v169, v169, v172
	v_rcp_f32_e32 v172, v170
	v_cvt_f32_i32_e32 v168, v168
	v_cmp_neq_f32_e64 s[10:11], s58, v0
	v_mul_f32_e32 v175, v174, v172
	v_mul_f32_e32 v176, v170, v175
	v_fma_f32 v177, v175, v170, -v176
	v_fmac_f32_e32 v177, v175, v169
	v_add_f32_e32 v194, v176, v177
	v_sub_f32_e32 v195, v174, v194
	v_sub_f32_e32 v174, v174, v195
	v_sub_f32_e32 v176, v194, v176
	v_sub_f32_e32 v174, v174, v194
	v_add_f32_e32 v171, v171, v174
	v_sub_f32_e32 v174, v176, v177
	v_add_f32_e32 v171, v174, v171
	v_add_f32_e32 v174, v195, v171
	v_mul_f32_e32 v176, v172, v174
	v_mul_f32_e32 v177, v170, v176
	v_fma_f32 v170, v176, v170, -v177
	v_fmac_f32_e32 v170, v176, v169
	v_sub_f32_e32 v169, v195, v174
	v_add_f32_e32 v169, v171, v169
	v_add_f32_e32 v171, v177, v170
	v_sub_f32_e32 v194, v174, v171
	v_sub_f32_e32 v174, v174, v194
	v_sub_f32_e32 v177, v171, v177
	v_sub_f32_e32 v171, v174, v171
	v_add_f32_e32 v169, v169, v171
	v_sub_f32_e32 v170, v177, v170
	v_add_f32_e32 v169, v170, v169
	v_add_f32_e32 v170, v175, v176
	v_add_f32_e32 v169, v194, v169
	v_sub_f32_e32 v171, v170, v175
	v_mul_f32_e32 v169, v172, v169
	v_sub_f32_e32 v171, v176, v171
	v_add_f32_e32 v169, v171, v169
	v_mul_f32_e32 v175, 0x3f317218, v168
	v_add_f32_e32 v171, v170, v169
	v_fma_f32 v176, v168, s60, -v175
	v_mul_f32_e32 v172, v171, v171
	v_fmac_f32_e32 v176, 0xb102e308, v168
	v_sub_f32_e32 v168, v171, v170
	v_fmamk_f32 v174, v172, 0x3e9b6dac, v196
	v_sub_f32_e32 v168, v169, v168
	v_add_f32_e32 v169, v175, v176
	v_fmaak_f32 v174, v172, v174, 0x3f2aaada
	v_sub_f32_e32 v170, v169, v175
	v_ldexp_f32 v175, v171, 1
	v_mul_f32_e32 v171, v171, v172
	v_mul_f32_e32 v171, v171, v174
	v_add_f32_e32 v172, v175, v171
	v_sub_f32_e32 v174, v172, v175
	v_ldexp_f32 v168, v168, 1
	v_sub_f32_e32 v171, v171, v174
	v_add_f32_e32 v168, v168, v171
	v_add_f32_e32 v171, v172, v168
	v_sub_f32_e32 v172, v171, v172
	v_sub_f32_e32 v168, v168, v172
	v_add_f32_e32 v172, v169, v171
	v_sub_f32_e32 v174, v172, v169
	v_sub_f32_e32 v175, v172, v174
	v_sub_f32_e32 v170, v176, v170
	v_sub_f32_e32 v169, v169, v175
	v_sub_f32_e32 v171, v171, v174
	v_add_f32_e32 v169, v171, v169
	v_add_f32_e32 v171, v170, v168
	v_sub_f32_e32 v174, v171, v170
	v_sub_f32_e32 v175, v171, v174
	v_sub_f32_e32 v170, v170, v175
	v_sub_f32_e32 v168, v168, v174
	v_add_f32_e32 v169, v171, v169
	v_add_f32_e32 v168, v168, v170
	v_add_f32_e32 v170, v172, v169
	v_sub_f32_e32 v171, v170, v172
	v_sub_f32_e32 v169, v169, v171
	v_add_f32_e32 v168, v168, v169
	v_add_f32_e32 v168, v170, v168
	v_cndmask_b32_e64 v168, v197, v168, s[10:11]
	v_cmp_lt_f32_e64 s[10:11], |v0|, s61
	s_nop 1
	v_cndmask_b32_e64 v0, v168, v0, s[10:11]
	v_sub_f32_e32 v0, v165, v0
	v_lshl_add_u64 v[168:169], v[166:167], 0, s[2:3]
	global_store_dword v[168:169], v0, off
	global_load_dword v0, v1, s[18:19] offset:48
	s_or_b32 s2, s38, 12
	s_ashr_i32 s3, s2, 31
	s_lshl_b64 s[2:3], s[2:3], 16
	s_waitcnt vmcnt(0)
;   DI void operator()(int tok0, int feat0, f32x16 (&acc)[2][2], int r, int hh) const {
;     ...
;           for (int i = 0; i < 16; ++i) {
;             const float xv = acc[0][mt][i] + bf[i];
;             const float ls = fminf(xv, 0.f) - log1pf(expf(-fabsf(xv)));
;             lf[((size_t)(b * 16 + i)) * SEQ + s] = ls;
;           }
	v_add_f32_e32 v0, v126, v0
	v_mul_f32_e64 v168, |v0|, s54
	v_fma_f32 v169, |v0|, s54, -v168
	v_rndne_f32_e32 v170, v168
	v_fma_f32 v169, |v0|, s55, v169
	v_sub_f32_e32 v168, v168, v170
	v_add_f32_e32 v168, v168, v169
	v_exp_f32_e32 v168, v168
	v_cvt_i32_f32_e32 v169, v170
	v_cmp_ngt_f32_e64 s[10:11], |v0|, s56
	v_min_f32_e32 v165, 0, v0
	v_ldexp_f32 v168, v168, v169
	v_cndmask_b32_e64 v168, 0, v168, s[10:11]
	v_cmp_nlt_f32_e64 s[10:11], |v0|, s57
	s_nop 1
	v_cndmask_b32_e64 v0, v197, v168, s[10:11]
	v_add_f32_e32 v170, 1.0, v0
	v_add_f32_e32 v168, -1.0, v170
	v_sub_f32_e32 v169, v168, v170
	v_add_f32_e32 v169, 1.0, v169
	v_sub_f32_e32 v168, v0, v168
	v_add_f32_e32 v171, v168, v169
	v_frexp_mant_f32_e32 v168, v170
	v_cmp_gt_f32_e64 s[10:11], s59, v168
	v_cvt_f64_f32_e32 v[168:169], v170
	v_frexp_exp_i32_f64_e32 v168, v[168:169]
	v_subbrev_co_u32_e64 v168, s[10:11], 0, v168, s[10:11]
	v_sub_u32_e32 v169, 0, v168
	v_ldexp_f32 v170, v170, v169
	v_ldexp_f32 v169, v171, v169
	v_add_f32_e32 v171, -1.0, v170
	v_add_f32_e32 v172, 1.0, v171
	v_sub_f32_e32 v172, v170, v172
	v_add_f32_e32 v172, v169, v172
	v_add_f32_e32 v174, v171, v172
	v_sub_f32_e32 v171, v171, v174
	v_add_f32_e32 v171, v172, v171
	v_add_f32_e32 v172, 1.0, v170
	v_add_f32_e32 v175, -1.0, v172
	v_sub_f32_e32 v170, v170, v175
	v_add_f32_e32 v169, v169, v170
	v_add_f32_e32 v170, v172, v169
	v_sub_f32_e32 v172, v172, v170
	v_add_f32_e32 v169, v169, v172
	v_rcp_f32_e32 v172, v170
	v_cvt_f32_i32_e32 v168, v168
	v_cmp_neq_f32_e64 s[10:11], s58, v0
	v_mul_f32_e32 v175, v174, v172
	v_mul_f32_e32 v176, v170, v175
	v_fma_f32 v177, v175, v170, -v176
	v_fmac_f32_e32 v177, v175, v169
	v_add_f32_e32 v194, v176, v177
	v_sub_f32_e32 v195, v174, v194
	v_sub_f32_e32 v174, v174, v195
	v_sub_f32_e32 v176, v194, v176
	v_sub_f32_e32 v174, v174, v194
	v_add_f32_e32 v171, v171, v174
	v_sub_f32_e32 v174, v176, v177
	v_add_f32_e32 v171, v174, v171
	v_add_f32_e32 v174, v195, v171
	v_mul_f32_e32 v176, v172, v174
	v_mul_f32_e32 v177, v170, v176
	v_fma_f32 v170, v176, v170, -v177
	v_fmac_f32_e32 v170, v176, v169
	v_sub_f32_e32 v169, v195, v174
	v_add_f32_e32 v169, v171, v169
	v_add_f32_e32 v171, v177, v170
	v_sub_f32_e32 v194, v174, v171
	v_sub_f32_e32 v174, v174, v194
	v_sub_f32_e32 v177, v171, v177
	v_sub_f32_e32 v171, v174, v171
	v_add_f32_e32 v169, v169, v171
	v_sub_f32_e32 v170, v177, v170
	v_add_f32_e32 v169, v170, v169
	v_add_f32_e32 v170, v175, v176
	v_add_f32_e32 v169, v194, v169
	v_sub_f32_e32 v171, v170, v175
	v_mul_f32_e32 v169, v172, v169
	v_sub_f32_e32 v171, v176, v171
	v_add_f32_e32 v169, v171, v169
	v_mul_f32_e32 v175, 0x3f317218, v168
	v_add_f32_e32 v171, v170, v169
	v_fma_f32 v176, v168, s60, -v175
	v_mul_f32_e32 v172, v171, v171
	v_fmac_f32_e32 v176, 0xb102e308, v168
	v_sub_f32_e32 v168, v171, v170
	v_fmamk_f32 v174, v172, 0x3e9b6dac, v196
	v_sub_f32_e32 v168, v169, v168
	v_add_f32_e32 v169, v175, v176
	v_fmaak_f32 v174, v172, v174, 0x3f2aaada
	v_sub_f32_e32 v170, v169, v175
	v_ldexp_f32 v175, v171, 1
	v_mul_f32_e32 v171, v171, v172
	v_mul_f32_e32 v171, v171, v174
	v_add_f32_e32 v172, v175, v171
	v_sub_f32_e32 v174, v172, v175
	v_ldexp_f32 v168, v168, 1
	v_sub_f32_e32 v171, v171, v174
	v_add_f32_e32 v168, v168, v171
	v_add_f32_e32 v171, v172, v168
	v_sub_f32_e32 v172, v171, v172
	v_sub_f32_e32 v168, v168, v172
	v_add_f32_e32 v172, v169, v171
	v_sub_f32_e32 v174, v172, v169
	v_sub_f32_e32 v175, v172, v174
	v_sub_f32_e32 v170, v176, v170
	v_sub_f32_e32 v169, v169, v175
	v_sub_f32_e32 v171, v171, v174
	v_add_f32_e32 v169, v171, v169
	v_add_f32_e32 v171, v170, v168
	v_sub_f32_e32 v174, v171, v170
	v_sub_f32_e32 v175, v171, v174
	v_sub_f32_e32 v170, v170, v175
	v_sub_f32_e32 v168, v168, v174
	v_add_f32_e32 v169, v171, v169
	v_add_f32_e32 v168, v168, v170
	v_add_f32_e32 v170, v172, v169
	v_sub_f32_e32 v171, v170, v172
	v_sub_f32_e32 v169, v169, v171
	v_add_f32_e32 v168, v168, v169
	v_add_f32_e32 v168, v170, v168
	v_cndmask_b32_e64 v168, v197, v168, s[10:11]
	v_cmp_lt_f32_e64 s[10:11], |v0|, s61
	s_nop 1
	v_cndmask_b32_e64 v0, v168, v0, s[10:11]
	v_sub_f32_e32 v0, v165, v0
	v_lshl_add_u64 v[168:169], v[166:167], 0, s[2:3]
	global_store_dword v[168:169], v0, off
	global_load_dword v0, v1, s[18:19] offset:52
	s_or_b32 s2, s38, 13
	s_ashr_i32 s3, s2, 31
	s_lshl_b64 s[2:3], s[2:3], 16
	s_waitcnt vmcnt(0)
;   DI void operator()(int tok0, int feat0, f32x16 (&acc)[2][2], int r, int hh) const {
;     ...
;           for (int i = 0; i < 16; ++i) {
;             const float xv = acc[0][mt][i] + bf[i];
;             const float ls = fminf(xv, 0.f) - log1pf(expf(-fabsf(xv)));
;             lf[((size_t)(b * 16 + i)) * SEQ + s] = ls;
;           }
	v_add_f32_e32 v0, v127, v0
	v_mul_f32_e64 v168, |v0|, s54
	v_fma_f32 v169, |v0|, s54, -v168
	v_rndne_f32_e32 v170, v168
	v_fma_f32 v169, |v0|, s55, v169
	v_sub_f32_e32 v168, v168, v170
	v_add_f32_e32 v168, v168, v169
	v_exp_f32_e32 v168, v168
	v_cvt_i32_f32_e32 v169, v170
	v_cmp_ngt_f32_e64 s[10:11], |v0|, s56
	v_min_f32_e32 v165, 0, v0
	v_ldexp_f32 v168, v168, v169
	v_cndmask_b32_e64 v168, 0, v168, s[10:11]
	v_cmp_nlt_f32_e64 s[10:11], |v0|, s57
	s_nop 1
	v_cndmask_b32_e64 v0, v197, v168, s[10:11]
	v_add_f32_e32 v170, 1.0, v0
	v_add_f32_e32 v168, -1.0, v170
	v_sub_f32_e32 v169, v168, v170
	v_add_f32_e32 v169, 1.0, v169
	v_sub_f32_e32 v168, v0, v168
	v_add_f32_e32 v171, v168, v169
	v_frexp_mant_f32_e32 v168, v170
	v_cmp_gt_f32_e64 s[10:11], s59, v168
	v_cvt_f64_f32_e32 v[168:169], v170
	v_frexp_exp_i32_f64_e32 v168, v[168:169]
	v_subbrev_co_u32_e64 v168, s[10:11], 0, v168, s[10:11]
	v_sub_u32_e32 v169, 0, v168
	v_ldexp_f32 v170, v170, v169
	v_ldexp_f32 v169, v171, v169
	v_add_f32_e32 v171, -1.0, v170
	v_add_f32_e32 v172, 1.0, v171
	v_sub_f32_e32 v172, v170, v172
	v_add_f32_e32 v172, v169, v172
	v_add_f32_e32 v174, v171, v172
	v_sub_f32_e32 v171, v171, v174
	v_add_f32_e32 v171, v172, v171
	v_add_f32_e32 v172, 1.0, v170
	v_add_f32_e32 v175, -1.0, v172
	v_sub_f32_e32 v170, v170, v175
	v_add_f32_e32 v169, v169, v170
	v_add_f32_e32 v170, v172, v169
	v_sub_f32_e32 v172, v172, v170
	v_add_f32_e32 v169, v169, v172
	v_rcp_f32_e32 v172, v170
	v_cvt_f32_i32_e32 v168, v168
	v_cmp_neq_f32_e64 s[10:11], s58, v0
	v_mul_f32_e32 v175, v174, v172
	v_mul_f32_e32 v176, v170, v175
	v_fma_f32 v177, v175, v170, -v176
	v_fmac_f32_e32 v177, v175, v169
	v_add_f32_e32 v194, v176, v177
	v_sub_f32_e32 v195, v174, v194
	v_sub_f32_e32 v174, v174, v195
	v_sub_f32_e32 v176, v194, v176
	v_sub_f32_e32 v174, v174, v194
	v_add_f32_e32 v171, v171, v174
	v_sub_f32_e32 v174, v176, v177
	v_add_f32_e32 v171, v174, v171
	v_add_f32_e32 v174, v195, v171
	v_mul_f32_e32 v176, v172, v174
	v_mul_f32_e32 v177, v170, v176
	v_fma_f32 v170, v176, v170, -v177
	v_fmac_f32_e32 v170, v176, v169
	v_sub_f32_e32 v169, v195, v174
	v_add_f32_e32 v169, v171, v169
	v_add_f32_e32 v171, v177, v170
	v_sub_f32_e32 v194, v174, v171
	v_sub_f32_e32 v174, v174, v194
	v_sub_f32_e32 v177, v171, v177
	v_sub_f32_e32 v171, v174, v171
	v_add_f32_e32 v169, v169, v171
	v_sub_f32_e32 v170, v177, v170
	v_add_f32_e32 v169, v170, v169
	v_add_f32_e32 v170, v175, v176
	v_add_f32_e32 v169, v194, v169
	v_sub_f32_e32 v171, v170, v175
	v_mul_f32_e32 v169, v172, v169
	v_sub_f32_e32 v171, v176, v171
	v_add_f32_e32 v169, v171, v169
	v_mul_f32_e32 v175, 0x3f317218, v168
	v_add_f32_e32 v171, v170, v169
	v_fma_f32 v176, v168, s60, -v175
	v_mul_f32_e32 v172, v171, v171
	v_fmac_f32_e32 v176, 0xb102e308, v168
	v_sub_f32_e32 v168, v171, v170
	v_fmamk_f32 v174, v172, 0x3e9b6dac, v196
	v_sub_f32_e32 v168, v169, v168
	v_add_f32_e32 v169, v175, v176
	v_fmaak_f32 v174, v172, v174, 0x3f2aaada
	v_sub_f32_e32 v170, v169, v175
	v_ldexp_f32 v175, v171, 1
	v_mul_f32_e32 v171, v171, v172
	v_mul_f32_e32 v171, v171, v174
	v_add_f32_e32 v172, v175, v171
	v_sub_f32_e32 v174, v172, v175
	v_ldexp_f32 v168, v168, 1
	v_sub_f32_e32 v171, v171, v174
	v_add_f32_e32 v168, v168, v171
	v_add_f32_e32 v171, v172, v168
	v_sub_f32_e32 v172, v171, v172
	v_sub_f32_e32 v168, v168, v172
	v_add_f32_e32 v172, v169, v171
	v_sub_f32_e32 v174, v172, v169
	v_sub_f32_e32 v175, v172, v174
	v_sub_f32_e32 v170, v176, v170
	v_sub_f32_e32 v169, v169, v175
	v_sub_f32_e32 v171, v171, v174
	v_add_f32_e32 v169, v171, v169
	v_add_f32_e32 v171, v170, v168
	v_sub_f32_e32 v174, v171, v170
	v_sub_f32_e32 v175, v171, v174
	v_sub_f32_e32 v170, v170, v175
	v_sub_f32_e32 v168, v168, v174
	v_add_f32_e32 v169, v171, v169
	v_add_f32_e32 v168, v168, v170
	v_add_f32_e32 v170, v172, v169
	v_sub_f32_e32 v171, v170, v172
	v_sub_f32_e32 v169, v169, v171
	v_add_f32_e32 v168, v168, v169
	v_add_f32_e32 v168, v170, v168
	v_cndmask_b32_e64 v168, v197, v168, s[10:11]
	v_cmp_lt_f32_e64 s[10:11], |v0|, s61
	s_nop 1
	v_cndmask_b32_e64 v0, v168, v0, s[10:11]
	v_sub_f32_e32 v0, v165, v0
	v_lshl_add_u64 v[168:169], v[166:167], 0, s[2:3]
	global_store_dword v[168:169], v0, off
	global_load_dword v0, v1, s[18:19] offset:56
	s_or_b32 s2, s38, 14
	s_ashr_i32 s3, s2, 31
	s_lshl_b64 s[2:3], s[2:3], 16
	s_waitcnt vmcnt(0)
;   DI void operator()(int tok0, int feat0, f32x16 (&acc)[2][2], int r, int hh) const {
;     ...
;           for (int i = 0; i < 16; ++i) {
;             const float xv = acc[0][mt][i] + bf[i];
;             const float ls = fminf(xv, 0.f) - log1pf(expf(-fabsf(xv)));
;             lf[((size_t)(b * 16 + i)) * SEQ + s] = ls;
;           }
	v_add_f32_e32 v0, v128, v0
	v_mul_f32_e64 v168, |v0|, s54
	v_fma_f32 v169, |v0|, s54, -v168
	v_rndne_f32_e32 v170, v168
	v_fma_f32 v169, |v0|, s55, v169
	v_sub_f32_e32 v168, v168, v170
	v_add_f32_e32 v168, v168, v169
	v_exp_f32_e32 v168, v168
	v_cvt_i32_f32_e32 v169, v170
	v_cmp_ngt_f32_e64 s[10:11], |v0|, s56
	v_min_f32_e32 v165, 0, v0
	v_ldexp_f32 v168, v168, v169
	v_cndmask_b32_e64 v168, 0, v168, s[10:11]
	v_cmp_nlt_f32_e64 s[10:11], |v0|, s57
	s_nop 1
	v_cndmask_b32_e64 v0, v197, v168, s[10:11]
	v_add_f32_e32 v170, 1.0, v0
	v_add_f32_e32 v168, -1.0, v170
	v_sub_f32_e32 v169, v168, v170
	v_add_f32_e32 v169, 1.0, v169
	v_sub_f32_e32 v168, v0, v168
	v_add_f32_e32 v171, v168, v169
	v_frexp_mant_f32_e32 v168, v170
	v_cmp_gt_f32_e64 s[10:11], s59, v168
	v_cvt_f64_f32_e32 v[168:169], v170
	v_frexp_exp_i32_f64_e32 v168, v[168:169]
	v_subbrev_co_u32_e64 v168, s[10:11], 0, v168, s[10:11]
	v_sub_u32_e32 v169, 0, v168
	v_ldexp_f32 v170, v170, v169
	v_ldexp_f32 v169, v171, v169
	v_add_f32_e32 v171, -1.0, v170
	v_add_f32_e32 v172, 1.0, v171
	v_sub_f32_e32 v172, v170, v172
	v_add_f32_e32 v172, v169, v172
	v_add_f32_e32 v174, v171, v172
	v_sub_f32_e32 v171, v171, v174
	v_add_f32_e32 v171, v172, v171
	v_add_f32_e32 v172, 1.0, v170
	v_add_f32_e32 v175, -1.0, v172
	v_sub_f32_e32 v170, v170, v175
	v_add_f32_e32 v169, v169, v170
	v_add_f32_e32 v170, v172, v169
	v_sub_f32_e32 v172, v172, v170
	v_add_f32_e32 v169, v169, v172
	v_rcp_f32_e32 v172, v170
	v_cvt_f32_i32_e32 v168, v168
	v_cmp_neq_f32_e64 s[10:11], s58, v0
	v_mul_f32_e32 v175, v174, v172
	v_mul_f32_e32 v176, v170, v175
	v_fma_f32 v177, v175, v170, -v176
	v_fmac_f32_e32 v177, v175, v169
	v_add_f32_e32 v194, v176, v177
	v_sub_f32_e32 v195, v174, v194
	v_sub_f32_e32 v174, v174, v195
	v_sub_f32_e32 v176, v194, v176
	v_sub_f32_e32 v174, v174, v194
	v_add_f32_e32 v171, v171, v174
	v_sub_f32_e32 v174, v176, v177
	v_add_f32_e32 v171, v174, v171
	v_add_f32_e32 v174, v195, v171
	v_mul_f32_e32 v176, v172, v174
	v_mul_f32_e32 v177, v170, v176
	v_fma_f32 v170, v176, v170, -v177
	v_fmac_f32_e32 v170, v176, v169
	v_sub_f32_e32 v169, v195, v174
	v_add_f32_e32 v169, v171, v169
	v_add_f32_e32 v171, v177, v170
	v_sub_f32_e32 v194, v174, v171
	v_sub_f32_e32 v174, v174, v194
	v_sub_f32_e32 v177, v171, v177
	v_sub_f32_e32 v171, v174, v171
	v_add_f32_e32 v169, v169, v171
	v_sub_f32_e32 v170, v177, v170
	v_add_f32_e32 v169, v170, v169
	v_add_f32_e32 v170, v175, v176
	v_add_f32_e32 v169, v194, v169
	v_sub_f32_e32 v171, v170, v175
	v_mul_f32_e32 v169, v172, v169
	v_sub_f32_e32 v171, v176, v171
	v_add_f32_e32 v169, v171, v169
	v_mul_f32_e32 v175, 0x3f317218, v168
	v_add_f32_e32 v171, v170, v169
	v_fma_f32 v176, v168, s60, -v175
	v_mul_f32_e32 v172, v171, v171
	v_fmac_f32_e32 v176, 0xb102e308, v168
	v_sub_f32_e32 v168, v171, v170
	v_fmamk_f32 v174, v172, 0x3e9b6dac, v196
	v_sub_f32_e32 v168, v169, v168
	v_add_f32_e32 v169, v175, v176
	v_fmaak_f32 v174, v172, v174, 0x3f2aaada
	v_sub_f32_e32 v170, v169, v175
	v_ldexp_f32 v175, v171, 1
	v_mul_f32_e32 v171, v171, v172
	v_mul_f32_e32 v171, v171, v174
	v_add_f32_e32 v172, v175, v171
	v_sub_f32_e32 v174, v172, v175
	v_ldexp_f32 v168, v168, 1
	v_sub_f32_e32 v171, v171, v174
	v_add_f32_e32 v168, v168, v171
	v_add_f32_e32 v171, v172, v168
	v_sub_f32_e32 v172, v171, v172
	v_sub_f32_e32 v168, v168, v172
	v_add_f32_e32 v172, v169, v171
	v_sub_f32_e32 v174, v172, v169
	v_sub_f32_e32 v175, v172, v174
	v_sub_f32_e32 v170, v176, v170
	v_sub_f32_e32 v169, v169, v175
	v_sub_f32_e32 v171, v171, v174
	v_add_f32_e32 v169, v171, v169
	v_add_f32_e32 v171, v170, v168
	v_sub_f32_e32 v174, v171, v170
	v_sub_f32_e32 v175, v171, v174
	v_sub_f32_e32 v170, v170, v175
	v_sub_f32_e32 v168, v168, v174
	v_add_f32_e32 v169, v171, v169
	v_add_f32_e32 v168, v168, v170
	v_add_f32_e32 v170, v172, v169
	v_sub_f32_e32 v171, v170, v172
	v_sub_f32_e32 v169, v169, v171
	v_add_f32_e32 v168, v168, v169
	v_add_f32_e32 v168, v170, v168
	v_cndmask_b32_e64 v168, v197, v168, s[10:11]
	v_cmp_lt_f32_e64 s[10:11], |v0|, s61
	s_nop 1
	v_cndmask_b32_e64 v0, v168, v0, s[10:11]
	v_sub_f32_e32 v0, v165, v0
	v_lshl_add_u64 v[168:169], v[166:167], 0, s[2:3]
	global_store_dword v[168:169], v0, off
	global_load_dword v0, v1, s[18:19] offset:60
	s_or_b32 s2, s38, 15
	s_ashr_i32 s3, s2, 31
	s_lshl_b64 s[4:5], s[2:3], 16
	v_lshl_add_u64 v[166:167], v[166:167], 0, s[4:5]
	s_waitcnt vmcnt(0)
;   DI void operator()(int tok0, int feat0, f32x16 (&acc)[2][2], int r, int hh) const {
;     ...
;       } else if (feat0 == 4096) {
;         if (hh == 0) {
; #pragma unroll
;           for (int i = 0; i < 16; ++i) {
;             const float xv = acc[0][mt][i] + bf[i];
;             const float ls = fminf(xv, 0.f) - log1pf(expf(-fabsf(xv)));
;             lf[((size_t)(b * 16 + i)) * SEQ + s] = ls;
;           }
;         }
	v_add_f32_e32 v0, v129, v0
	v_mul_f32_e64 v168, |v0|, s54
	v_fma_f32 v169, |v0|, s54, -v168
	v_rndne_f32_e32 v170, v168
	v_fma_f32 v169, |v0|, s55, v169
	v_sub_f32_e32 v168, v168, v170
	v_add_f32_e32 v168, v168, v169
	v_exp_f32_e32 v168, v168
	v_cvt_i32_f32_e32 v169, v170
	v_cmp_ngt_f32_e64 s[10:11], |v0|, s56
	v_min_f32_e32 v165, 0, v0
	v_ldexp_f32 v168, v168, v169
	v_cndmask_b32_e64 v168, 0, v168, s[10:11]
	v_cmp_nlt_f32_e64 s[10:11], |v0|, s57
	s_nop 1
	v_cndmask_b32_e64 v0, v197, v168, s[10:11]
	v_add_f32_e32 v170, 1.0, v0
	v_add_f32_e32 v168, -1.0, v170
	v_sub_f32_e32 v169, v168, v170
	v_add_f32_e32 v169, 1.0, v169
	v_sub_f32_e32 v168, v0, v168
	v_add_f32_e32 v171, v168, v169
	v_frexp_mant_f32_e32 v168, v170
	v_cmp_gt_f32_e64 s[10:11], s59, v168
	v_cvt_f64_f32_e32 v[168:169], v170
	v_frexp_exp_i32_f64_e32 v168, v[168:169]
	v_subbrev_co_u32_e64 v168, s[10:11], 0, v168, s[10:11]
	v_sub_u32_e32 v169, 0, v168
	v_ldexp_f32 v170, v170, v169
	v_ldexp_f32 v169, v171, v169
	v_add_f32_e32 v171, -1.0, v170
	v_add_f32_e32 v172, 1.0, v171
	v_sub_f32_e32 v172, v170, v172
	v_add_f32_e32 v172, v169, v172
	v_add_f32_e32 v174, v171, v172
	v_sub_f32_e32 v171, v171, v174
	v_add_f32_e32 v171, v172, v171
	v_add_f32_e32 v172, 1.0, v170
	v_add_f32_e32 v175, -1.0, v172
	v_sub_f32_e32 v170, v170, v175
	v_add_f32_e32 v169, v169, v170
	v_add_f32_e32 v170, v172, v169
	v_sub_f32_e32 v172, v172, v170
	v_add_f32_e32 v169, v169, v172
	v_rcp_f32_e32 v172, v170
	v_cvt_f32_i32_e32 v168, v168
	v_cmp_neq_f32_e64 s[10:11], s58, v0
	v_mul_f32_e32 v175, v174, v172
	v_mul_f32_e32 v176, v170, v175
	v_fma_f32 v177, v175, v170, -v176
	v_fmac_f32_e32 v177, v175, v169
	v_add_f32_e32 v194, v176, v177
	v_sub_f32_e32 v195, v174, v194
	v_sub_f32_e32 v174, v174, v195
	v_sub_f32_e32 v176, v194, v176
	v_sub_f32_e32 v174, v174, v194
	v_add_f32_e32 v171, v171, v174
	v_sub_f32_e32 v174, v176, v177
	v_add_f32_e32 v171, v174, v171
	v_add_f32_e32 v174, v195, v171
	v_mul_f32_e32 v176, v172, v174
	v_mul_f32_e32 v177, v170, v176
	v_fma_f32 v170, v176, v170, -v177
	v_fmac_f32_e32 v170, v176, v169
	v_sub_f32_e32 v169, v195, v174
	v_add_f32_e32 v169, v171, v169
	v_add_f32_e32 v171, v177, v170
	v_sub_f32_e32 v194, v174, v171
	v_sub_f32_e32 v174, v174, v194
	v_sub_f32_e32 v177, v171, v177
	v_sub_f32_e32 v171, v174, v171
	v_add_f32_e32 v169, v169, v171
	v_sub_f32_e32 v170, v177, v170
	v_add_f32_e32 v169, v170, v169
	v_add_f32_e32 v170, v175, v176
	v_add_f32_e32 v169, v194, v169
	v_sub_f32_e32 v171, v170, v175
	v_mul_f32_e32 v169, v172, v169
	v_sub_f32_e32 v171, v176, v171
	v_add_f32_e32 v169, v171, v169
	v_mul_f32_e32 v175, 0x3f317218, v168
	v_add_f32_e32 v171, v170, v169
	v_fma_f32 v176, v168, s60, -v175
	v_mul_f32_e32 v172, v171, v171
	v_fmac_f32_e32 v176, 0xb102e308, v168
	v_sub_f32_e32 v168, v171, v170
	v_fmamk_f32 v174, v172, 0x3e9b6dac, v196
	v_sub_f32_e32 v168, v169, v168
	v_add_f32_e32 v169, v175, v176
	v_fmaak_f32 v174, v172, v174, 0x3f2aaada
	v_sub_f32_e32 v170, v169, v175
	v_ldexp_f32 v175, v171, 1
	v_mul_f32_e32 v171, v171, v172
	v_mul_f32_e32 v171, v171, v174
	v_add_f32_e32 v172, v175, v171
	v_sub_f32_e32 v174, v172, v175
	v_ldexp_f32 v168, v168, 1
	v_sub_f32_e32 v171, v171, v174
	v_add_f32_e32 v168, v168, v171
	v_add_f32_e32 v171, v172, v168
	v_sub_f32_e32 v172, v171, v172
	v_sub_f32_e32 v168, v168, v172
	v_add_f32_e32 v172, v169, v171
	v_sub_f32_e32 v174, v172, v169
	v_sub_f32_e32 v175, v172, v174
	v_sub_f32_e32 v170, v176, v170
	v_sub_f32_e32 v169, v169, v175
	v_sub_f32_e32 v171, v171, v174
	v_add_f32_e32 v169, v171, v169
	v_add_f32_e32 v171, v170, v168
	v_sub_f32_e32 v174, v171, v170
	v_sub_f32_e32 v175, v171, v174
	v_sub_f32_e32 v170, v170, v175
	v_sub_f32_e32 v168, v168, v174
	v_add_f32_e32 v169, v171, v169
	v_add_f32_e32 v168, v168, v170
	v_add_f32_e32 v170, v172, v169
	v_sub_f32_e32 v171, v170, v172
	v_sub_f32_e32 v169, v169, v171
	v_add_f32_e32 v168, v168, v169
	v_add_f32_e32 v168, v170, v168
	v_cndmask_b32_e64 v168, v197, v168, s[10:11]
	v_cmp_lt_f32_e64 s[10:11], |v0|, s61
	s_nop 1
	v_cndmask_b32_e64 v0, v168, v0, s[10:11]
	v_sub_f32_e32 v0, v165, v0
	global_store_dword v[166:167], v0, off

; #define G_GLOAD(XR, WR, KT) { _Pragma("unroll") for (int i_ = 0; i_ < 4; ++i_) XR[i_] = *(const u32x4*)(Xt + ((size_t)(64 * i_) * ldx + (KT) * 64) * 2 + xoff); \
;     _Pragma("unroll") for (int i_ = 0; i_ < 4; ++i_) WR[i_] = *(const u32x4*)(Wtb + ((size_t)(64 * i_) * K + (KT) * 64) * 2 + woff); }
; #define G_LSTORE(XR, WR, STG) { char* xs_ = lds + (STG) * G_STAGE; char* ws_ = xs_ + G_XB; \
;     _Pragma("unroll") for (int i_ = 0; i_ < 4; ++i_) *(u32x4*)(xs_ + (lrow + 64 * i_) * LROW + lch * 16) = XR[i_]; \
;     _Pragma("unroll") for (int i_ = 0; i_ < 4; ++i_) *(u32x4*)(ws_ + (lrow + 64 * i_) * LROW + lch * 16) = WR[i_]; }
; template <class Epi>
; DI void gemm_phase(const bf16_t* __restrict__ X, const int ldx, const bf16_t* __restrict__ Wt, const int N, const int K, const Epi& epi, char* lds) {
;     ...
;     const int L = chunk * 32 + slot, band = L / (4 * nNt), rem = L % (4 * nNt);
;     const int mt_ = band * 4 + (rem & 3), nt_ = rem >> 2;
;     const char* Xt = (const char*)(X + (size_t)(mt_ * 256) * ldx);
;     const char* Wtb = (const char*)(Wt + (size_t)(nt_ * 256) * K);
;     const unsigned xoff = (unsigned)(lrow * ldx + lch * 8) * 2u, woff = (unsigned)(lrow * K + lch * 8) * 2u;
;     const bool has_next = !Epi::kFull && (chunk + 8 < nchunks);
;     const int Ln = (has_next ? chunk + 8 : chunk) * 32 + slot, band_n = Ln / (4 * nNt), rem_n = Ln % (4 * nNt);
;     const char* Xt_n = (const char*)(X + (size_t)((band_n * 4 + (rem_n & 3)) * 256) * ldx);
;     const char* Wtb_n = (const char*)(Wt + (size_t)((rem_n >> 2) * 256) * K);
;     f32x16 acc[2][2][2];
;     ...
;     asm volatile("" ::: "memory");
;     if (Epi::kFull || chunk == xcd) {
;       G_GLOAD(xr0, wr0, 0);
;       G_LSTORE(xr0, wr0, 0);
;       __syncthreads();
;       G_GLOAD(xr0, wr0, 1);
;     }
; #pragma unroll
;     for (int c = 0; c < 2; ++c)
; #pragma unroll
;       for (int a = 0; a < 2; ++a)
; #pragma unroll
;         for (int b = 0; b < 2; ++b)
; #pragma unroll
;           for (int i = 0; i < 16; ++i) acc[c][a][b][i] = 0.f;
.LBB0_310:
	s_add_i32 s36, s10, 8
	s_cmp_gt_u32 s10, 47
	s_cselect_b64 s[24:25], -1, 0
	s_cmp_lt_u32 s10, 48
	s_cselect_b32 s10, s36, s10
	s_cselect_b32 s5, 0, 15
	s_cselect_b32 s12, 1, 15
	s_lshl_b32 s10, s10, 5
	v_readlane_b32 s11, v254, 3
	s_add_i32 s10, s10, s11
	s_lshr_b32 s11, s10, 3
	s_mul_hi_u32 s11, s11, 0x24924925
	s_mul_i32 s14, s11, 56
	s_sub_i32 s26, s10, s14
	s_lshl_b32 s10, s11, 10
	s_lshl_b32 s11, s26, 8
	s_and_b32 s11, s11, 0x300
	s_or_b32 s10, s11, s10
	s_ashr_i32 s11, s10, 31
	s_lshl_b64 s[10:11], s[10:11], 11
	s_add_u32 s14, s30, s10
	s_addc_u32 s15, s31, s11
	s_lshl_b32 s10, s26, 17
	s_and_b32 s10, s10, 0x780000
	s_add_u32 s26, s34, s10
	v_mov_b32_e32 v2, 0
	s_mov_b32 s13, 3
	s_addc_u32 s27, s35, 0
	v_mov_b32_e32 v3, v2
	v_mov_b32_e32 v4, v2
	v_mov_b32_e32 v5, v2
	v_mov_b32_e32 v6, v2
	v_mov_b32_e32 v7, v2
	v_mov_b32_e32 v8, v2
	v_mov_b32_e32 v9, v2
	v_mov_b32_e32 v10, v2
	v_mov_b32_e32 v11, v2
	v_mov_b32_e32 v12, v2
	v_mov_b32_e32 v13, v2
	v_mov_b32_e32 v14, v2
	v_mov_b32_e32 v15, v2
	v_mov_b32_e32 v16, v2
	v_mov_b32_e32 v17, v2
	s_waitcnt vmcnt(5)
	v_mov_b32_e32 v34, v2
	v_mov_b32_e32 v35, v2
	v_mov_b32_e32 v36, v2
	v_mov_b32_e32 v37, v2
	s_waitcnt vmcnt(4)
	v_mov_b32_e32 v38, v2
	v_mov_b32_e32 v39, v2
	v_mov_b32_e32 v40, v2
	v_mov_b32_e32 v41, v2
	s_waitcnt vmcnt(3)
	v_mov_b32_e32 v42, v2
	v_mov_b32_e32 v43, v2
	v_mov_b32_e32 v44, v2
	v_mov_b32_e32 v45, v2
	s_waitcnt vmcnt(2)
	v_mov_b32_e32 v46, v2
	v_mov_b32_e32 v47, v2
	v_mov_b32_e32 v48, v2
	v_mov_b32_e32 v49, v2
	v_mov_b32_e32 v18, v2
	v_mov_b32_e32 v19, v2
	v_mov_b32_e32 v20, v2
	v_mov_b32_e32 v21, v2
	v_mov_b32_e32 v22, v2
	v_mov_b32_e32 v23, v2
	v_mov_b32_e32 v24, v2
	v_mov_b32_e32 v25, v2
	v_mov_b32_e32 v26, v2
	v_mov_b32_e32 v27, v2
	v_mov_b32_e32 v28, v2
	v_mov_b32_e32 v29, v2
	v_mov_b32_e32 v30, v2
	v_mov_b32_e32 v31, v2
	v_mov_b32_e32 v32, v2
	v_mov_b32_e32 v33, v2
	s_waitcnt vmcnt(1)
	v_mov_b32_e32 v50, v2
	v_mov_b32_e32 v51, v2
	v_mov_b32_e32 v52, v2
	v_mov_b32_e32 v53, v2
	s_waitcnt vmcnt(0)
	v_mov_b32_e32 v54, v2
	v_mov_b32_e32 v55, v2
	v_mov_b32_e32 v56, v2
	v_mov_b32_e32 v57, v2
	v_mov_b32_e32 v58, v2
	v_mov_b32_e32 v59, v2
	v_mov_b32_e32 v60, v2
	v_mov_b32_e32 v61, v2
	v_mov_b32_e32 v62, v2
	v_mov_b32_e32 v63, v2
	v_mov_b32_e32 v64, v2
	v_mov_b32_e32 v65, v2
	v_mov_b32_e32 v66, v2
	v_mov_b32_e32 v67, v2
	v_mov_b32_e32 v68, v2
	v_mov_b32_e32 v69, v2
	v_mov_b32_e32 v70, v2
	v_mov_b32_e32 v71, v2
	v_mov_b32_e32 v72, v2
	v_mov_b32_e32 v73, v2
	v_mov_b32_e32 v74, v2
	v_mov_b32_e32 v75, v2
	v_mov_b32_e32 v76, v2
	v_mov_b32_e32 v77, v2
	v_mov_b32_e32 v78, v2
	v_mov_b32_e32 v79, v2
	v_mov_b32_e32 v80, v2
	v_mov_b32_e32 v81, v2
	v_mov_b32_e32 v98, v2
	v_mov_b32_e32 v99, v2
	v_mov_b32_e32 v100, v2
	v_mov_b32_e32 v101, v2
	v_mov_b32_e32 v102, v2
	v_mov_b32_e32 v103, v2
	v_mov_b32_e32 v104, v2
	v_mov_b32_e32 v105, v2
	v_mov_b32_e32 v106, v2
	v_mov_b32_e32 v107, v2
	v_mov_b32_e32 v108, v2
	v_mov_b32_e32 v109, v2
	v_mov_b32_e32 v110, v2
	v_mov_b32_e32 v111, v2
	v_mov_b32_e32 v112, v2
	v_mov_b32_e32 v113, v2
	v_mov_b32_e32 v82, v2
	v_mov_b32_e32 v83, v2
	v_mov_b32_e32 v84, v2
	v_mov_b32_e32 v85, v2
	v_mov_b32_e32 v86, v2
	v_mov_b32_e32 v87, v2
	v_mov_b32_e32 v88, v2
	v_mov_b32_e32 v89, v2
	v_mov_b32_e32 v90, v2
	v_mov_b32_e32 v91, v2
	v_mov_b32_e32 v92, v2
	v_mov_b32_e32 v93, v2
	v_mov_b32_e32 v94, v2
	v_mov_b32_e32 v95, v2
	v_mov_b32_e32 v96, v2
	v_mov_b32_e32 v97, v2
	v_mov_b32_e32 v114, v2
	v_mov_b32_e32 v115, v2
	v_mov_b32_e32 v116, v2
	v_mov_b32_e32 v117, v2
	v_mov_b32_e32 v118, v2
	v_mov_b32_e32 v119, v2
	v_mov_b32_e32 v120, v2
	v_mov_b32_e32 v121, v2
	v_mov_b32_e32 v122, v2
	v_mov_b32_e32 v123, v2
	v_mov_b32_e32 v124, v2
	v_mov_b32_e32 v125, v2
	v_mov_b32_e32 v126, v2
	v_mov_b32_e32 v127, v2
	v_mov_b32_e32 v128, v2
	v_mov_b32_e32 v129, v2
	v_add_u32_e32 v232, s91, v170
	v_add_u32_e32 v233, s1, v170
	v_add_u32_e32 v234, s76, v170
.LBB0_311:
	v_add_u32_e32 v0, v184, v185
	ds_read_b128 v[162:165], v0
	ds_read_b128 v[166:169], v0 offset:4608
	v_add_u32_e32 v0, v184, v186
	ds_read_b128 v[176:179], v0 offset:36864
	ds_read_b128 v[180:183], v0 offset:41472
	ds_read_b128 v[216:219], v0 offset:46080
	ds_read_b128 v[220:223], v0 offset:50688
	ds_read_b128 v[224:227], v189 offset:32
	ds_read_b128 v[228:231], v189 offset:4640
	s_add_i32 s28, s13, -3
	s_cmp_lt_u32 s28, 14
	s_cselect_b64 s[38:39], -1, 0
	s_and_b64 s[10:11], s[38:39], exec
	s_cselect_b32 s11, s9, s27
	s_cselect_b32 s10, s8, s26
	s_cselect_b32 s41, s7, s15
	s_cselect_b32 s40, s6, s14
	s_add_i32 s29, s13, -1
	s_waitcnt lgkmcnt(5)
	v_mfma_f32_32x32x16_bf16 v[114:129], v[176:179], v[162:165], v[114:129]
	v_mfma_f32_32x32x16_bf16 v[82:97], v[176:179], v[166:169], v[82:97]
	s_waitcnt lgkmcnt(4)
	v_mfma_f32_32x32x16_bf16 v[98:113], v[180:183], v[162:165], v[98:113]
	v_mfma_f32_32x32x16_bf16 v[66:81], v[180:183], v[166:169], v[66:81]
	s_waitcnt lgkmcnt(3)
	v_mfma_f32_32x32x16_bf16 v[50:65], v[216:219], v[162:165], v[50:65]
	s_and_b64 s[38:39], s[38:39], exec
	s_cselect_b32 s29, s29, s5
	v_mfma_f32_32x32x16_bf16 v[18:33], v[216:219], v[166:169], v[18:33]
	s_waitcnt lgkmcnt(2)
	v_mfma_f32_32x32x16_bf16 v[34:49], v[220:223], v[162:165], v[34:49]
	ds_read_b128 v[162:165], v190 offset:36896
	ds_read_b128 v[176:179], v190 offset:41504
	v_mfma_f32_32x32x16_bf16 v[2:17], v[220:223], v[166:169], v[2:17]
	s_lshl_b32 s96, s29, 7
	s_add_u32 s100, s40, s96
	s_addc_u32 s101, s41, 0
	s_waitcnt vmcnt(3)
; #define G_GLOAD(XR, WR, KT) { _Pragma("unroll") for (int i_ = 0; i_ < 4; ++i_) XR[i_] = *(const u32x4*)(Xt + ((size_t)(64 * i_) * ldx + (KT) * 64) * 2 + xoff); \
;     _Pragma("unroll") for (int i_ = 0; i_ < 4; ++i_) WR[i_] = *(const u32x4*)(Wtb + ((size_t)(64 * i_) * K + (KT) * 64) * 2 + woff); }
; #define G_LSTORE(XR, WR, STG) { char* xs_ = lds + (STG) * G_STAGE; char* ws_ = xs_ + G_XB; \
;     _Pragma("unroll") for (int i_ = 0; i_ < 4; ++i_) *(u32x4*)(xs_ + (lrow + 64 * i_) * LROW + lch * 16) = XR[i_]; \
;     _Pragma("unroll") for (int i_ = 0; i_ < 4; ++i_) *(u32x4*)(ws_ + (lrow + 64 * i_) * LROW + lch * 16) = WR[i_]; }
; template <class Epi>
; DI void gemm_phase(const bf16_t* __restrict__ X, const int ldx, const bf16_t* __restrict__ Wt, const int N, const int K, const Epi& epi, char* lds) {
;     ...
;     asm volatile("" ::: "memory");
;     if (Epi::kFull || chunk == xcd) {
;       G_GLOAD(xr0, wr0, 0);
;       G_LSTORE(xr0, wr0, 0);
;       __syncthreads();
;       G_GLOAD(xr0, wr0, 1);
;     }
; #pragma unroll
;     for (int c = 0; c < 2; ++c)
; #pragma unroll
;       for (int a = 0; a < 2; ++a)
; #pragma unroll
;         for (int b = 0; b < 2; ++b)
; #pragma unroll
;           for (int i = 0; i < 16; ++i) acc[c][a][b][i] = 0.f;
	ds_write_b128 v191, v[138:141] offset:9216
	ds_write_b128 v191, v[134:137]
	s_nop 0
	global_load_dwordx4 v[134:137], v170, s[100:101]
	global_load_dwordx4 v[138:141], v232, s[100:101]
	ds_write_b128 v191, v[130:133] offset:18432
	ds_write_b128 v191, v[142:145] offset:27648
	s_nop 0
	global_load_dwordx4 v[130:133], v233, s[100:101]
	global_load_dwordx4 v[142:145], v234, s[100:101]
	ds_read_b128 v[166:169], v190 offset:46112
	ds_read_b128 v[180:183], v190 offset:50720
	ds_read_b128 v[216:219], v189 offset:64
	ds_read_b128 v[220:223], v189 offset:4672
	s_waitcnt lgkmcnt(9)
	v_mfma_f32_32x32x16_bf16 v[114:129], v[162:165], v[224:227], v[114:129]
	v_mfma_f32_32x32x16_bf16 v[82:97], v[162:165], v[228:231], v[82:97]
	s_waitcnt lgkmcnt(8)
	v_mfma_f32_32x32x16_bf16 v[98:113], v[176:179], v[224:227], v[98:113]
	v_mfma_f32_32x32x16_bf16 v[66:81], v[176:179], v[228:231], v[66:81]
	s_waitcnt lgkmcnt(3)
	v_mfma_f32_32x32x16_bf16 v[50:65], v[166:169], v[224:227], v[50:65]
	v_mfma_f32_32x32x16_bf16 v[18:33], v[166:169], v[228:231], v[18:33]
	ds_read_b128 v[162:165], v190 offset:36928
	ds_read_b128 v[166:169], v190 offset:41536
	s_waitcnt lgkmcnt(4)
	v_mfma_f32_32x32x16_bf16 v[34:49], v[180:183], v[224:227], v[34:49]
	v_mfma_f32_32x32x16_bf16 v[2:17], v[180:183], v[228:231], v[2:17]
	s_add_u32 s100, s10, s96
	s_addc_u32 s101, s11, 0
	s_waitcnt vmcnt(6)
	ds_write_b128 v208, v[154:157] offset:9216
	s_waitcnt vmcnt(5)
	ds_write_b128 v208, v[146:149]
	s_nop 0
	global_load_dwordx4 v[146:149], v170, s[100:101]
	global_load_dwordx4 v[154:157], v232, s[100:101]
	ds_read_b128 v[176:179], v190 offset:46144
	ds_read_b128 v[180:183], v190 offset:50752
	ds_read_b128 v[224:227], v189 offset:96
	ds_read_b128 v[228:231], v189 offset:4704
	s_waitcnt lgkmcnt(7)
	v_mfma_f32_32x32x16_bf16 v[114:129], v[162:165], v[216:219], v[114:129]
	v_mfma_f32_32x32x16_bf16 v[82:97], v[162:165], v[220:223], v[82:97]
	s_waitcnt lgkmcnt(6)
	v_mfma_f32_32x32x16_bf16 v[98:113], v[166:169], v[216:219], v[98:113]
	v_mfma_f32_32x32x16_bf16 v[66:81], v[166:169], v[220:223], v[66:81]
	s_waitcnt lgkmcnt(3)
	v_mfma_f32_32x32x16_bf16 v[50:65], v[176:179], v[216:219], v[50:65]
	ds_read_b128 v[162:165], v190 offset:36960
	ds_read_b128 v[166:169], v190 offset:41568
	v_mfma_f32_32x32x16_bf16 v[18:33], v[176:179], v[220:223], v[18:33]
	s_waitcnt lgkmcnt(4)
	v_mfma_f32_32x32x16_bf16 v[34:49], v[180:183], v[216:219], v[34:49]
	v_mfma_f32_32x32x16_bf16 v[2:17], v[180:183], v[220:223], v[2:17]
	ds_write_b128 v208, v[150:153] offset:18432
	s_waitcnt vmcnt(6)
	ds_write_b128 v208, v[158:161] offset:27648
	s_nop 0
	global_load_dwordx4 v[150:153], v233, s[100:101]
	global_load_dwordx4 v[158:161], v234, s[100:101]
	ds_read_b128 v[176:179], v190 offset:46176
	ds_read_b128 v[180:183], v190 offset:50784
	s_waitcnt lgkmcnt(5)
	v_mfma_f32_32x32x16_bf16 v[114:129], v[162:165], v[224:227], v[114:129]
	v_mfma_f32_32x32x16_bf16 v[82:97], v[162:165], v[228:231], v[82:97]
	s_waitcnt lgkmcnt(4)
	v_mfma_f32_32x32x16_bf16 v[98:113], v[166:169], v[224:227], v[98:113]
	v_mfma_f32_32x32x16_bf16 v[66:81], v[166:169], v[228:231], v[66:81]
	s_waitcnt lgkmcnt(1)
	v_mfma_f32_32x32x16_bf16 v[50:65], v[176:179], v[224:227], v[50:65]
	v_mfma_f32_32x32x16_bf16 v[18:33], v[176:179], v[228:231], v[18:33]
	s_waitcnt lgkmcnt(0)
	v_mfma_f32_32x32x16_bf16 v[34:49], v[180:183], v[224:227], v[34:49]
	v_mfma_f32_32x32x16_bf16 v[2:17], v[180:183], v[228:231], v[2:17]
	s_barrier
	ds_read_b128 v[162:165], v209
	ds_read_b128 v[166:169], v209 offset:4608
	ds_read_b128 v[176:179], v210
	ds_read_b128 v[180:183], v210 offset:4608
	ds_read_b128 v[216:219], v210 offset:9216
	ds_read_b128 v[220:223], v210 offset:13824
	v_add_u32_e32 v0, v187, v175
	ds_read_b128 v[224:227], v0 offset:32
	ds_read_b128 v[228:231], v211 offset:32
	s_cmp_lt_u32 s28, 13
	s_cselect_b64 s[10:11], -1, 0
	s_and_b64 s[10:11], s[10:11], exec
	s_cselect_b32 s39, s7, s15
	s_cselect_b32 s38, s6, s14
	s_cselect_b32 s11, s9, s27
	s_cselect_b32 s10, s8, s26
	s_waitcnt lgkmcnt(5)
	v_mfma_f32_32x32x16_bf16 v[114:129], v[176:179], v[162:165], v[114:129]
	v_mfma_f32_32x32x16_bf16 v[82:97], v[176:179], v[166:169], v[82:97]
	s_waitcnt lgkmcnt(4)
	v_mfma_f32_32x32x16_bf16 v[98:113], v[180:183], v[162:165], v[98:113]
	v_mfma_f32_32x32x16_bf16 v[66:81], v[180:183], v[166:169], v[66:81]
	s_waitcnt lgkmcnt(3)
	v_mfma_f32_32x32x16_bf16 v[50:65], v[216:219], v[162:165], v[50:65]
	v_add_u32_e32 v174, v188, v175
	s_cselect_b32 s29, s13, s12
	v_mfma_f32_32x32x16_bf16 v[18:33], v[216:219], v[166:169], v[18:33]
	s_waitcnt lgkmcnt(2)
	v_mfma_f32_32x32x16_bf16 v[34:49], v[220:223], v[162:165], v[34:49]
	ds_read_b128 v[162:165], v174 offset:32
	ds_read_b128 v[176:179], v212 offset:32
	v_mfma_f32_32x32x16_bf16 v[2:17], v[220:223], v[166:169], v[2:17]
	s_lshl_b32 s96, s29, 7
	s_add_u32 s100, s38, s96
	s_addc_u32 s101, s39, 0
	s_waitcnt vmcnt(6)
	ds_write_b128 v215, v[138:141] offset:9216
	ds_write_b128 v215, v[134:137]
	s_nop 0
	global_load_dwordx4 v[134:137], v170, s[100:101]
	global_load_dwordx4 v[138:141], v232, s[100:101]
	s_waitcnt vmcnt(7)
	ds_write_b128 v215, v[130:133] offset:18432
	s_waitcnt vmcnt(6)
	ds_write_b128 v215, v[142:145] offset:27648
	s_nop 0
	global_load_dwordx4 v[130:133], v233, s[100:101]
	global_load_dwordx4 v[142:145], v234, s[100:101]
	ds_read_b128 v[166:169], v213 offset:32
	ds_read_b128 v[180:183], v214 offset:32
	ds_read_b128 v[216:219], v0 offset:64
	ds_read_b128 v[220:223], v211 offset:64
	s_waitcnt lgkmcnt(9)
	v_mfma_f32_32x32x16_bf16 v[114:129], v[162:165], v[224:227], v[114:129]
	v_mfma_f32_32x32x16_bf16 v[82:97], v[162:165], v[228:231], v[82:97]
	s_waitcnt lgkmcnt(8)
; template <class Epi>
; DI void gemm_phase(const bf16_t* __restrict__ X, const int ldx, const bf16_t* __restrict__ Wt, const int N, const int K, const Epi& epi, char* lds) {
;     ...
;     asm volatile("" ::: "memory");
;     if (Epi::kFull || chunk == xcd) {
;       G_GLOAD(xr0, wr0, 0);
;       G_LSTORE(xr0, wr0, 0);
;       __syncthreads();
;       G_GLOAD(xr0, wr0, 1);
;     }
; #pragma unroll
;     for (int c = 0; c < 2; ++c)
; #pragma unroll
;       for (int a = 0; a < 2; ++a)
; #pragma unroll
;         for (int b = 0; b < 2; ++b)
; #pragma unroll
;           for (int i = 0; i < 16; ++i) acc[c][a][b][i] = 0.f;
;   DI void operator()(int tok0, int feat0, f32x16 (&acc)[2][2], int r, int hh) const {
;     const int seg = feat0 >> 9, c0 = feat0 & 511;
; #pragma unroll
;     for (int mt = 0; mt < 2; ++mt) {
;       const int tok = tok0 + mt * 32 + r, b = tok >> 14, s = tok & (SEQ - 1);
; #pragma unroll
;       for (int nt = 0; nt < 2; ++nt)
; #pragma unroll
;         for (int gp = 0; gp < 2; ++gp) {
;           const int c = c0 + nt * 32 + 16 * hh + 8 * gp;
;           float v[8];
; #pragma unroll
;           for (int e = 0; e < 8; ++e) v[e] = acc[nt][mt][8 * gp + e];
;           if (seg == 0 || seg == 3) {
;             u32x4 o = {pk2(siluf_(v[0]), siluf_(v[1])), pk2(siluf_(v[2]), siluf_(v[3])), pk2(siluf_(v[4]), siluf_(v[5])), pk2(siluf_(v[6]), siluf_(v[7]))};
;             *(u32x4*)((seg == 0 ? aq : ag) + (size_t)tok * 512 + c) = o;
;           } else if (seg == 1) {
; #pragma unroll
;             for (int h2 = 0; h2 < 2; ++h2) {
;               f32x4 lbv = *(const f32x4*)(lb + c + 4 * h2), o;
; #pragma unroll
;               for (int e = 0; e < 4; ++e) o[e] = __logf(lbv[e] + (1.f - lbv[e]) * sigmoidf_(v[4 * h2 + e]));
;               *(f32x4*)(alf + (size_t)tok * 512 + c + 4 * h2) = o;
;             }
;           } else if (seg == 4 || seg == 5) {
;             const float sc = seg == 4 ? 0.125f * LOG2E : 1.f;
;             u32x4 o = {pk2(v[0] * sc, v[1] * sc), pk2(v[2] * sc, v[3] * sc), pk2(v[4] * sc, v[5] * sc), pk2(v[6] * sc, v[7] * sc)};
;             *(u32x4*)((seg == 4 ? bq : bk) + (size_t)tok * 512 + c) = o;
;           } else {
;             bf16_t* dst = (seg == 2 ? aiT : bvT) + ((size_t)((b * 4 + (c >> 7)) * 128 + (c & 127))) * SEQ + (seg == 2 ? s : swz32(s));
; #pragma unroll
	v_mfma_f32_32x32x16_bf16 v[98:113], v[176:179], v[224:227], v[98:113]
	v_mfma_f32_32x32x16_bf16 v[66:81], v[176:179], v[228:231], v[66:81]
	s_waitcnt lgkmcnt(3)
	v_mfma_f32_32x32x16_bf16 v[50:65], v[166:169], v[224:227], v[50:65]
	v_mfma_f32_32x32x16_bf16 v[18:33], v[166:169], v[228:231], v[18:33]
	ds_read_b128 v[162:165], v174 offset:64
	ds_read_b128 v[166:169], v212 offset:64
	s_waitcnt lgkmcnt(4)
	v_mfma_f32_32x32x16_bf16 v[34:49], v[180:183], v[224:227], v[34:49]
	v_mfma_f32_32x32x16_bf16 v[2:17], v[180:183], v[228:231], v[2:17]
	s_add_u32 s100, s10, s96
	s_addc_u32 s101, s11, 0
	s_waitcnt vmcnt(6)
	ds_write_b128 v215, v[154:157] offset:46080
	ds_write_b128 v215, v[146:149] offset:36864
	s_nop 0
	global_load_dwordx4 v[146:149], v170, s[100:101]
	global_load_dwordx4 v[154:157], v232, s[100:101]
	ds_read_b128 v[176:179], v213 offset:64
	ds_read_b128 v[180:183], v214 offset:64
	ds_read_b128 v[224:227], v0 offset:96
	ds_read_b128 v[228:231], v211 offset:96
	s_waitcnt lgkmcnt(7)
	v_mfma_f32_32x32x16_bf16 v[114:129], v[162:165], v[216:219], v[114:129]
	v_mfma_f32_32x32x16_bf16 v[82:97], v[162:165], v[220:223], v[82:97]
	s_waitcnt lgkmcnt(6)
	v_mfma_f32_32x32x16_bf16 v[98:113], v[166:169], v[216:219], v[98:113]
	v_mfma_f32_32x32x16_bf16 v[66:81], v[166:169], v[220:223], v[66:81]
	s_waitcnt lgkmcnt(3)
	v_mfma_f32_32x32x16_bf16 v[50:65], v[176:179], v[216:219], v[50:65]
	ds_read_b128 v[162:165], v174 offset:96
	ds_read_b128 v[166:169], v212 offset:96
	v_mfma_f32_32x32x16_bf16 v[18:33], v[176:179], v[220:223], v[18:33]
	s_waitcnt lgkmcnt(4)
	v_mfma_f32_32x32x16_bf16 v[34:49], v[180:183], v[216:219], v[34:49]
	v_mfma_f32_32x32x16_bf16 v[2:17], v[180:183], v[220:223], v[2:17]
	s_waitcnt vmcnt(7)
	ds_write_b128 v215, v[150:153] offset:55296
	s_waitcnt vmcnt(6)
	ds_write_b128 v215, v[158:161] offset:64512
	s_nop 0
	global_load_dwordx4 v[150:153], v233, s[100:101]
	global_load_dwordx4 v[158:161], v234, s[100:101]
	ds_read_b128 v[176:179], v213 offset:96
	ds_read_b128 v[180:183], v214 offset:96
	s_waitcnt lgkmcnt(5)
	v_mfma_f32_32x32x16_bf16 v[114:129], v[162:165], v[224:227], v[114:129]
	v_mfma_f32_32x32x16_bf16 v[82:97], v[162:165], v[228:231], v[82:97]
	s_waitcnt lgkmcnt(4)
	v_mfma_f32_32x32x16_bf16 v[98:113], v[166:169], v[224:227], v[98:113]
	v_mfma_f32_32x32x16_bf16 v[66:81], v[166:169], v[228:231], v[66:81]
	s_waitcnt lgkmcnt(1)
	v_mfma_f32_32x32x16_bf16 v[50:65], v[176:179], v[224:227], v[50:65]
	v_mfma_f32_32x32x16_bf16 v[18:33], v[176:179], v[228:231], v[18:33]
	s_waitcnt lgkmcnt(0)
	v_mfma_f32_32x32x16_bf16 v[34:49], v[180:183], v[224:227], v[34:49]
	v_mfma_f32_32x32x16_bf16 v[2:17], v[180:183], v[228:231], v[2:17]
	s_add_i32 s13, s13, 2
	s_cmp_gt_u32 s28, 13
	s_barrier
	s_cbranch_scc0 .LBB0_311
	v_mov_b32_e32 v0, v192
	s_ashr_i32 s2, s2, 5
	v_ashrrev_i32_e32 v162, 1, v0
	v_and_b32_e32 v162, 0xffffff80, v162
	v_lshrrev_b32_e32 v165, 1, v0
	v_add_u32_e32 v162, s3, v162
	v_and_b32_e32 v164, 0xdf, v0
	v_and_b32_e32 v0, 16, v165
	s_movk_i32 s3, 0x180
	v_and_or_b32 v216, v162, s3, v0
	s_movk_i32 s3, 0x200
	v_ashrrev_i32_e32 v163, 9, v162
	v_cmp_gt_u32_e64 s[12:13], s3, v162
	s_movk_i32 s3, 0x1ff
	v_cmp_lt_u32_e32 vcc, s3, v162
	v_cmp_ne_u32_e64 s[6:7], 3, v163
	s_and_b64 s[26:27], vcc, s[6:7]
	v_and_b32_e32 v0, 0xfffffc00, v162
	v_cmp_eq_u32_e32 vcc, 4, v163
	v_mov_b32_e32 v162, 0x3e38aa3b
	v_cmp_ne_u32_e64 s[8:9], 1, v163
	v_cmp_eq_u32_e64 s[10:11], 2, v163
	v_cndmask_b32_e32 v174, 1.0, v162, vcc
	v_bfrev_b32_e32 v162, 48
	v_mov_b32_e32 v163, 0xa000000
	v_or_b32_e32 v180, s4, v164
	v_cndmask_b32_e32 v172, v162, v163, vcc
	v_mov_b32_e32 v162, s4
	s_and_b32 s37, s2, 0xfffffe00
	s_movk_i32 s2, 0x3fd3
	v_bitop3_b32 v163, v164, s53, v162 bitop3:0xc8
	v_bitop3_b32 v162, v164, s2, v162 bitop3:0xc8
	v_lshlrev_b32_e32 v164, 1, v180
	s_movk_i32 s3, 0x800
	v_and_b32_e32 v218, 8, v164
	v_and_b32_e32 v219, 4, v165
	v_cmp_ne_u32_e64 s[6:7], s3, v0
	v_mov_b32_e32 v0, 0x6000000
	v_or3_b32 v162, v162, v218, v219
	v_ashrrev_i32_e32 v181, 31, v180
	v_cndmask_b32_e64 v0, v207, v0, s[10:11]
	v_mov_b32_e32 v173, v1
	v_cndmask_b32_e64 v217, v162, v163, s[10:11]
	v_lshlrev_b64 v[178:179], 10, v[180:181]
	v_lshlrev_b64 v[176:177], 11, v[180:181]
	s_and_saveexec_b64 s[2:3], s[26:27]
	s_xor_b64 s[4:5], exec, s[2:3]
	s_cbranch_execz .LBB0_322
	s_and_saveexec_b64 s[2:3], s[8:9]
	s_xor_b64 s[14:15], exec, s[2:3]
	s_cbranch_execz .LBB0_319
	s_and_saveexec_b64 s[2:3], s[6:7]
	s_xor_b64 s[28:29], exec, s[2:3]
	s_cbranch_execz .LBB0_316
	v_or_b32_e32 v164, s37, v216
	v_ashrrev_i32_e32 v165, 31, v164
	v_lshl_add_u64 v[162:163], s[16:17], 0, v[0:1]
	v_lshlrev_b64 v[164:165], 15, v[164:165]
	v_lshl_add_u64 v[162:163], v[162:163], 0, v[164:165]
	v_lshlrev_b32_e32 v164, 1, v217
	v_mov_b32_e32 v165, v1
	v_lshl_add_u64 v[162:163], v[162:163], 0, v[164:165]
	v_cvt_pk_bf16_f32 v164, v114, s0
	global_store_short v[162:163], v164, off
	v_add_co_u32_e32 v164, vcc, 0x8000, v162
	v_cvt_pk_bf16_f32 v166, v115, s0
	s_nop 0
	v_addc_co_u32_e32 v165, vcc, 0, v163, vcc
	global_store_short v[164:165], v166, off
	v_add_co_u32_e32 v164, vcc, s65, v162
	v_cvt_pk_bf16_f32 v166, v116, s0
	s_nop 0
	v_addc_co_u32_e32 v165, vcc, 0, v163, vcc
	global_store_short v[164:165], v166, off
	v_add_co_u32_e32 v164, vcc, 0x18000, v162
	v_cvt_pk_bf16_f32 v166, v117, s0
	s_nop 0
	v_addc_co_u32_e32 v165, vcc, 0, v163, vcc
	global_store_short v[164:165], v166, off
	v_add_co_u32_e32 v164, vcc, s91, v162
	v_cvt_pk_bf16_f32 v166, v118, s0
	s_nop 0
	v_addc_co_u32_e32 v165, vcc, 0, v163, vcc
	global_store_short v[164:165], v166, off
	v_add_co_u32_e32 v164, vcc, 0x28000, v162
	v_cvt_pk_bf16_f32 v166, v119, s0
	s_nop 0
	v_addc_co_u32_e32 v165, vcc, 0, v163, vcc
	global_store_short v[164:165], v166, off
	v_add_co_u32_e32 v164, vcc, 0x30000, v162
	v_cvt_pk_bf16_f32 v166, v120, s0
	s_nop 0
	v_addc_co_u32_e32 v165, vcc, 0, v163, vcc
	v_add_co_u32_e32 v162, vcc, 0x38000, v162
	global_store_short v[164:165], v166, off
	v_cvt_pk_bf16_f32 v164, v121, s0
	v_addc_co_u32_e32 v163, vcc, 0, v163, vcc
	global_store_short v[162:163], v164, off

; #define G_GLOAD(XR, WR, KT) { _Pragma("unroll") for (int i_ = 0; i_ < 4; ++i_) XR[i_] = *(const u32x4*)(Xt + ((size_t)(64 * i_) * ldx + (KT) * 64) * 2 + xoff); \
;     _Pragma("unroll") for (int i_ = 0; i_ < 4; ++i_) WR[i_] = *(const u32x4*)(Wtb + ((size_t)(64 * i_) * K + (KT) * 64) * 2 + woff); }
; #define G_LSTORE(XR, WR, STG) { char* xs_ = lds + (STG) * G_STAGE; char* ws_ = xs_ + G_XB; \
;     _Pragma("unroll") for (int i_ = 0; i_ < 4; ++i_) *(u32x4*)(xs_ + (lrow + 64 * i_) * LROW + lch * 16) = XR[i_]; \
;     _Pragma("unroll") for (int i_ = 0; i_ < 4; ++i_) *(u32x4*)(ws_ + (lrow + 64 * i_) * LROW + lch * 16) = WR[i_]; }
; template <class Epi>
; DI void gemm_phase(const bf16_t* __restrict__ X, const int ldx, const bf16_t* __restrict__ Wt, const int N, const int K, const Epi& epi, char* lds) {
;     ...
;     const int L = chunk * 32 + slot, band = L / (4 * nNt), rem = L % (4 * nNt);
;     const int mt_ = band * 4 + (rem & 3), nt_ = rem >> 2;
;     const char* Xt = (const char*)(X + (size_t)(mt_ * 256) * ldx);
;     const char* Wtb = (const char*)(Wt + (size_t)(nt_ * 256) * K);
;     const unsigned xoff = (unsigned)(lrow * ldx + lch * 8) * 2u, woff = (unsigned)(lrow * K + lch * 8) * 2u;
;     const bool has_next = !Epi::kFull && (chunk + 8 < nchunks);
;     const int Ln = (has_next ? chunk + 8 : chunk) * 32 + slot, band_n = Ln / (4 * nNt), rem_n = Ln % (4 * nNt);
;     const char* Xt_n = (const char*)(X + (size_t)((band_n * 4 + (rem_n & 3)) * 256) * ldx);
;     const char* Wtb_n = (const char*)(Wt + (size_t)((rem_n >> 2) * 256) * K);
;     f32x16 acc[2][2][2];
;     ...
;     asm volatile("" ::: "memory");
;     if (Epi::kFull || chunk == xcd) {
;       G_GLOAD(xr0, wr0, 0);
;       G_LSTORE(xr0, wr0, 0);
;       __syncthreads();
;       G_GLOAD(xr0, wr0, 1);
;     }
; #pragma unroll
;     for (int c = 0; c < 2; ++c)
; #pragma unroll
;       for (int a = 0; a < 2; ++a)
; #pragma unroll
;         for (int b = 0; b < 2; ++b)
; #pragma unroll
;           for (int i = 0; i < 16; ++i) acc[c][a][b][i] = 0.f;
.LBB0_738:
	s_add_i32 s9, s16, 8
	s_cmpk_gt_u32 s16, 0x4f
	s_cselect_b64 s[4:5], -1, 0
	s_cmpk_lt_u32 s16, 0x50
	s_cselect_b32 s16, s9, s16
	s_cselect_b32 s21, 0, 15
	s_cselect_b32 s22, 1, 15
	s_lshl_b32 s16, s16, 5
	v_readlane_b32 s17, v254, 3
	s_add_i32 s16, s16, s17
	s_mul_hi_u32 s17, s16, 0xba2e8ba3
	s_lshr_b32 s17, s17, 6
	s_mul_i32 s23, s17, 0x58
	s_sub_i32 s26, s16, s23
	s_lshl_b32 s16, s17, 10
	s_lshl_b32 s17, s26, 8
	s_and_b32 s17, s17, 0x300
	s_or_b32 s16, s17, s16
	s_ashr_i32 s17, s16, 31
	s_lshl_b64 s[16:17], s[16:17], 11
	s_add_u32 s23, s2, s16
	s_addc_u32 s25, s18, s17
	s_lshl_b32 s16, s26, 17
	s_and_b32 s16, s16, 0xf80000
	s_add_u32 s26, s19, s16
	v_mov_b32_e32 v2, 0
	s_addc_u32 s27, s20, 0
	s_mov_b32 s28, 3
	v_mov_b32_e32 v3, v2
	v_mov_b32_e32 v4, v2
	v_mov_b32_e32 v5, v2
	v_mov_b32_e32 v6, v2
	v_mov_b32_e32 v7, v2
	v_mov_b32_e32 v8, v2
	v_mov_b32_e32 v9, v2
	v_mov_b32_e32 v10, v2
	v_mov_b32_e32 v11, v2
	v_mov_b32_e32 v12, v2
	v_mov_b32_e32 v13, v2
	v_mov_b32_e32 v14, v2
	v_mov_b32_e32 v15, v2
	v_mov_b32_e32 v16, v2
	v_mov_b32_e32 v17, v2
	s_waitcnt vmcnt(5)
	v_mov_b32_e32 v34, v2
	v_mov_b32_e32 v35, v2
	v_mov_b32_e32 v36, v2
	v_mov_b32_e32 v37, v2
	s_waitcnt vmcnt(4)
	v_mov_b32_e32 v38, v2
	v_mov_b32_e32 v39, v2
	v_mov_b32_e32 v40, v2
	v_mov_b32_e32 v41, v2
	s_waitcnt vmcnt(3)
	v_mov_b32_e32 v42, v2
	v_mov_b32_e32 v43, v2
	v_mov_b32_e32 v44, v2
	v_mov_b32_e32 v45, v2
	s_waitcnt vmcnt(2)
	v_mov_b32_e32 v46, v2
	v_mov_b32_e32 v47, v2
	v_mov_b32_e32 v48, v2
	v_mov_b32_e32 v49, v2
	v_mov_b32_e32 v18, v2
	v_mov_b32_e32 v19, v2
	v_mov_b32_e32 v20, v2
	v_mov_b32_e32 v21, v2
	v_mov_b32_e32 v22, v2
	v_mov_b32_e32 v23, v2
	v_mov_b32_e32 v24, v2
	v_mov_b32_e32 v25, v2
	v_mov_b32_e32 v26, v2
	v_mov_b32_e32 v27, v2
	v_mov_b32_e32 v28, v2
	v_mov_b32_e32 v29, v2
	v_mov_b32_e32 v30, v2
	v_mov_b32_e32 v31, v2
	v_mov_b32_e32 v32, v2
	v_mov_b32_e32 v33, v2
	s_waitcnt vmcnt(1)
	v_mov_b32_e32 v50, v2
	v_mov_b32_e32 v51, v2
	v_mov_b32_e32 v52, v2
	v_mov_b32_e32 v53, v2
	s_waitcnt vmcnt(0)
	v_mov_b32_e32 v54, v2
	v_mov_b32_e32 v55, v2
	v_mov_b32_e32 v56, v2
	v_mov_b32_e32 v57, v2
	v_mov_b32_e32 v58, v2
	v_mov_b32_e32 v59, v2
	v_mov_b32_e32 v60, v2
	v_mov_b32_e32 v61, v2
	v_mov_b32_e32 v62, v2
	v_mov_b32_e32 v63, v2
	v_mov_b32_e32 v64, v2
	v_mov_b32_e32 v65, v2
	v_mov_b32_e32 v66, v2
	v_mov_b32_e32 v67, v2
	v_mov_b32_e32 v68, v2
	v_mov_b32_e32 v69, v2
	v_mov_b32_e32 v70, v2
	v_mov_b32_e32 v71, v2
	v_mov_b32_e32 v72, v2
	v_mov_b32_e32 v73, v2
	v_mov_b32_e32 v74, v2
	v_mov_b32_e32 v75, v2
	v_mov_b32_e32 v76, v2
	v_mov_b32_e32 v77, v2
	v_mov_b32_e32 v78, v2
	v_mov_b32_e32 v79, v2
	v_mov_b32_e32 v80, v2
	v_mov_b32_e32 v81, v2
	v_mov_b32_e32 v98, v2
	v_mov_b32_e32 v99, v2
	v_mov_b32_e32 v100, v2
	v_mov_b32_e32 v101, v2
	v_mov_b32_e32 v102, v2
	v_mov_b32_e32 v103, v2
	v_mov_b32_e32 v104, v2
	v_mov_b32_e32 v105, v2
	v_mov_b32_e32 v106, v2
	v_mov_b32_e32 v107, v2
	v_mov_b32_e32 v108, v2
	v_mov_b32_e32 v109, v2
	v_mov_b32_e32 v110, v2
	v_mov_b32_e32 v111, v2
	v_mov_b32_e32 v112, v2
	v_mov_b32_e32 v113, v2
	v_mov_b32_e32 v82, v2
	v_mov_b32_e32 v83, v2
	v_mov_b32_e32 v84, v2
	v_mov_b32_e32 v85, v2
	v_mov_b32_e32 v86, v2
	v_mov_b32_e32 v87, v2
	v_mov_b32_e32 v88, v2
	v_mov_b32_e32 v89, v2
	v_mov_b32_e32 v90, v2
	v_mov_b32_e32 v91, v2
	v_mov_b32_e32 v92, v2
	v_mov_b32_e32 v93, v2
	v_mov_b32_e32 v94, v2
	v_mov_b32_e32 v95, v2
	v_mov_b32_e32 v96, v2
	v_mov_b32_e32 v97, v2
	v_mov_b32_e32 v114, v2
	v_mov_b32_e32 v115, v2
	v_mov_b32_e32 v116, v2
	v_mov_b32_e32 v117, v2
	v_mov_b32_e32 v118, v2
	v_mov_b32_e32 v119, v2
	v_mov_b32_e32 v120, v2
	v_mov_b32_e32 v121, v2
	v_mov_b32_e32 v122, v2
	v_mov_b32_e32 v123, v2
	v_mov_b32_e32 v124, v2
	v_mov_b32_e32 v125, v2
	v_mov_b32_e32 v126, v2
	v_mov_b32_e32 v127, v2
	v_mov_b32_e32 v128, v2
	v_mov_b32_e32 v129, v2
	v_add_u32_e32 v232, s91, v162
	v_add_u32_e32 v233, s1, v162
	v_add_u32_e32 v234, s76, v162
.LBB0_739:
	v_add_u32_e32 v0, v171, v172
	ds_read_b128 v[164:167], v0
	ds_read_b128 v[188:191], v0 offset:4608
	v_add_u32_e32 v0, v171, v173
	ds_read_b128 v[194:197], v0 offset:36864
	ds_read_b128 v[202:205], v0 offset:41472
	ds_read_b128 v[206:209], v0 offset:46080
	ds_read_b128 v[210:213], v0 offset:50688
	ds_read_b128 v[214:217], v176 offset:32
	ds_read_b128 v[218:221], v176 offset:4640
	s_add_i32 s29, s28, -3
	s_cmp_lt_u32 s29, 14
	s_cselect_b64 s[30:31], -1, 0
	s_and_b64 s[16:17], s[30:31], exec
	s_cselect_b32 s17, s15, s27
	s_cselect_b32 s16, s14, s26
	s_cselect_b32 s35, s13, s25
	s_cselect_b32 s34, s12, s23
	s_add_i32 s33, s28, -1
	s_waitcnt lgkmcnt(5)
	v_mfma_f32_32x32x16_bf16 v[114:129], v[194:197], v[164:167], v[114:129]
	v_mfma_f32_32x32x16_bf16 v[82:97], v[194:197], v[188:191], v[82:97]
	s_waitcnt lgkmcnt(4)
	v_mfma_f32_32x32x16_bf16 v[98:113], v[202:205], v[164:167], v[98:113]
	v_mfma_f32_32x32x16_bf16 v[66:81], v[202:205], v[188:191], v[66:81]
	s_waitcnt lgkmcnt(3)
	v_mfma_f32_32x32x16_bf16 v[50:65], v[206:209], v[164:167], v[50:65]
	s_and_b64 s[30:31], s[30:31], exec
	s_cselect_b32 s30, s33, s21
	v_mfma_f32_32x32x16_bf16 v[18:33], v[206:209], v[188:191], v[18:33]
	s_waitcnt lgkmcnt(2)
	v_mfma_f32_32x32x16_bf16 v[34:49], v[210:213], v[164:167], v[34:49]
	ds_read_b128 v[164:167], v177 offset:36896
	ds_read_b128 v[194:197], v177 offset:41504
	v_mfma_f32_32x32x16_bf16 v[2:17], v[210:213], v[188:191], v[2:17]
	s_lshl_b32 s96, s30, 7
	s_add_u32 s100, s34, s96
	s_addc_u32 s101, s35, 0
	s_waitcnt vmcnt(6)
	ds_write_b128 v178, v[142:145] offset:9216
	ds_write_b128 v178, v[134:137]
	s_nop 0
	global_load_dwordx4 v[134:137], v162, s[100:101]
	global_load_dwordx4 v[142:145], v232, s[100:101]
	s_waitcnt vmcnt(7)
; #define G_GLOAD(XR, WR, KT) { _Pragma("unroll") for (int i_ = 0; i_ < 4; ++i_) XR[i_] = *(const u32x4*)(Xt + ((size_t)(64 * i_) * ldx + (KT) * 64) * 2 + xoff); \
;     _Pragma("unroll") for (int i_ = 0; i_ < 4; ++i_) WR[i_] = *(const u32x4*)(Wtb + ((size_t)(64 * i_) * K + (KT) * 64) * 2 + woff); }
; #define G_LSTORE(XR, WR, STG) { char* xs_ = lds + (STG) * G_STAGE; char* ws_ = xs_ + G_XB; \
;     _Pragma("unroll") for (int i_ = 0; i_ < 4; ++i_) *(u32x4*)(xs_ + (lrow + 64 * i_) * LROW + lch * 16) = XR[i_]; \
;     _Pragma("unroll") for (int i_ = 0; i_ < 4; ++i_) *(u32x4*)(ws_ + (lrow + 64 * i_) * LROW + lch * 16) = WR[i_]; }
; template <class Epi>
; DI void gemm_phase(const bf16_t* __restrict__ X, const int ldx, const bf16_t* __restrict__ Wt, const int N, const int K, const Epi& epi, char* lds) {
;     ...
;     asm volatile("" ::: "memory");
;     if (Epi::kFull || chunk == xcd) {
;       G_GLOAD(xr0, wr0, 0);
;       G_LSTORE(xr0, wr0, 0);
;       __syncthreads();
;       G_GLOAD(xr0, wr0, 1);
;     }
; #pragma unroll
;     for (int c = 0; c < 2; ++c)
; #pragma unroll
;       for (int a = 0; a < 2; ++a)
; #pragma unroll
;         for (int b = 0; b < 2; ++b)
; #pragma unroll
;           for (int i = 0; i < 16; ++i) acc[c][a][b][i] = 0.f;
	ds_write_b128 v178, v[130:133] offset:18432
	s_waitcnt vmcnt(6)
	ds_write_b128 v178, v[150:153] offset:27648
	s_nop 0
	global_load_dwordx4 v[130:133], v233, s[100:101]
	global_load_dwordx4 v[150:153], v234, s[100:101]
	ds_read_b128 v[188:191], v177 offset:46112
	ds_read_b128 v[202:205], v177 offset:50720
	ds_read_b128 v[206:209], v176 offset:64
	ds_read_b128 v[210:213], v176 offset:4672
	s_waitcnt lgkmcnt(9)
	v_mfma_f32_32x32x16_bf16 v[114:129], v[164:167], v[214:217], v[114:129]
	v_mfma_f32_32x32x16_bf16 v[82:97], v[164:167], v[218:221], v[82:97]
	s_waitcnt lgkmcnt(8)
	v_mfma_f32_32x32x16_bf16 v[98:113], v[194:197], v[214:217], v[98:113]
	v_mfma_f32_32x32x16_bf16 v[66:81], v[194:197], v[218:221], v[66:81]
	s_waitcnt lgkmcnt(3)
	v_mfma_f32_32x32x16_bf16 v[50:65], v[188:191], v[214:217], v[50:65]
	v_mfma_f32_32x32x16_bf16 v[18:33], v[188:191], v[218:221], v[18:33]
	ds_read_b128 v[164:167], v177 offset:36928
	ds_read_b128 v[188:191], v177 offset:41536
	s_waitcnt lgkmcnt(4)
	v_mfma_f32_32x32x16_bf16 v[34:49], v[202:205], v[214:217], v[34:49]
	v_mfma_f32_32x32x16_bf16 v[2:17], v[202:205], v[218:221], v[2:17]
	s_add_u32 s100, s16, s96
	s_addc_u32 s101, s17, 0
	s_waitcnt vmcnt(6)
	ds_write_b128 v179, v[154:157] offset:9216
	ds_write_b128 v179, v[138:141]
	s_nop 0
	global_load_dwordx4 v[138:141], v162, s[100:101]
	global_load_dwordx4 v[154:157], v232, s[100:101]
	ds_read_b128 v[194:197], v177 offset:46144
	ds_read_b128 v[202:205], v177 offset:50752
	ds_read_b128 v[214:217], v176 offset:96
	ds_read_b128 v[218:221], v176 offset:4704
	s_waitcnt lgkmcnt(7)
	v_mfma_f32_32x32x16_bf16 v[114:129], v[164:167], v[206:209], v[114:129]
	v_mfma_f32_32x32x16_bf16 v[82:97], v[164:167], v[210:213], v[82:97]
	s_waitcnt lgkmcnt(6)
	v_mfma_f32_32x32x16_bf16 v[98:113], v[188:191], v[206:209], v[98:113]
	v_mfma_f32_32x32x16_bf16 v[66:81], v[188:191], v[210:213], v[66:81]
	s_waitcnt lgkmcnt(3)
	v_mfma_f32_32x32x16_bf16 v[50:65], v[194:197], v[206:209], v[50:65]
	ds_read_b128 v[164:167], v177 offset:36960
	ds_read_b128 v[188:191], v177 offset:41568
	v_mfma_f32_32x32x16_bf16 v[18:33], v[194:197], v[210:213], v[18:33]
	s_waitcnt lgkmcnt(4)
	v_mfma_f32_32x32x16_bf16 v[34:49], v[202:205], v[206:209], v[34:49]
	v_mfma_f32_32x32x16_bf16 v[2:17], v[202:205], v[210:213], v[2:17]
	s_waitcnt vmcnt(7)
	ds_write_b128 v179, v[146:149] offset:18432
	s_waitcnt vmcnt(6)
	ds_write_b128 v179, v[158:161] offset:27648
	s_nop 0
	global_load_dwordx4 v[146:149], v233, s[100:101]
	global_load_dwordx4 v[158:161], v234, s[100:101]
	ds_read_b128 v[194:197], v177 offset:46176
	ds_read_b128 v[202:205], v177 offset:50784
	s_waitcnt lgkmcnt(5)
	v_mfma_f32_32x32x16_bf16 v[114:129], v[164:167], v[214:217], v[114:129]
	v_mfma_f32_32x32x16_bf16 v[82:97], v[164:167], v[218:221], v[82:97]
	s_waitcnt lgkmcnt(4)
	v_mfma_f32_32x32x16_bf16 v[98:113], v[188:191], v[214:217], v[98:113]
	v_mfma_f32_32x32x16_bf16 v[66:81], v[188:191], v[218:221], v[66:81]
	s_waitcnt lgkmcnt(1)
	v_mfma_f32_32x32x16_bf16 v[50:65], v[194:197], v[214:217], v[50:65]
	v_mfma_f32_32x32x16_bf16 v[18:33], v[194:197], v[218:221], v[18:33]
	s_waitcnt lgkmcnt(0)
	v_mfma_f32_32x32x16_bf16 v[34:49], v[202:205], v[214:217], v[34:49]
	v_mfma_f32_32x32x16_bf16 v[2:17], v[202:205], v[218:221], v[2:17]
	s_barrier
	ds_read_b128 v[164:167], v180
	ds_read_b128 v[188:191], v180 offset:4608
	ds_read_b128 v[194:197], v181
	ds_read_b128 v[202:205], v181 offset:4608
	ds_read_b128 v[206:209], v181 offset:9216
	ds_read_b128 v[210:213], v181 offset:13824
	v_add_u32_e32 v0, v174, v170
	ds_read_b128 v[214:217], v0 offset:32
	ds_read_b128 v[218:221], v182 offset:32
	s_cmp_lt_u32 s29, 13
	s_cselect_b64 s[16:17], -1, 0
	s_and_b64 s[16:17], s[16:17], exec
	s_cselect_b32 s31, s13, s25
	s_cselect_b32 s30, s12, s23
	s_cselect_b32 s17, s15, s27
	s_cselect_b32 s16, s14, s26
	s_waitcnt lgkmcnt(5)
	v_mfma_f32_32x32x16_bf16 v[114:129], v[194:197], v[164:167], v[114:129]
	v_mfma_f32_32x32x16_bf16 v[82:97], v[194:197], v[188:191], v[82:97]
	s_waitcnt lgkmcnt(4)
	v_mfma_f32_32x32x16_bf16 v[98:113], v[202:205], v[164:167], v[98:113]
	v_mfma_f32_32x32x16_bf16 v[66:81], v[202:205], v[188:191], v[66:81]
	s_waitcnt lgkmcnt(3)
	v_mfma_f32_32x32x16_bf16 v[50:65], v[206:209], v[164:167], v[50:65]
	v_add_u32_e32 v187, v175, v170
	s_cselect_b32 s33, s28, s22
	v_mfma_f32_32x32x16_bf16 v[18:33], v[206:209], v[188:191], v[18:33]
	s_waitcnt lgkmcnt(2)
	v_mfma_f32_32x32x16_bf16 v[34:49], v[210:213], v[164:167], v[34:49]
	ds_read_b128 v[164:167], v187 offset:32
	ds_read_b128 v[194:197], v183 offset:32
	v_mfma_f32_32x32x16_bf16 v[2:17], v[210:213], v[188:191], v[2:17]
	s_lshl_b32 s96, s33, 7
	s_add_u32 s100, s30, s96
	s_addc_u32 s101, s31, 0
	s_waitcnt vmcnt(6)
	ds_write_b128 v186, v[142:145] offset:9216
	ds_write_b128 v186, v[134:137]
	s_nop 0
	global_load_dwordx4 v[134:137], v162, s[100:101]
	global_load_dwordx4 v[142:145], v232, s[100:101]
	s_waitcnt vmcnt(7)
	ds_write_b128 v186, v[130:133] offset:18432
	s_waitcnt vmcnt(6)
	ds_write_b128 v186, v[150:153] offset:27648
	s_nop 0
	global_load_dwordx4 v[130:133], v233, s[100:101]
	global_load_dwordx4 v[150:153], v234, s[100:101]
	ds_read_b128 v[188:191], v184 offset:32
	ds_read_b128 v[202:205], v185 offset:32
	ds_read_b128 v[206:209], v0 offset:64
	ds_read_b128 v[210:213], v182 offset:64
	s_waitcnt lgkmcnt(9)
	v_mfma_f32_32x32x16_bf16 v[114:129], v[164:167], v[214:217], v[114:129]
	v_mfma_f32_32x32x16_bf16 v[82:97], v[164:167], v[218:221], v[82:97]
	s_waitcnt lgkmcnt(8)
	v_mfma_f32_32x32x16_bf16 v[98:113], v[194:197], v[214:217], v[98:113]
	v_mfma_f32_32x32x16_bf16 v[66:81], v[194:197], v[218:221], v[66:81]
	s_waitcnt lgkmcnt(3)
; DI unsigned pk2(float lo, float hi) { f32x2 v = {lo, hi}; bf16x2v b = __builtin_convertvector(v, bf16x2v); return __builtin_bit_cast(unsigned, b); }
; DI float siluf_(float x) { return x * __builtin_amdgcn_rcpf(1.f + __builtin_amdgcn_exp2f(-LOG2E * x)); }
; #define G_GLOAD(XR, WR, KT) { _Pragma("unroll") for (int i_ = 0; i_ < 4; ++i_) XR[i_] = *(const u32x4*)(Xt + ((size_t)(64 * i_) * ldx + (KT) * 64) * 2 + xoff); \
;     _Pragma("unroll") for (int i_ = 0; i_ < 4; ++i_) WR[i_] = *(const u32x4*)(Wtb + ((size_t)(64 * i_) * K + (KT) * 64) * 2 + woff); }
; #define G_LSTORE(XR, WR, STG) { char* xs_ = lds + (STG) * G_STAGE; char* ws_ = xs_ + G_XB; \
;     _Pragma("unroll") for (int i_ = 0; i_ < 4; ++i_) *(u32x4*)(xs_ + (lrow + 64 * i_) * LROW + lch * 16) = XR[i_]; \
;     _Pragma("unroll") for (int i_ = 0; i_ < 4; ++i_) *(u32x4*)(ws_ + (lrow + 64 * i_) * LROW + lch * 16) = WR[i_]; }
; template <class Epi>
; DI void gemm_phase(const bf16_t* __restrict__ X, const int ldx, const bf16_t* __restrict__ Wt, const int N, const int K, const Epi& epi, char* lds) {
;     ...
;     asm volatile("" ::: "memory");
;     if (Epi::kFull || chunk == xcd) {
;       G_GLOAD(xr0, wr0, 0);
;       G_LSTORE(xr0, wr0, 0);
;       __syncthreads();
;       G_GLOAD(xr0, wr0, 1);
;     }
; #pragma unroll
;     for (int c = 0; c < 2; ++c)
; #pragma unroll
;       for (int a = 0; a < 2; ++a)
; #pragma unroll
;         for (int b = 0; b < 2; ++b)
; #pragma unroll
;           for (int i = 0; i < 16; ++i) acc[c][a][b][i] = 0.f;
;   DI void operator()(int tok0, int feat0, f32x16 (&acc)[2][2], int r, int hh) const {
;     const int u0 = (feat0 >> 6) * 32;
; #pragma unroll
;     for (int mt = 0; mt < 2; ++mt) {
;       bf16_t* dst = act + (size_t)(tok0 + mt * 32 + r) * DFF + u0 + 16 * hh;
; #pragma unroll
;       for (int gp = 0; gp < 2; ++gp) {
;         u32x4 o;
; #pragma unroll
;         for (int q = 0; q < 4; ++q) { const int i = 8 * gp + 2 * q; o[q] = pk2(siluf_(acc[0][mt][i]) * acc[1][mt][i], siluf_(acc[0][mt][i + 1]) * acc[1][mt][i + 1]); }
;         *(u32x4*)(dst + 8 * gp) = o;
	v_mfma_f32_32x32x16_bf16 v[50:65], v[188:191], v[214:217], v[50:65]
	v_mfma_f32_32x32x16_bf16 v[18:33], v[188:191], v[218:221], v[18:33]
	ds_read_b128 v[164:167], v187 offset:64
	ds_read_b128 v[188:191], v183 offset:64
	s_waitcnt lgkmcnt(4)
	v_mfma_f32_32x32x16_bf16 v[34:49], v[202:205], v[214:217], v[34:49]
	v_mfma_f32_32x32x16_bf16 v[2:17], v[202:205], v[218:221], v[2:17]
	s_add_u32 s100, s16, s96
	s_addc_u32 s101, s17, 0
	s_waitcnt vmcnt(6)
	ds_write_b128 v186, v[154:157] offset:46080
	ds_write_b128 v186, v[138:141] offset:36864
	s_nop 0
	global_load_dwordx4 v[138:141], v162, s[100:101]
	global_load_dwordx4 v[154:157], v232, s[100:101]
	ds_read_b128 v[194:197], v184 offset:64
	ds_read_b128 v[202:205], v185 offset:64
	ds_read_b128 v[214:217], v0 offset:96
	ds_read_b128 v[218:221], v182 offset:96
	s_waitcnt lgkmcnt(7)
	v_mfma_f32_32x32x16_bf16 v[114:129], v[164:167], v[206:209], v[114:129]
	v_mfma_f32_32x32x16_bf16 v[82:97], v[164:167], v[210:213], v[82:97]
	s_waitcnt lgkmcnt(6)
	v_mfma_f32_32x32x16_bf16 v[98:113], v[188:191], v[206:209], v[98:113]
	v_mfma_f32_32x32x16_bf16 v[66:81], v[188:191], v[210:213], v[66:81]
	s_waitcnt lgkmcnt(3)
	v_mfma_f32_32x32x16_bf16 v[50:65], v[194:197], v[206:209], v[50:65]
	ds_read_b128 v[164:167], v187 offset:96
	ds_read_b128 v[188:191], v183 offset:96
	v_mfma_f32_32x32x16_bf16 v[18:33], v[194:197], v[210:213], v[18:33]
	s_waitcnt lgkmcnt(4)
	v_mfma_f32_32x32x16_bf16 v[34:49], v[202:205], v[206:209], v[34:49]
	v_mfma_f32_32x32x16_bf16 v[2:17], v[202:205], v[210:213], v[2:17]
	s_waitcnt vmcnt(7)
	ds_write_b128 v186, v[146:149] offset:55296
	s_waitcnt vmcnt(6)
	ds_write_b128 v186, v[158:161] offset:64512
	s_nop 0
	global_load_dwordx4 v[146:149], v233, s[100:101]
	global_load_dwordx4 v[158:161], v234, s[100:101]
	ds_read_b128 v[194:197], v184 offset:96
	ds_read_b128 v[202:205], v185 offset:96
	s_waitcnt lgkmcnt(5)
	v_mfma_f32_32x32x16_bf16 v[114:129], v[164:167], v[214:217], v[114:129]
	v_mfma_f32_32x32x16_bf16 v[82:97], v[164:167], v[218:221], v[82:97]
	s_waitcnt lgkmcnt(4)
	v_mfma_f32_32x32x16_bf16 v[98:113], v[188:191], v[214:217], v[98:113]
	v_mfma_f32_32x32x16_bf16 v[66:81], v[188:191], v[218:221], v[66:81]
	s_waitcnt lgkmcnt(1)
	v_mfma_f32_32x32x16_bf16 v[50:65], v[194:197], v[214:217], v[50:65]
	v_mfma_f32_32x32x16_bf16 v[18:33], v[194:197], v[218:221], v[18:33]
	s_waitcnt lgkmcnt(0)
	v_mfma_f32_32x32x16_bf16 v[34:49], v[202:205], v[214:217], v[34:49]
	v_mfma_f32_32x32x16_bf16 v[2:17], v[202:205], v[218:221], v[2:17]
	s_add_i32 s28, s28, 2
	s_cmp_gt_u32 s29, 13
	s_barrier
	s_cbranch_scc0 .LBB0_739
	v_mov_b32_e32 v0, v192
	v_mov_b64_e32 v[166:167], s[6:7]
	v_ashrrev_i32_e32 v164, 1, v0
	v_and_b32_e32 v164, 0xffffff80, v164
	v_add_u32_e32 v164, s3, v164
	v_ashrrev_i32_e32 v164, 1, v164
	v_and_b32_e32 v165, 0xdf, v0
	v_or_b32_e32 v187, s8, v165
	v_ashrrev_i32_e32 v165, 31, v164
	v_mad_i64_i32 v[188:189], s[12:13], v187, s69, v[166:167]
	v_lshlrev_b64 v[168:169], 1, v[164:165]
	v_lshl_add_u64 v[164:165], v[188:189], 0, v[168:169]
	v_mul_f32_e32 v188, 0xbfb8aa3b, v114
	v_mul_f32_e32 v189, 0xbfb8aa3b, v115
	v_exp_f32_e32 v188, v188
	v_exp_f32_e32 v189, v189
	v_and_b32_e32 v0, 32, v0
	v_lshl_add_u64 v[164:165], v[164:165], 0, v[0:1]
	v_add_f32_e32 v188, 1.0, v188
	v_add_f32_e32 v189, 1.0, v189
	v_rcp_f32_e32 v188, v188
	v_rcp_f32_e32 v189, v189
	s_nop 0
	v_pk_mul_f32 v[114:115], v[114:115], v[188:189]
	s_nop 0
	v_pk_mul_f32 v[98:99], v[98:99], v[114:115]
	s_nop 0
	v_cvt_pk_bf16_f32 v98, v98, v99
	v_mul_f32_e32 v99, 0xbfb8aa3b, v116
	v_exp_f32_e32 v99, v99
	s_nop 0
	v_add_f32_e32 v99, 1.0, v99
	v_rcp_f32_e32 v114, v99
	v_mul_f32_e32 v99, 0xbfb8aa3b, v117
	v_exp_f32_e32 v99, v99
	s_nop 0
	v_add_f32_e32 v99, 1.0, v99
	v_rcp_f32_e32 v115, v99
	s_nop 0
	v_pk_mul_f32 v[114:115], v[116:117], v[114:115]
	s_nop 0
	v_pk_mul_f32 v[100:101], v[100:101], v[114:115]
	s_nop 0
	v_cvt_pk_bf16_f32 v99, v100, v101
	v_mul_f32_e32 v100, 0xbfb8aa3b, v118
	v_mul_f32_e32 v101, 0xbfb8aa3b, v119
	v_exp_f32_e32 v100, v100
	v_exp_f32_e32 v101, v101
	v_add_f32_e32 v100, 1.0, v100
	v_add_f32_e32 v101, 1.0, v101
	v_rcp_f32_e32 v100, v100
	v_rcp_f32_e32 v101, v101
	s_nop 0
	v_pk_mul_f32 v[100:101], v[118:119], v[100:101]
	s_nop 0
	v_pk_mul_f32 v[100:101], v[102:103], v[100:101]
	s_nop 0
	v_cvt_pk_bf16_f32 v100, v100, v101
	v_mul_f32_e32 v101, 0xbfb8aa3b, v120
	v_exp_f32_e32 v101, v101
	s_nop 0
	v_add_f32_e32 v101, 1.0, v101
	v_rcp_f32_e32 v102, v101
	v_mul_f32_e32 v101, 0xbfb8aa3b, v121
	v_exp_f32_e32 v101, v101
	s_nop 0
	v_add_f32_e32 v101, 1.0, v101
	v_rcp_f32_e32 v103, v101
	s_nop 0
	v_pk_mul_f32 v[102:103], v[120:121], v[102:103]
	s_nop 0
	v_pk_mul_f32 v[102:103], v[104:105], v[102:103]
	s_nop 0
	v_cvt_pk_bf16_f32 v101, v102, v103
	global_store_dwordx4 v[164:165], v[98:101], off
	s_nop 1
	v_mul_f32_e32 v98, 0xbfb8aa3b, v122
	v_mul_f32_e32 v99, 0xbfb8aa3b, v123
	v_exp_f32_e32 v98, v98
	v_exp_f32_e32 v99, v99
	v_add_f32_e32 v98, 1.0, v98
	v_add_f32_e32 v99, 1.0, v99
	v_rcp_f32_e32 v98, v98
	v_rcp_f32_e32 v99, v99
	s_nop 0
	v_pk_mul_f32 v[98:99], v[122:123], v[98:99]
	s_nop 0
	v_pk_mul_f32 v[98:99], v[106:107], v[98:99]
	s_nop 0
	v_cvt_pk_bf16_f32 v98, v98, v99
	v_mul_f32_e32 v99, 0xbfb8aa3b, v124
	v_exp_f32_e32 v99, v99
	s_nop 0
	v_add_f32_e32 v99, 1.0, v99
	v_rcp_f32_e32 v100, v99
	v_mul_f32_e32 v99, 0xbfb8aa3b, v125
	v_exp_f32_e32 v99, v99
	s_nop 0
	v_add_f32_e32 v99, 1.0, v99
	v_rcp_f32_e32 v101, v99
	s_nop 0
	v_pk_mul_f32 v[100:101], v[124:125], v[100:101]
	s_nop 0
	v_pk_mul_f32 v[100:101], v[108:109], v[100:101]
	s_nop 0
	v_cvt_pk_bf16_f32 v99, v100, v101
	v_mul_f32_e32 v100, 0xbfb8aa3b, v126
	v_mul_f32_e32 v101, 0xbfb8aa3b, v127
; DI unsigned pk2(float lo, float hi) { f32x2 v = {lo, hi}; bf16x2v b = __builtin_convertvector(v, bf16x2v); return __builtin_bit_cast(unsigned, b); }
; DI float siluf_(float x) { return x * __builtin_amdgcn_rcpf(1.f + __builtin_amdgcn_exp2f(-LOG2E * x)); }
;   DI void operator()(int tok0, int feat0, f32x16 (&acc)[2][2], int r, int hh) const {
;     const int u0 = (feat0 >> 6) * 32;
; #pragma unroll
;     for (int mt = 0; mt < 2; ++mt) {
;       bf16_t* dst = act + (size_t)(tok0 + mt * 32 + r) * DFF + u0 + 16 * hh;
; #pragma unroll
;       for (int gp = 0; gp < 2; ++gp) {
;         u32x4 o;
; #pragma unroll
;         for (int q = 0; q < 4; ++q) { const int i = 8 * gp + 2 * q; o[q] = pk2(siluf_(acc[0][mt][i]) * acc[1][mt][i], siluf_(acc[0][mt][i + 1]) * acc[1][mt][i + 1]); }
;         *(u32x4*)(dst + 8 * gp) = o;
;       }
	v_exp_f32_e32 v100, v100
	v_exp_f32_e32 v101, v101
	v_add_f32_e32 v100, 1.0, v100
	v_add_f32_e32 v101, 1.0, v101
	v_rcp_f32_e32 v100, v100
	v_rcp_f32_e32 v101, v101
	s_nop 0
	v_pk_mul_f32 v[100:101], v[126:127], v[100:101]
	s_nop 0
	v_pk_mul_f32 v[100:101], v[110:111], v[100:101]
	s_nop 0
	v_cvt_pk_bf16_f32 v100, v100, v101
	v_mul_f32_e32 v101, 0xbfb8aa3b, v128
	v_exp_f32_e32 v101, v101
	s_nop 0
	v_add_f32_e32 v101, 1.0, v101
	v_rcp_f32_e32 v102, v101
	v_mul_f32_e32 v101, 0xbfb8aa3b, v129
	v_exp_f32_e32 v101, v101
	s_nop 0
	v_add_f32_e32 v101, 1.0, v101
	v_rcp_f32_e32 v103, v101
	s_nop 0
	v_pk_mul_f32 v[102:103], v[128:129], v[102:103]
	s_nop 0
	v_pk_mul_f32 v[102:103], v[112:113], v[102:103]
	s_nop 0
	v_cvt_pk_bf16_f32 v101, v102, v103
	global_store_dwordx4 v[164:165], v[98:101], off offset:16
	s_nop 1
	v_or_b32_e32 v98, 32, v187
	v_mad_i64_i32 v[98:99], s[12:13], v98, s69, v[166:167]
	v_lshl_add_u64 v[98:99], v[98:99], 0, v[168:169]
	v_lshl_add_u64 v[98:99], v[98:99], 0, v[0:1]
	v_mul_f32_e32 v0, 0xbfb8aa3b, v82
	v_exp_f32_e32 v0, v0
	s_nop 0
	v_add_f32_e32 v0, 1.0, v0
	v_rcp_f32_e32 v100, v0
	v_mul_f32_e32 v0, 0xbfb8aa3b, v83
	v_exp_f32_e32 v0, v0
	s_nop 0
	v_add_f32_e32 v0, 1.0, v0
	v_rcp_f32_e32 v101, v0
	v_mul_f32_e32 v0, 0xbfb8aa3b, v84
	v_exp_f32_e32 v0, v0
	v_pk_mul_f32 v[82:83], v[82:83], v[100:101]
	s_nop 0
	v_pk_mul_f32 v[66:67], v[66:67], v[82:83]
	v_add_f32_e32 v0, 1.0, v0
	v_rcp_f32_e32 v82, v0
	v_mul_f32_e32 v0, 0xbfb8aa3b, v85
	v_exp_f32_e32 v0, v0
	v_cvt_pk_bf16_f32 v66, v66, v67
	v_add_f32_e32 v0, 1.0, v0
	v_rcp_f32_e32 v83, v0
	v_mul_f32_e32 v0, 0xbfb8aa3b, v86
	v_exp_f32_e32 v0, v0
	v_pk_mul_f32 v[82:83], v[84:85], v[82:83]
	s_nop 0
	v_pk_mul_f32 v[68:69], v[68:69], v[82:83]
	v_add_f32_e32 v0, 1.0, v0
	v_cvt_pk_bf16_f32 v67, v68, v69
	v_rcp_f32_e32 v68, v0
	v_mul_f32_e32 v0, 0xbfb8aa3b, v87
	v_exp_f32_e32 v0, v0
	s_nop 0
	v_add_f32_e32 v0, 1.0, v0
	v_rcp_f32_e32 v69, v0
	v_mul_f32_e32 v0, 0xbfb8aa3b, v88
	v_exp_f32_e32 v0, v0
	v_pk_mul_f32 v[68:69], v[86:87], v[68:69]
	s_nop 0
	v_pk_mul_f32 v[68:69], v[70:71], v[68:69]
	v_add_f32_e32 v0, 1.0, v0
	v_rcp_f32_e32 v70, v0
	v_mul_f32_e32 v0, 0xbfb8aa3b, v89
	v_exp_f32_e32 v0, v0
	v_cvt_pk_bf16_f32 v68, v68, v69
	v_add_f32_e32 v0, 1.0, v0
	v_rcp_f32_e32 v71, v0
	v_mul_f32_e32 v0, 0xbfb8aa3b, v90
	v_exp_f32_e32 v0, v0
	v_pk_mul_f32 v[70:71], v[88:89], v[70:71]
	s_nop 0
	v_pk_mul_f32 v[70:71], v[72:73], v[70:71]
	v_add_f32_e32 v0, 1.0, v0
	v_cvt_pk_bf16_f32 v69, v70, v71
	global_store_dwordx4 v[98:99], v[66:69], off
	s_nop 1
	v_rcp_f32_e32 v66, v0
	v_mul_f32_e32 v0, 0xbfb8aa3b, v91
	v_exp_f32_e32 v0, v0
	s_nop 0
	v_add_f32_e32 v0, 1.0, v0
	v_rcp_f32_e32 v67, v0
	v_mul_f32_e32 v0, 0xbfb8aa3b, v92
	v_exp_f32_e32 v0, v0
	v_pk_mul_f32 v[66:67], v[90:91], v[66:67]
	s_nop 0
	v_pk_mul_f32 v[66:67], v[74:75], v[66:67]
	v_add_f32_e32 v0, 1.0, v0
	v_rcp_f32_e32 v68, v0
	v_mul_f32_e32 v0, 0xbfb8aa3b, v93
	v_exp_f32_e32 v0, v0
	v_cvt_pk_bf16_f32 v66, v66, v67
	v_add_f32_e32 v0, 1.0, v0
	v_rcp_f32_e32 v69, v0
	v_mul_f32_e32 v0, 0xbfb8aa3b, v94
	v_exp_f32_e32 v0, v0
	v_pk_mul_f32 v[68:69], v[92:93], v[68:69]
	s_nop 0
	v_pk_mul_f32 v[68:69], v[76:77], v[68:69]
	v_add_f32_e32 v0, 1.0, v0
	v_cvt_pk_bf16_f32 v67, v68, v69
	v_rcp_f32_e32 v68, v0
	v_mul_f32_e32 v0, 0xbfb8aa3b, v95
	v_exp_f32_e32 v0, v0
	s_nop 0
	v_add_f32_e32 v0, 1.0, v0
	v_rcp_f32_e32 v69, v0
	v_mul_f32_e32 v0, 0xbfb8aa3b, v96
	v_exp_f32_e32 v0, v0
	v_pk_mul_f32 v[68:69], v[94:95], v[68:69]
	s_nop 0
	v_pk_mul_f32 v[68:69], v[78:79], v[68:69]
	v_add_f32_e32 v0, 1.0, v0
	v_rcp_f32_e32 v70, v0
	v_mul_f32_e32 v0, 0xbfb8aa3b, v97
	v_exp_f32_e32 v0, v0
	v_cvt_pk_bf16_f32 v68, v68, v69
	v_add_f32_e32 v0, 1.0, v0
	v_rcp_f32_e32 v71, v0
	s_nop 0
	v_pk_mul_f32 v[70:71], v[96:97], v[70:71]
	s_nop 0
	v_pk_mul_f32 v[70:71], v[80:81], v[70:71]
	s_nop 0
	v_cvt_pk_bf16_f32 v69, v70, v71
	global_store_dwordx4 v[98:99], v[66:69], off offset:16
	v_mul_f32_e32 v0, 0xbfb8aa3b, v50
	v_exp_f32_e32 v0, v0
	s_nop 0
	v_add_f32_e32 v0, 1.0, v0
	v_rcp_f32_e32 v66, v0
	v_mul_f32_e32 v0, 0xbfb8aa3b, v51
	v_exp_f32_e32 v0, v0
	s_nop 0
	v_add_f32_e32 v0, 1.0, v0
	v_rcp_f32_e32 v67, v0
	v_mul_f32_e32 v0, 0xbfb8aa3b, v52
	v_exp_f32_e32 v0, v0
	v_pk_mul_f32 v[50:51], v[50:51], v[66:67]
	s_nop 0
	v_pk_mul_f32 v[34:35], v[34:35], v[50:51]
	v_add_f32_e32 v0, 1.0, v0
	v_rcp_f32_e32 v50, v0
	v_mul_f32_e32 v0, 0xbfb8aa3b, v53
	v_exp_f32_e32 v0, v0
	v_cvt_pk_bf16_f32 v34, v34, v35
	v_add_f32_e32 v0, 1.0, v0
	v_rcp_f32_e32 v51, v0
	v_mul_f32_e32 v0, 0xbfb8aa3b, v54
	v_exp_f32_e32 v0, v0
	v_pk_mul_f32 v[50:51], v[52:53], v[50:51]
	s_nop 0
	v_pk_mul_f32 v[36:37], v[36:37], v[50:51]
	v_add_f32_e32 v0, 1.0, v0
	v_cvt_pk_bf16_f32 v35, v36, v37
	v_rcp_f32_e32 v36, v0
	v_mul_f32_e32 v0, 0xbfb8aa3b, v55
	v_exp_f32_e32 v0, v0
	s_nop 0
	v_add_f32_e32 v0, 1.0, v0
	v_rcp_f32_e32 v37, v0
	v_mul_f32_e32 v0, 0xbfb8aa3b, v56
	v_exp_f32_e32 v0, v0
	v_pk_mul_f32 v[36:37], v[54:55], v[36:37]
	s_nop 0
	v_pk_mul_f32 v[36:37], v[38:39], v[36:37]
	v_add_f32_e32 v0, 1.0, v0
	v_rcp_f32_e32 v38, v0
	v_mul_f32_e32 v0, 0xbfb8aa3b, v57
	v_exp_f32_e32 v0, v0
	v_cvt_pk_bf16_f32 v36, v36, v37
	v_add_f32_e32 v0, 1.0, v0
	v_rcp_f32_e32 v39, v0
	v_mul_f32_e32 v0, 0xbfb8aa3b, v58
	v_exp_f32_e32 v0, v0
	v_pk_mul_f32 v[38:39], v[56:57], v[38:39]
; #define GAS __attribute__((address_space(1)))
; DI unsigned pk2(float lo, float hi) { f32x2 v = {lo, hi}; bf16x2v b = __builtin_convertvector(v, bf16x2v); return __builtin_bit_cast(unsigned, b); }
; DI float siluf_(float x) { return x * __builtin_amdgcn_rcpf(1.f + __builtin_amdgcn_exp2f(-LOG2E * x)); }
;   DI void operator()(int tok0, int feat0, f32x16 (&acc)[2][2], int r, int hh) const {
;     const int u0 = (feat0 >> 6) * 32;
; #pragma unroll
;     for (int mt = 0; mt < 2; ++mt) {
;       bf16_t* dst = act + (size_t)(tok0 + mt * 32 + r) * DFF + u0 + 16 * hh;
; #pragma unroll
;       for (int gp = 0; gp < 2; ++gp) {
;         u32x4 o;
; #pragma unroll
;         for (int q = 0; q < 4; ++q) { const int i = 8 * gp + 2 * q; o[q] = pk2(siluf_(acc[0][mt][i]) * acc[1][mt][i], siluf_(acc[0][mt][i + 1]) * acc[1][mt][i + 1]); }
;         *(u32x4*)(dst + 8 * gp) = o;
;       }
; DI void grid_barrier(unsigned* ctr, const unsigned target) {
;   asm volatile("s_waitcnt vmcnt(0)" ::: "memory");
;   __syncthreads();
;   if (threadIdx.x == 0) {
;     __builtin_amdgcn_fence(__ATOMIC_RELEASE, "agent");
;     asm volatile("s_waitcnt vmcnt(0)" ::: "memory");
;     __hip_atomic_fetch_add((GAS unsigned*)ctr, 1u, __ATOMIC_RELAXED, __HIP_MEMORY_SCOPE_AGENT);
;     while (__hip_atomic_load((GAS unsigned*)ctr, __ATOMIC_RELAXED, __HIP_MEMORY_SCOPE_AGENT) < target) __builtin_amdgcn_s_sleep(1);
	s_nop 0
	v_pk_mul_f32 v[38:39], v[40:41], v[38:39]
	v_add_f32_e32 v0, 1.0, v0
	v_cvt_pk_bf16_f32 v37, v38, v39
	global_store_dwordx4 v[164:165], v[34:37], off offset:64
	s_nop 1
	v_rcp_f32_e32 v34, v0
	v_mul_f32_e32 v0, 0xbfb8aa3b, v59
	v_exp_f32_e32 v0, v0
	s_nop 0
	v_add_f32_e32 v0, 1.0, v0
	v_rcp_f32_e32 v35, v0
	v_mul_f32_e32 v0, 0xbfb8aa3b, v60
	v_exp_f32_e32 v0, v0
	v_pk_mul_f32 v[34:35], v[58:59], v[34:35]
	s_nop 0
	v_pk_mul_f32 v[34:35], v[42:43], v[34:35]
	v_add_f32_e32 v0, 1.0, v0
	v_rcp_f32_e32 v36, v0
	v_mul_f32_e32 v0, 0xbfb8aa3b, v61
	v_exp_f32_e32 v0, v0
	v_cvt_pk_bf16_f32 v34, v34, v35
	v_add_f32_e32 v0, 1.0, v0
	v_rcp_f32_e32 v37, v0
	v_mul_f32_e32 v0, 0xbfb8aa3b, v62
	v_exp_f32_e32 v0, v0
	v_pk_mul_f32 v[36:37], v[60:61], v[36:37]
	s_nop 0
	v_pk_mul_f32 v[36:37], v[44:45], v[36:37]
	v_add_f32_e32 v0, 1.0, v0
	v_cvt_pk_bf16_f32 v35, v36, v37
	v_rcp_f32_e32 v36, v0
	v_mul_f32_e32 v0, 0xbfb8aa3b, v63
	v_exp_f32_e32 v0, v0
	s_nop 0
	v_add_f32_e32 v0, 1.0, v0
	v_rcp_f32_e32 v37, v0
	v_mul_f32_e32 v0, 0xbfb8aa3b, v64
	v_exp_f32_e32 v0, v0
	v_pk_mul_f32 v[36:37], v[62:63], v[36:37]
	s_nop 0
	v_pk_mul_f32 v[36:37], v[46:47], v[36:37]
	v_add_f32_e32 v0, 1.0, v0
	v_rcp_f32_e32 v38, v0
	v_mul_f32_e32 v0, 0xbfb8aa3b, v65
	v_exp_f32_e32 v0, v0
	v_cvt_pk_bf16_f32 v36, v36, v37
	v_add_f32_e32 v0, 1.0, v0
	v_rcp_f32_e32 v39, v0
	v_mul_f32_e32 v0, 0xbfb8aa3b, v18
	v_exp_f32_e32 v0, v0
	v_pk_mul_f32 v[38:39], v[64:65], v[38:39]
	s_nop 0
	v_pk_mul_f32 v[38:39], v[48:49], v[38:39]
	v_add_f32_e32 v0, 1.0, v0
	v_cvt_pk_bf16_f32 v37, v38, v39
	global_store_dwordx4 v[164:165], v[34:37], off offset:80
	s_nop 1
	v_rcp_f32_e32 v34, v0
	v_mul_f32_e32 v0, 0xbfb8aa3b, v19
	v_exp_f32_e32 v0, v0
	s_nop 0
	v_add_f32_e32 v0, 1.0, v0
	v_rcp_f32_e32 v35, v0
	v_mul_f32_e32 v0, 0xbfb8aa3b, v20
	v_exp_f32_e32 v0, v0
	v_pk_mul_f32 v[18:19], v[18:19], v[34:35]
	s_nop 0
	v_pk_mul_f32 v[2:3], v[2:3], v[18:19]
	v_add_f32_e32 v0, 1.0, v0
	v_rcp_f32_e32 v18, v0
	v_mul_f32_e32 v0, 0xbfb8aa3b, v21
	v_exp_f32_e32 v0, v0
	v_cvt_pk_bf16_f32 v2, v2, v3
	v_add_f32_e32 v0, 1.0, v0
	v_rcp_f32_e32 v19, v0
	v_mul_f32_e32 v0, 0xbfb8aa3b, v22
	v_exp_f32_e32 v0, v0
	v_pk_mul_f32 v[18:19], v[20:21], v[18:19]
	s_nop 0
	v_pk_mul_f32 v[4:5], v[4:5], v[18:19]
	v_add_f32_e32 v0, 1.0, v0
	v_cvt_pk_bf16_f32 v3, v4, v5
	v_rcp_f32_e32 v4, v0
	v_mul_f32_e32 v0, 0xbfb8aa3b, v23
	v_exp_f32_e32 v0, v0
	s_nop 0
	v_add_f32_e32 v0, 1.0, v0
	v_rcp_f32_e32 v5, v0
	v_mul_f32_e32 v0, 0xbfb8aa3b, v24
	v_exp_f32_e32 v0, v0
	v_pk_mul_f32 v[4:5], v[22:23], v[4:5]
	s_nop 0
	v_pk_mul_f32 v[4:5], v[6:7], v[4:5]
	v_add_f32_e32 v0, 1.0, v0
	v_rcp_f32_e32 v6, v0
	v_mul_f32_e32 v0, 0xbfb8aa3b, v25
	v_exp_f32_e32 v0, v0
	v_cvt_pk_bf16_f32 v4, v4, v5
	v_add_f32_e32 v0, 1.0, v0
	v_rcp_f32_e32 v7, v0
	v_mul_f32_e32 v0, 0xbfb8aa3b, v26
	v_exp_f32_e32 v0, v0
	v_pk_mul_f32 v[6:7], v[24:25], v[6:7]
	s_nop 0
	v_pk_mul_f32 v[6:7], v[8:9], v[6:7]
	v_add_f32_e32 v0, 1.0, v0
	v_cvt_pk_bf16_f32 v5, v6, v7
	global_store_dwordx4 v[98:99], v[2:5], off offset:64
	s_nop 1
	v_rcp_f32_e32 v2, v0
	v_mul_f32_e32 v0, 0xbfb8aa3b, v27
	v_exp_f32_e32 v0, v0
	s_nop 0
	v_add_f32_e32 v0, 1.0, v0
	v_rcp_f32_e32 v3, v0
	v_mul_f32_e32 v0, 0xbfb8aa3b, v28
	v_exp_f32_e32 v0, v0
	v_pk_mul_f32 v[2:3], v[26:27], v[2:3]
	s_nop 0
	v_pk_mul_f32 v[2:3], v[10:11], v[2:3]
	v_add_f32_e32 v0, 1.0, v0
	v_rcp_f32_e32 v4, v0
	v_mul_f32_e32 v0, 0xbfb8aa3b, v29
	v_exp_f32_e32 v0, v0
	v_cvt_pk_bf16_f32 v2, v2, v3
	v_add_f32_e32 v0, 1.0, v0
	v_rcp_f32_e32 v5, v0
	v_mul_f32_e32 v0, 0xbfb8aa3b, v30
	v_exp_f32_e32 v0, v0
	v_pk_mul_f32 v[4:5], v[28:29], v[4:5]
	s_nop 0
	v_pk_mul_f32 v[4:5], v[12:13], v[4:5]
	v_add_f32_e32 v0, 1.0, v0
	v_cvt_pk_bf16_f32 v3, v4, v5
	v_rcp_f32_e32 v4, v0
	v_mul_f32_e32 v0, 0xbfb8aa3b, v31
	v_exp_f32_e32 v0, v0
	s_nop 0
	v_add_f32_e32 v0, 1.0, v0
	v_rcp_f32_e32 v5, v0
	v_mul_f32_e32 v0, 0xbfb8aa3b, v32
	v_exp_f32_e32 v0, v0
	v_pk_mul_f32 v[4:5], v[30:31], v[4:5]
	s_nop 0
	v_pk_mul_f32 v[4:5], v[14:15], v[4:5]
	v_add_f32_e32 v0, 1.0, v0
	v_rcp_f32_e32 v6, v0
	v_mul_f32_e32 v0, 0xbfb8aa3b, v33
	v_exp_f32_e32 v0, v0
	v_cvt_pk_bf16_f32 v4, v4, v5
	v_add_f32_e32 v0, 1.0, v0
	v_rcp_f32_e32 v7, v0
	s_nop 0
	v_pk_mul_f32 v[6:7], v[32:33], v[6:7]
	s_nop 0
	v_pk_mul_f32 v[6:7], v[16:17], v[6:7]
	s_nop 0
	v_cvt_pk_bf16_f32 v5, v6, v7
	global_store_dwordx4 v[98:99], v[2:5], off offset:80
	s_and_b64 vcc, exec, s[4:5]
	s_mov_b32 s16, s9
	s_cbranch_vccz .LBB0_736
	s_add_i32 s25, s24, 1
	s_cmp_ge_i32 s25, s79
	s_cbranch_scc1 .LBB0_762
	s_cmp_lg_u32 s24, s78
	s_mov_b64 s[4:5], -1
	v_mov_b32_e32 v206, v198
	v_mov_b32_e32 v207, v199
	s_cbranch_scc0 .LBB0_750
	s_waitcnt vmcnt(0)
	s_barrier
	s_mov_b64 s[4:5], exec
	v_readlane_b32 s2, v254, 26
	v_readlane_b32 s3, v254, 27
	s_and_b64 s[2:3], s[4:5], s[2:3]
	s_mov_b64 exec, s[2:3]
	s_cbranch_execz .LBB0_749
	s_load_dword s2, s[80:81], 0x0
	s_mov_b64 s[8:9], exec
	buffer_wbl2 sc1
	s_waitcnt vmcnt(0) lgkmcnt(0)
	s_waitcnt vmcnt(0)
	v_mbcnt_lo_u32_b32 v0, s8, 0
	s_add_u32 s6, s10, 0x1ee14400
	v_mbcnt_hi_u32_b32 v0, s9, v0
	s_addc_u32 s7, s11, 0
	v_cmp_eq_u32_e32 vcc, 0, v0
	s_and_saveexec_b64 s[10:11], vcc
	s_cbranch_execz .LBB0_746
	s_bcnt1_i32_b64 s3, s[8:9]
	v_mov_b32_e32 v0, s3
	global_atomic_add v1, v0, s[6:7]
